# MFMA order: k-snake within pair order (every second accumulator pair issues its second k-step first so the held operand repeats across pair boundaries)
# baseline (speedup 1.0000x reference)
; #define PG8_STAGE(bufoff, gbase, voff) do { _Pragma("unroll") for (int _i = 0; _i < 2; ++_i) \
;         __builtin_amdgcn_global_load_lds((const unsigned*)((const char*)(gbase) + (voff)[_i]), (PG8_LAS unsigned*)(lds + (bufoff) + ldsw + _i * 8192), 16, 0, 0); } while (0)
; #define PG8_LDA(dst, b, h) do { _Pragma("unroll") for (int m = 0; m < 4; ++m) _Pragma("unroll") for (int k = 0; k < 2; ++k) dst[m][k] = *(const PG8_LAS bf16x8*)(lds + PG8_SA(b, h) + aoff + m * 2048 + k * 1024); } while (0)
; #define PG8_LDB(dst, b, h) do { _Pragma("unroll") for (int n = 0; n < 2; ++n) _Pragma("unroll") for (int k = 0; k < 2; ++k) dst[n][k] = *(const PG8_LAS bf16x8*)(lds + PG8_SB(b, h) + boff + n * 2048 + k * 1024); } while (0)
; #define PG8_MMA(ai, bj, At, Bt) do { __builtin_amdgcn_s_setprio(1); _Pragma("unroll") for (int m = 0; m < 4; ++m) _Pragma("unroll") for (int n = 0; n < 2; ++n) _Pragma("unroll") for (int k = 0; k < 2; ++k) \
;         acc[ai][bj][m][n] = __builtin_amdgcn_mfma_f32_16x16x32_bf16(Bt[n][k], At[m][k], acc[ai][bj][m][n], 0, 0, 0); __builtin_amdgcn_s_setprio(0); } while (0)
; #define PG8_WAIT_V(n) asm volatile("s_waitcnt vmcnt(" #n ")" ::: "memory")
; #define PG8_WAIT_L(n) asm volatile("s_waitcnt lgkmcnt(" #n ")" ::: "memory")
; template <class Epi, class Sched, bool ALIGN_EPI = false, bool SP2 = false>
; __device__ __forceinline__ void gemm_phase(PG8_LAS unsigned char* lds, const Gemm g, const Sched& S, const Epi& E) {
;     ...
;             const bool last = (t == nt - 2);
;             const char* a1 = cA + (size_t)(t + 1) * kstep;
;             const char* a2 = last ? nA : cA + (size_t)(t + 2) * kstep; const char* b2 = last ? nB : cB + (size_t)(t + 2) * kstep;
;             const char* a3 = a2 + kstep; const char* b3 = b2 + kstep;
;             if (last && has_next) S.a_ready(nxt);
;             if constexpr (SP2) {
;             PG8_LDB(B0, 0, 0); PG8_LDB(B1, 0, 1); PG8_SCHED; PG8_LDA(At, 0, 0); PG8_STAGE(PG8_SA(1, 1), a1 + hstep, voffA);
;             PG8_WAIT_V(8); PG8_WAIT_L(0); PG8_BAR; PG8_MMA(0, 0, At, B0); PG8_MMA(0, 1, At, B1); PG8_BAR; PG8_SCHED;
;             PG8_LDA(At, 0, 1); PG8_STAGE(PG8_SB(0, 0), b2, voffB); PG8_STAGE(PG8_SB(0, 1), b2 + hstep, voffB); PG8_STAGE(PG8_SA(0, 0), a2, voffA);
;             PG8_WAIT_V(8); PG8_WAIT_L(0); PG8_BAR; PG8_MMA(1, 0, At, B0); PG8_MMA(1, 1, At, B1); PG8_BAR; PG8_SCHED;
.LBB0_202:
	s_add_i32 s78, s38, 2
	s_add_u32 s79, s22, 0x80
	s_addc_u32 s39, s23, 0
	s_cmp_eq_u32 s33, s38
	s_cselect_b32 s39, s7, s39
	s_cselect_b32 s38, s6, s79
	v_add_u32_e32 v0, s19, v150
	s_cselect_b32 s81, s17, s77
	s_cselect_b32 s80, s16, s76
	s_add_i32 s79, 0, 0x14000
	ds_read_b128 v[152:155], v0
	ds_read_b128 v[156:159], v0 offset:1024
	ds_read_b128 v[160:163], v0 offset:2048
	ds_read_b128 v[164:167], v0 offset:3072
	v_add_u32_e32 v0, s79, v150
	ds_read_b128 v[168:171], v0
	ds_read_b128 v[172:175], v0 offset:1024
	ds_read_b128 v[176:179], v0 offset:2048
	ds_read_b128 v[184:187], v0 offset:3072
	v_lshl_add_u64 v[2:3], s[22:23], 0, v[144:145]
	s_add_i32 m0, s42, 0xc000
	ds_read_b128 v[188:191], v151
	ds_read_b128 v[192:195], v151 offset:1024
	ds_read_b128 v[196:199], v151 offset:2048
	ds_read_b128 v[200:203], v151 offset:3072
	ds_read_b128 v[204:207], v151 offset:4096
	ds_read_b128 v[230:233], v151 offset:5120
	ds_read_b128 v[234:237], v151 offset:6144
	ds_read_b128 v[238:241], v151 offset:7168
	global_load_lds_dwordx4 v[2:3], off
	v_lshl_add_u64 v[2:3], s[22:23], 0, v[146:147]
	s_add_i32 m0, s42, 0xe000
	s_nop 0
	global_load_lds_dwordx4 v[2:3], off
	s_waitcnt vmcnt(8)
	s_waitcnt lgkmcnt(0)
	s_barrier
	s_setprio 1
	s_waitcnt lgkmcnt(0)
	v_mfma_f32_16x16x32_bf16 v[132:135], v[152:155], v[188:191], v[132:135]
	v_mfma_f32_16x16x32_bf16 v[132:135], v[156:159], v[192:195], v[132:135]
	v_mfma_f32_16x16x32_bf16 v[116:119], v[156:159], v[200:203], v[116:119]
	v_mfma_f32_16x16x32_bf16 v[116:119], v[152:155], v[196:199], v[116:119]
	v_mfma_f32_16x16x32_bf16 v[100:103], v[152:155], v[204:207], v[100:103]
	v_mfma_f32_16x16x32_bf16 v[100:103], v[156:159], v[230:233], v[100:103]
	v_mfma_f32_16x16x32_bf16 v[84:87], v[156:159], v[238:241], v[84:87]
	v_mfma_f32_16x16x32_bf16 v[84:87], v[152:155], v[234:237], v[84:87]
	v_mfma_f32_16x16x32_bf16 v[80:83], v[160:163], v[234:237], v[80:83]
	v_mfma_f32_16x16x32_bf16 v[80:83], v[164:167], v[238:241], v[80:83]
	v_mfma_f32_16x16x32_bf16 v[96:99], v[164:167], v[230:233], v[96:99]
	v_mfma_f32_16x16x32_bf16 v[96:99], v[160:163], v[204:207], v[96:99]
	v_mfma_f32_16x16x32_bf16 v[112:115], v[160:163], v[196:199], v[112:115]
	v_mfma_f32_16x16x32_bf16 v[112:115], v[164:167], v[200:203], v[112:115]
	v_mfma_f32_16x16x32_bf16 v[128:131], v[164:167], v[192:195], v[128:131]
	v_mfma_f32_16x16x32_bf16 v[128:131], v[160:163], v[188:191], v[128:131]
	s_setprio 0
	s_setprio 1
	v_mfma_f32_16x16x32_bf16 v[124:127], v[168:171], v[188:191], v[124:127]
	v_mfma_f32_16x16x32_bf16 v[124:127], v[172:175], v[192:195], v[124:127]
	v_mfma_f32_16x16x32_bf16 v[108:111], v[172:175], v[200:203], v[108:111]
	v_mfma_f32_16x16x32_bf16 v[108:111], v[168:171], v[196:199], v[108:111]
	v_mfma_f32_16x16x32_bf16 v[92:95], v[168:171], v[204:207], v[92:95]
	v_mfma_f32_16x16x32_bf16 v[92:95], v[172:175], v[230:233], v[92:95]
	v_mfma_f32_16x16x32_bf16 v[76:79], v[172:175], v[238:241], v[76:79]
	v_mfma_f32_16x16x32_bf16 v[76:79], v[168:171], v[234:237], v[76:79]
	v_mfma_f32_16x16x32_bf16 v[72:75], v[176:179], v[234:237], v[72:75]
	v_mfma_f32_16x16x32_bf16 v[72:75], v[184:187], v[238:241], v[72:75]
	v_mfma_f32_16x16x32_bf16 v[88:91], v[184:187], v[230:233], v[88:91]
	v_mfma_f32_16x16x32_bf16 v[88:91], v[176:179], v[204:207], v[88:91]
	v_mfma_f32_16x16x32_bf16 v[104:107], v[176:179], v[196:199], v[104:107]
	v_mfma_f32_16x16x32_bf16 v[104:107], v[184:187], v[200:203], v[104:107]
	v_mfma_f32_16x16x32_bf16 v[120:123], v[184:187], v[192:195], v[120:123]
	v_mfma_f32_16x16x32_bf16 v[120:123], v[176:179], v[188:191], v[120:123]
	s_setprio 0
	s_barrier
	s_add_i32 s82, s19, s20
	v_lshl_add_u64 v[2:3], s[80:81], 0, v[140:141]
	s_mov_b32 m0, s82
	ds_read_b128 v[188:191], v151 offset:16384
	ds_read_b128 v[192:195], v151 offset:17408
	ds_read_b128 v[196:199], v151 offset:18432
	ds_read_b128 v[200:203], v151 offset:19456
	ds_read_b128 v[204:207], v151 offset:20480
	ds_read_b128 v[230:233], v151 offset:21504
	ds_read_b128 v[234:237], v151 offset:22528
	ds_read_b128 v[238:241], v151 offset:23552
	global_load_lds_dwordx4 v[2:3], off
	s_add_i32 m0, s82, 0x2000
	v_lshl_add_u64 v[180:181], s[80:81], 0, v[136:137]
	s_add_u32 s80, s80, s48
	s_addc_u32 s81, s81, s49
	s_add_i32 s79, s79, s20
	global_load_lds_dwordx4 v[180:181], off
	v_lshl_add_u64 v[208:209], s[80:81], 0, v[140:141]
	s_mov_b32 m0, s79
	v_lshl_add_u64 v[216:217], s[80:81], 0, v[136:137]
	global_load_lds_dwordx4 v[208:209], off
	s_add_i32 m0, s79, 0x2000
	v_lshl_add_u64 v[224:225], s[38:39], 0, v[142:143]
	global_load_lds_dwordx4 v[216:217], off
	s_mov_b32 m0, s42
	v_lshl_add_u64 v[226:227], s[38:39], 0, v[138:139]
	global_load_lds_dwordx4 v[224:225], off
	s_mov_b32 m0, s45
	s_nop 0
	global_load_lds_dwordx4 v[226:227], off
	s_waitcnt vmcnt(8)
	s_waitcnt lgkmcnt(0)
	s_barrier
; #define PG8_STAGE(bufoff, gbase, voff) do { _Pragma("unroll") for (int _i = 0; _i < 2; ++_i) \
;         __builtin_amdgcn_global_load_lds((const unsigned*)((const char*)(gbase) + (voff)[_i]), (PG8_LAS unsigned*)(lds + (bufoff) + ldsw + _i * 8192), 16, 0, 0); } while (0)
; #define PG8_LDA(dst, b, h) do { _Pragma("unroll") for (int m = 0; m < 4; ++m) _Pragma("unroll") for (int k = 0; k < 2; ++k) dst[m][k] = *(const PG8_LAS bf16x8*)(lds + PG8_SA(b, h) + aoff + m * 2048 + k * 1024); } while (0)
; #define PG8_LDB(dst, b, h) do { _Pragma("unroll") for (int n = 0; n < 2; ++n) _Pragma("unroll") for (int k = 0; k < 2; ++k) dst[n][k] = *(const PG8_LAS bf16x8*)(lds + PG8_SB(b, h) + boff + n * 2048 + k * 1024); } while (0)
; #define PG8_MMA(ai, bj, At, Bt) do { __builtin_amdgcn_s_setprio(1); _Pragma("unroll") for (int m = 0; m < 4; ++m) _Pragma("unroll") for (int n = 0; n < 2; ++n) _Pragma("unroll") for (int k = 0; k < 2; ++k) \
;         acc[ai][bj][m][n] = __builtin_amdgcn_mfma_f32_16x16x32_bf16(Bt[n][k], At[m][k], acc[ai][bj][m][n], 0, 0, 0); __builtin_amdgcn_s_setprio(0); } while (0)
; #define PG8_WAIT_V(n) asm volatile("s_waitcnt vmcnt(" #n ")" ::: "memory")
; #define PG8_WAIT_L(n) asm volatile("s_waitcnt lgkmcnt(" #n ")" ::: "memory")
; #define PG8_BAR __builtin_amdgcn_s_barrier()
; #define PG8_SCHED __builtin_amdgcn_sched_barrier(0)
; template <class Epi, class Sched, bool ALIGN_EPI = false, bool SP2 = false>
; __device__ __forceinline__ void gemm_phase(PG8_LAS unsigned char* lds, const Gemm g, const Sched& S, const Epi& E) {
;     ...
;             PG8_WAIT_V(8); PG8_WAIT_L(0); PG8_BAR; PG8_MMA(1, 0, At, B0); PG8_MMA(1, 1, At, B1); PG8_BAR; PG8_SCHED;
;             PG8_LDB(B0, 1, 0); PG8_LDB(B1, 1, 1); PG8_SCHED; PG8_LDA(At, 1, 0); PG8_STAGE(PG8_SA(0, 1), a2 + hstep, voffA);
;             PG8_WAIT_V(8); PG8_WAIT_L(0); PG8_BAR; PG8_MMA(0, 0, At, B0); PG8_MMA(0, 1, At, B1); PG8_BAR; PG8_SCHED;
	s_setprio 1
	s_waitcnt lgkmcnt(0)
	v_mfma_f32_16x16x32_bf16 v[68:71], v[152:155], v[188:191], v[68:71]
	v_mfma_f32_16x16x32_bf16 v[68:71], v[156:159], v[192:195], v[68:71]
	v_mfma_f32_16x16x32_bf16 v[52:55], v[156:159], v[200:203], v[52:55]
	v_mfma_f32_16x16x32_bf16 v[52:55], v[152:155], v[196:199], v[52:55]
	v_mfma_f32_16x16x32_bf16 v[36:39], v[152:155], v[204:207], v[36:39]
	v_mfma_f32_16x16x32_bf16 v[36:39], v[156:159], v[230:233], v[36:39]
	v_mfma_f32_16x16x32_bf16 v[20:23], v[156:159], v[238:241], v[20:23]
	v_mfma_f32_16x16x32_bf16 v[20:23], v[152:155], v[234:237], v[20:23]
	v_mfma_f32_16x16x32_bf16 v[16:19], v[160:163], v[234:237], v[16:19]
	v_mfma_f32_16x16x32_bf16 v[16:19], v[164:167], v[238:241], v[16:19]
	v_mfma_f32_16x16x32_bf16 v[32:35], v[164:167], v[230:233], v[32:35]
	v_mfma_f32_16x16x32_bf16 v[32:35], v[160:163], v[204:207], v[32:35]
	v_mfma_f32_16x16x32_bf16 v[48:51], v[160:163], v[196:199], v[48:51]
	v_mfma_f32_16x16x32_bf16 v[48:51], v[164:167], v[200:203], v[48:51]
	v_mfma_f32_16x16x32_bf16 v[64:67], v[164:167], v[192:195], v[64:67]
	v_mfma_f32_16x16x32_bf16 v[64:67], v[160:163], v[188:191], v[64:67]
	s_setprio 0
	s_setprio 1
	v_mfma_f32_16x16x32_bf16 v[60:63], v[168:171], v[188:191], v[60:63]
	v_mfma_f32_16x16x32_bf16 v[60:63], v[172:175], v[192:195], v[60:63]
	v_mfma_f32_16x16x32_bf16 v[44:47], v[172:175], v[200:203], v[44:47]
	v_mfma_f32_16x16x32_bf16 v[44:47], v[168:171], v[196:199], v[44:47]
	v_mfma_f32_16x16x32_bf16 v[28:31], v[168:171], v[204:207], v[28:31]
	v_mfma_f32_16x16x32_bf16 v[28:31], v[172:175], v[230:233], v[28:31]
	v_mfma_f32_16x16x32_bf16 v[12:15], v[172:175], v[238:241], v[12:15]
	v_mfma_f32_16x16x32_bf16 v[12:15], v[168:171], v[234:237], v[12:15]
	v_mfma_f32_16x16x32_bf16 v[8:11], v[176:179], v[234:237], v[8:11]
	v_mfma_f32_16x16x32_bf16 v[8:11], v[184:187], v[238:241], v[8:11]
	v_mfma_f32_16x16x32_bf16 v[24:27], v[184:187], v[230:233], v[24:27]
	v_mfma_f32_16x16x32_bf16 v[24:27], v[176:179], v[204:207], v[24:27]
	v_mfma_f32_16x16x32_bf16 v[40:43], v[176:179], v[196:199], v[40:43]
	v_mfma_f32_16x16x32_bf16 v[40:43], v[184:187], v[200:203], v[40:43]
	v_mfma_f32_16x16x32_bf16 v[56:59], v[184:187], v[192:195], v[56:59]
	v_mfma_f32_16x16x32_bf16 v[56:59], v[176:179], v[188:191], v[56:59]
	s_setprio 0
	s_barrier
	v_add_u32_e32 v0, s91, v150
	s_add_i32 s79, 0, 0x1c000
	ds_read_b128 v[152:155], v0
	ds_read_b128 v[156:159], v0 offset:1024
	ds_read_b128 v[160:163], v0 offset:2048
	ds_read_b128 v[164:167], v0 offset:3072
	v_add_u32_e32 v0, s79, v150
	ds_read_b128 v[168:171], v0
	ds_read_b128 v[172:175], v0 offset:1024
	ds_read_b128 v[176:179], v0 offset:2048
	ds_read_b128 v[184:187], v0 offset:3072
	s_add_u32 s38, s38, s48
	s_addc_u32 s39, s39, s49
	s_mov_b32 m0, s46
	v_lshl_add_u64 v[228:229], s[38:39], 0, v[142:143]
	ds_read_b128 v[188:191], v151 offset:32768
	ds_read_b128 v[192:195], v151 offset:33792
	ds_read_b128 v[196:199], v151 offset:34816
	ds_read_b128 v[200:203], v151 offset:35840
	ds_read_b128 v[204:207], v151 offset:36864
	ds_read_b128 v[230:233], v151 offset:37888
	ds_read_b128 v[234:237], v151 offset:38912
	ds_read_b128 v[238:241], v151 offset:39936
	global_load_lds_dwordx4 v[228:229], off
	v_lshl_add_u64 v[228:229], s[38:39], 0, v[138:139]
	s_mov_b32 m0, s47
	s_nop 0
	global_load_lds_dwordx4 v[228:229], off
	s_waitcnt vmcnt(8)
	s_waitcnt lgkmcnt(0)
	s_barrier
	s_setprio 1
	s_waitcnt lgkmcnt(0)
	v_mfma_f32_16x16x32_bf16 v[132:135], v[152:155], v[188:191], v[132:135]
	v_mfma_f32_16x16x32_bf16 v[132:135], v[156:159], v[192:195], v[132:135]
	v_mfma_f32_16x16x32_bf16 v[116:119], v[156:159], v[200:203], v[116:119]
	v_mfma_f32_16x16x32_bf16 v[116:119], v[152:155], v[196:199], v[116:119]
	v_mfma_f32_16x16x32_bf16 v[100:103], v[152:155], v[204:207], v[100:103]
	v_mfma_f32_16x16x32_bf16 v[100:103], v[156:159], v[230:233], v[100:103]
	v_mfma_f32_16x16x32_bf16 v[84:87], v[156:159], v[238:241], v[84:87]
	v_mfma_f32_16x16x32_bf16 v[84:87], v[152:155], v[234:237], v[84:87]
	v_mfma_f32_16x16x32_bf16 v[80:83], v[160:163], v[234:237], v[80:83]
	v_mfma_f32_16x16x32_bf16 v[80:83], v[164:167], v[238:241], v[80:83]
	v_mfma_f32_16x16x32_bf16 v[96:99], v[164:167], v[230:233], v[96:99]
	v_mfma_f32_16x16x32_bf16 v[96:99], v[160:163], v[204:207], v[96:99]
	v_mfma_f32_16x16x32_bf16 v[112:115], v[160:163], v[196:199], v[112:115]
	v_mfma_f32_16x16x32_bf16 v[112:115], v[164:167], v[200:203], v[112:115]
	v_mfma_f32_16x16x32_bf16 v[128:131], v[164:167], v[192:195], v[128:131]
	v_mfma_f32_16x16x32_bf16 v[128:131], v[160:163], v[188:191], v[128:131]
	s_setprio 0
	s_setprio 1
	v_mfma_f32_16x16x32_bf16 v[124:127], v[168:171], v[188:191], v[124:127]
	v_mfma_f32_16x16x32_bf16 v[124:127], v[172:175], v[192:195], v[124:127]
	v_mfma_f32_16x16x32_bf16 v[108:111], v[172:175], v[200:203], v[108:111]
	v_mfma_f32_16x16x32_bf16 v[108:111], v[168:171], v[196:199], v[108:111]
	v_mfma_f32_16x16x32_bf16 v[92:95], v[168:171], v[204:207], v[92:95]
	v_mfma_f32_16x16x32_bf16 v[92:95], v[172:175], v[230:233], v[92:95]
	v_mfma_f32_16x16x32_bf16 v[76:79], v[172:175], v[238:241], v[76:79]
	v_mfma_f32_16x16x32_bf16 v[76:79], v[168:171], v[234:237], v[76:79]
	v_mfma_f32_16x16x32_bf16 v[72:75], v[176:179], v[234:237], v[72:75]
	v_mfma_f32_16x16x32_bf16 v[72:75], v[184:187], v[238:241], v[72:75]
	v_mfma_f32_16x16x32_bf16 v[88:91], v[184:187], v[230:233], v[88:91]
	v_mfma_f32_16x16x32_bf16 v[88:91], v[176:179], v[204:207], v[88:91]
	v_mfma_f32_16x16x32_bf16 v[104:107], v[176:179], v[196:199], v[104:107]
	v_mfma_f32_16x16x32_bf16 v[104:107], v[184:187], v[200:203], v[104:107]
	v_mfma_f32_16x16x32_bf16 v[120:123], v[184:187], v[192:195], v[120:123]
	v_mfma_f32_16x16x32_bf16 v[120:123], v[176:179], v[188:191], v[120:123]
	s_setprio 0
	s_barrier
; #define PG8_STAGE(bufoff, gbase, voff) do { _Pragma("unroll") for (int _i = 0; _i < 2; ++_i) \
;         __builtin_amdgcn_global_load_lds((const unsigned*)((const char*)(gbase) + (voff)[_i]), (PG8_LAS unsigned*)(lds + (bufoff) + ldsw + _i * 8192), 16, 0, 0); } while (0)
; #define PG8_LDA(dst, b, h) do { _Pragma("unroll") for (int m = 0; m < 4; ++m) _Pragma("unroll") for (int k = 0; k < 2; ++k) dst[m][k] = *(const PG8_LAS bf16x8*)(lds + PG8_SA(b, h) + aoff + m * 2048 + k * 1024); } while (0)
; #define PG8_MMA(ai, bj, At, Bt) do { __builtin_amdgcn_s_setprio(1); _Pragma("unroll") for (int m = 0; m < 4; ++m) _Pragma("unroll") for (int n = 0; n < 2; ++n) _Pragma("unroll") for (int k = 0; k < 2; ++k) \
;         acc[ai][bj][m][n] = __builtin_amdgcn_mfma_f32_16x16x32_bf16(Bt[n][k], At[m][k], acc[ai][bj][m][n], 0, 0, 0); __builtin_amdgcn_s_setprio(0); } while (0)
; #define PG8_WAIT_V(n) asm volatile("s_waitcnt vmcnt(" #n ")" ::: "memory")
; #define PG8_WAIT_L(n) asm volatile("s_waitcnt lgkmcnt(" #n ")" ::: "memory")
; #define PG8_BAR __builtin_amdgcn_s_barrier()
; #define PG8_SCHED __builtin_amdgcn_sched_barrier(0)
; template <class Epi, class Sched, bool ALIGN_EPI = false, bool SP2 = false>
; __device__ __forceinline__ void gemm_phase(PG8_LAS unsigned char* lds, const Gemm g, const Sched& S, const Epi& E) {
;     ...
;         for (int t = 0; t < nt; t += 2) {
;     ...
;             PG8_LDA(At, 1, 1); PG8_STAGE(PG8_SB(1, 0), b3, voffB); PG8_STAGE(PG8_SB(1, 1), b3 + hstep, voffB); PG8_STAGE(PG8_SA(1, 0), a3, voffA);
;             PG8_WAIT_V(8); PG8_WAIT_L(0); PG8_BAR; PG8_MMA(1, 0, At, B0); PG8_MMA(1, 1, At, B1); PG8_BAR; PG8_SCHED;
	s_add_i32 s38, s91, s20
	v_lshl_add_u64 v[2:3], v[2:3], 0, s[24:25]
	s_mov_b32 m0, s38
	ds_read_b128 v[188:191], v151 offset:49152
	ds_read_b128 v[192:195], v151 offset:50176
	ds_read_b128 v[196:199], v151 offset:51200
	ds_read_b128 v[200:203], v151 offset:52224
	ds_read_b128 v[204:207], v151 offset:53248
	ds_read_b128 v[230:233], v151 offset:54272
	ds_read_b128 v[234:237], v151 offset:55296
	ds_read_b128 v[238:241], v151 offset:56320
	global_load_lds_dwordx4 v[2:3], off
	v_lshl_add_u64 v[2:3], v[180:181], 0, s[24:25]
	s_add_i32 m0, s38, 0x2000
	s_add_i32 s38, s79, s20
	global_load_lds_dwordx4 v[2:3], off
	v_lshl_add_u64 v[2:3], v[208:209], 0, s[24:25]
	s_mov_b32 m0, s38
	s_nop 0
	global_load_lds_dwordx4 v[2:3], off
	v_lshl_add_u64 v[2:3], v[216:217], 0, s[24:25]
	s_add_i32 m0, s38, 0x2000
	s_nop 0
	global_load_lds_dwordx4 v[2:3], off
	v_lshl_add_u64 v[2:3], v[224:225], 0, s[24:25]
	s_mov_b32 m0, s52
	s_nop 0
	global_load_lds_dwordx4 v[2:3], off
	v_lshl_add_u64 v[2:3], v[226:227], 0, s[24:25]
	s_mov_b32 m0, s53
	s_nop 0
	global_load_lds_dwordx4 v[2:3], off
	s_waitcnt vmcnt(8)
	s_waitcnt lgkmcnt(0)
	s_barrier
	s_setprio 1
	s_waitcnt lgkmcnt(0)
	v_mfma_f32_16x16x32_bf16 v[68:71], v[152:155], v[188:191], v[68:71]
	v_mfma_f32_16x16x32_bf16 v[68:71], v[156:159], v[192:195], v[68:71]
	v_mfma_f32_16x16x32_bf16 v[52:55], v[156:159], v[200:203], v[52:55]
	v_mfma_f32_16x16x32_bf16 v[52:55], v[152:155], v[196:199], v[52:55]
	v_mfma_f32_16x16x32_bf16 v[36:39], v[152:155], v[204:207], v[36:39]
	v_mfma_f32_16x16x32_bf16 v[36:39], v[156:159], v[230:233], v[36:39]
	v_mfma_f32_16x16x32_bf16 v[20:23], v[156:159], v[238:241], v[20:23]
	v_mfma_f32_16x16x32_bf16 v[20:23], v[152:155], v[234:237], v[20:23]
	v_mfma_f32_16x16x32_bf16 v[16:19], v[160:163], v[234:237], v[16:19]
	v_mfma_f32_16x16x32_bf16 v[16:19], v[164:167], v[238:241], v[16:19]
	v_mfma_f32_16x16x32_bf16 v[32:35], v[164:167], v[230:233], v[32:35]
	v_mfma_f32_16x16x32_bf16 v[32:35], v[160:163], v[204:207], v[32:35]
	v_mfma_f32_16x16x32_bf16 v[48:51], v[160:163], v[196:199], v[48:51]
	v_mfma_f32_16x16x32_bf16 v[48:51], v[164:167], v[200:203], v[48:51]
	v_mfma_f32_16x16x32_bf16 v[64:67], v[164:167], v[192:195], v[64:67]
	v_mfma_f32_16x16x32_bf16 v[64:67], v[160:163], v[188:191], v[64:67]
	s_setprio 0
	s_setprio 1
	v_mfma_f32_16x16x32_bf16 v[60:63], v[168:171], v[188:191], v[60:63]
	v_mfma_f32_16x16x32_bf16 v[60:63], v[172:175], v[192:195], v[60:63]
	v_mfma_f32_16x16x32_bf16 v[44:47], v[172:175], v[200:203], v[44:47]
	v_mfma_f32_16x16x32_bf16 v[44:47], v[168:171], v[196:199], v[44:47]
	v_mfma_f32_16x16x32_bf16 v[28:31], v[168:171], v[204:207], v[28:31]
	v_mfma_f32_16x16x32_bf16 v[28:31], v[172:175], v[230:233], v[28:31]
	v_mfma_f32_16x16x32_bf16 v[12:15], v[172:175], v[238:241], v[12:15]
	v_mfma_f32_16x16x32_bf16 v[12:15], v[168:171], v[234:237], v[12:15]
	v_mfma_f32_16x16x32_bf16 v[8:11], v[176:179], v[234:237], v[8:11]
	v_mfma_f32_16x16x32_bf16 v[8:11], v[184:187], v[238:241], v[8:11]
	v_mfma_f32_16x16x32_bf16 v[24:27], v[184:187], v[230:233], v[24:27]
	v_mfma_f32_16x16x32_bf16 v[24:27], v[176:179], v[204:207], v[24:27]
	v_mfma_f32_16x16x32_bf16 v[40:43], v[176:179], v[196:199], v[40:43]
	v_mfma_f32_16x16x32_bf16 v[40:43], v[184:187], v[200:203], v[40:43]
	v_mfma_f32_16x16x32_bf16 v[56:59], v[184:187], v[192:195], v[56:59]
	v_mfma_f32_16x16x32_bf16 v[56:59], v[176:179], v[188:191], v[56:59]
	s_setprio 0
	s_barrier
	s_add_u32 s22, s22, 0x100
	s_addc_u32 s23, s23, 0
	s_add_u32 s76, s76, 0x100
	s_addc_u32 s77, s77, 0
	s_cmp_ge_u32 s78, s9
	s_mov_b32 s38, s78
	s_cbranch_scc0 .LBB0_202

; #define PG8_STAGE(bufoff, gbase, voff) do { _Pragma("unroll") for (int _i = 0; _i < 2; ++_i) \
;         __builtin_amdgcn_global_load_lds((const unsigned*)((const char*)(gbase) + (voff)[_i]), (PG8_LAS unsigned*)(lds + (bufoff) + ldsw + _i * 8192), 16, 0, 0); } while (0)
; #define PG8_LDA(dst, b, h) do { _Pragma("unroll") for (int m = 0; m < 4; ++m) _Pragma("unroll") for (int k = 0; k < 2; ++k) dst[m][k] = *(const PG8_LAS bf16x8*)(lds + PG8_SA(b, h) + aoff + m * 2048 + k * 1024); } while (0)
; #define PG8_LDB(dst, b, h) do { _Pragma("unroll") for (int n = 0; n < 2; ++n) _Pragma("unroll") for (int k = 0; k < 2; ++k) dst[n][k] = *(const PG8_LAS bf16x8*)(lds + PG8_SB(b, h) + boff + n * 2048 + k * 1024); } while (0)
; #define PG8_MMA(ai, bj, At, Bt) do { __builtin_amdgcn_s_setprio(1); _Pragma("unroll") for (int m = 0; m < 4; ++m) _Pragma("unroll") for (int n = 0; n < 2; ++n) _Pragma("unroll") for (int k = 0; k < 2; ++k) \
;         acc[ai][bj][m][n] = __builtin_amdgcn_mfma_f32_16x16x32_bf16(Bt[n][k], At[m][k], acc[ai][bj][m][n], 0, 0, 0); __builtin_amdgcn_s_setprio(0); } while (0)
; #define PG8_WAIT_V(n) asm volatile("s_waitcnt vmcnt(" #n ")" ::: "memory")
; #define PG8_WAIT_L(n) asm volatile("s_waitcnt lgkmcnt(" #n ")" ::: "memory")
; template <class Epi, class Sched, bool ALIGN_EPI = false, bool SP2 = false>
; __device__ __forceinline__ void gemm_phase(PG8_LAS unsigned char* lds, const Gemm g, const Sched& S, const Epi& E) {
;     ...
;             const bool last = (t == nt - 2);
;             const char* a1 = cA + (size_t)(t + 1) * kstep;
;             const char* a2 = last ? nA : cA + (size_t)(t + 2) * kstep; const char* b2 = last ? nB : cB + (size_t)(t + 2) * kstep;
;             const char* a3 = a2 + kstep; const char* b3 = b2 + kstep;
;             if (last && has_next) S.a_ready(nxt);
;             if constexpr (SP2) {
;             PG8_LDB(B0, 0, 0); PG8_LDB(B1, 0, 1); PG8_SCHED; PG8_LDA(At, 0, 0); PG8_STAGE(PG8_SA(1, 1), a1 + hstep, voffA);
;             PG8_WAIT_V(8); PG8_WAIT_L(0); PG8_BAR; PG8_MMA(0, 0, At, B0); PG8_MMA(0, 1, At, B1); PG8_BAR; PG8_SCHED;
;             PG8_LDA(At, 0, 1); PG8_STAGE(PG8_SB(0, 0), b2, voffB); PG8_STAGE(PG8_SB(0, 1), b2 + hstep, voffB); PG8_STAGE(PG8_SA(0, 0), a2, voffA);
;             PG8_WAIT_V(8); PG8_WAIT_L(0); PG8_BAR; PG8_MMA(1, 0, At, B0); PG8_MMA(1, 1, At, B1); PG8_BAR; PG8_SCHED;
.LBB0_245:
	v_readlane_b32 s22, v252, 59
	v_readlane_b32 s23, v252, 60
	s_andn2_b64 vcc, exec, s[22:23]
	s_cbranch_vccnz .LBB0_252
	s_add_u32 s40, s6, s48
	s_addc_u32 s41, s7, s49
	s_add_u32 s37, s6, 0x100
	s_addc_u32 s80, s7, 0
	s_and_b64 s[22:23], s[12:13], exec
	s_cselect_b32 s23, s5, s80
	s_cselect_b32 s22, s4, s37
	s_add_u32 s37, s10, 0x100
	s_addc_u32 s82, s11, 0
	s_and_b64 s[80:81], s[12:13], exec
	s_cselect_b32 s85, s17, s82
	s_cselect_b32 s84, s16, s37
	s_add_i32 s83, 0, 0x14000
	v_add_u32_e32 v150, s19, v147
	v_add_u32_e32 v151, s83, v147
	ds_read_b128 v[152:155], v150
	ds_read_b128 v[156:159], v150 offset:1024
	ds_read_b128 v[160:163], v150 offset:2048
	ds_read_b128 v[164:167], v150 offset:3072
	ds_read_b128 v[168:171], v151
	ds_read_b128 v[172:175], v151 offset:1024
	ds_read_b128 v[176:179], v151 offset:2048
	ds_read_b128 v[184:187], v151 offset:3072
	v_lshl_add_u64 v[180:181], s[40:41], 0, v[2:3]
	s_add_i32 s37, s47, 0xc000
	v_lshl_add_u64 v[180:181], v[180:181], 0, s[24:25]
	s_mov_b32 m0, s37
	ds_read_b128 v[188:191], v149
	ds_read_b128 v[192:195], v149 offset:1024
	ds_read_b128 v[196:199], v149 offset:2048
	ds_read_b128 v[200:203], v149 offset:3072
	ds_read_b128 v[204:207], v149 offset:4096
	ds_read_b128 v[230:233], v149 offset:5120
	ds_read_b128 v[234:237], v149 offset:6144
	ds_read_b128 v[238:241], v149 offset:7168
	global_load_lds_dwordx4 v[180:181], off
	v_lshl_add_u64 v[180:181], s[40:41], 0, v[136:137]
	s_add_i32 s80, s47, 0xe000
	v_lshl_add_u64 v[180:181], v[180:181], 0, s[24:25]
	s_mov_b32 m0, s80
	s_nop 0
	global_load_lds_dwordx4 v[180:181], off
	s_waitcnt vmcnt(8)
	s_waitcnt lgkmcnt(0)
	s_barrier
	s_setprio 1
	s_waitcnt lgkmcnt(0)
	v_mfma_f32_16x16x32_bf16 v[132:135], v[152:155], v[188:191], v[132:135]
	v_mfma_f32_16x16x32_bf16 v[132:135], v[156:159], v[192:195], v[132:135]
	v_mfma_f32_16x16x32_bf16 v[116:119], v[156:159], v[200:203], v[116:119]
	v_mfma_f32_16x16x32_bf16 v[116:119], v[152:155], v[196:199], v[116:119]
	v_mfma_f32_16x16x32_bf16 v[100:103], v[152:155], v[204:207], v[100:103]
	v_mfma_f32_16x16x32_bf16 v[100:103], v[156:159], v[230:233], v[100:103]
	v_mfma_f32_16x16x32_bf16 v[84:87], v[156:159], v[238:241], v[84:87]
	v_mfma_f32_16x16x32_bf16 v[84:87], v[152:155], v[234:237], v[84:87]
	v_mfma_f32_16x16x32_bf16 v[80:83], v[160:163], v[234:237], v[80:83]
	v_mfma_f32_16x16x32_bf16 v[80:83], v[164:167], v[238:241], v[80:83]
	v_mfma_f32_16x16x32_bf16 v[96:99], v[164:167], v[230:233], v[96:99]
	v_mfma_f32_16x16x32_bf16 v[96:99], v[160:163], v[204:207], v[96:99]
	v_mfma_f32_16x16x32_bf16 v[112:115], v[160:163], v[196:199], v[112:115]
	v_mfma_f32_16x16x32_bf16 v[112:115], v[164:167], v[200:203], v[112:115]
	v_mfma_f32_16x16x32_bf16 v[128:131], v[164:167], v[192:195], v[128:131]
	v_mfma_f32_16x16x32_bf16 v[128:131], v[160:163], v[188:191], v[128:131]
	s_setprio 0
	s_setprio 1
	v_mfma_f32_16x16x32_bf16 v[124:127], v[168:171], v[188:191], v[124:127]
	v_mfma_f32_16x16x32_bf16 v[124:127], v[172:175], v[192:195], v[124:127]
	v_mfma_f32_16x16x32_bf16 v[108:111], v[172:175], v[200:203], v[108:111]
	v_mfma_f32_16x16x32_bf16 v[108:111], v[168:171], v[196:199], v[108:111]
	v_mfma_f32_16x16x32_bf16 v[92:95], v[168:171], v[204:207], v[92:95]
	v_mfma_f32_16x16x32_bf16 v[92:95], v[172:175], v[230:233], v[92:95]
	v_mfma_f32_16x16x32_bf16 v[76:79], v[172:175], v[238:241], v[76:79]
	v_mfma_f32_16x16x32_bf16 v[76:79], v[168:171], v[234:237], v[76:79]
	v_mfma_f32_16x16x32_bf16 v[72:75], v[176:179], v[234:237], v[72:75]
	v_mfma_f32_16x16x32_bf16 v[72:75], v[184:187], v[238:241], v[72:75]
	v_mfma_f32_16x16x32_bf16 v[88:91], v[184:187], v[230:233], v[88:91]
	v_mfma_f32_16x16x32_bf16 v[88:91], v[176:179], v[204:207], v[88:91]
	v_mfma_f32_16x16x32_bf16 v[104:107], v[176:179], v[196:199], v[104:107]
	v_mfma_f32_16x16x32_bf16 v[104:107], v[184:187], v[200:203], v[104:107]
	v_mfma_f32_16x16x32_bf16 v[120:123], v[184:187], v[192:195], v[120:123]
	v_mfma_f32_16x16x32_bf16 v[120:123], v[176:179], v[188:191], v[120:123]
	s_setprio 0
	s_barrier
	s_add_i32 s81, s19, s46
	s_add_i32 s82, s81, 0x2000
	v_lshl_add_u64 v[208:209], s[84:85], 0, v[0:1]
	s_mov_b32 m0, s81
	s_add_u32 s40, s84, s48
	ds_read_b128 v[188:191], v149 offset:16384
	ds_read_b128 v[192:195], v149 offset:17408
	ds_read_b128 v[196:199], v149 offset:18432
	ds_read_b128 v[200:203], v149 offset:19456
	ds_read_b128 v[204:207], v149 offset:20480
	ds_read_b128 v[230:233], v149 offset:21504
	ds_read_b128 v[234:237], v149 offset:22528
	ds_read_b128 v[238:241], v149 offset:23552
	global_load_lds_dwordx4 v[208:209], off
	v_lshl_add_u64 v[216:217], s[84:85], 0, v[138:139]
	s_mov_b32 m0, s82
	s_addc_u32 s41, s85, s49
	s_add_i32 s83, s83, s46
	global_load_lds_dwordx4 v[216:217], off
	v_lshl_add_u64 v[224:225], s[40:41], 0, v[0:1]
	s_mov_b32 m0, s83
	s_add_i32 s84, s83, 0x2000
	global_load_lds_dwordx4 v[224:225], off
	v_lshl_add_u64 v[226:227], s[40:41], 0, v[138:139]
	s_mov_b32 m0, s84
	v_lshl_add_u64 v[228:229], s[22:23], 0, v[2:3]
	global_load_lds_dwordx4 v[226:227], off
	s_mov_b32 m0, s47
	v_lshl_add_u64 v[242:243], s[22:23], 0, v[136:137]
	global_load_lds_dwordx4 v[228:229], off
	s_mov_b32 m0, s52
	s_nop 0
	global_load_lds_dwordx4 v[242:243], off
	s_waitcnt vmcnt(8)
	s_waitcnt lgkmcnt(0)
	s_barrier
; #define PG8_STAGE(bufoff, gbase, voff) do { _Pragma("unroll") for (int _i = 0; _i < 2; ++_i) \
;         __builtin_amdgcn_global_load_lds((const unsigned*)((const char*)(gbase) + (voff)[_i]), (PG8_LAS unsigned*)(lds + (bufoff) + ldsw + _i * 8192), 16, 0, 0); } while (0)
; #define PG8_LDA(dst, b, h) do { _Pragma("unroll") for (int m = 0; m < 4; ++m) _Pragma("unroll") for (int k = 0; k < 2; ++k) dst[m][k] = *(const PG8_LAS bf16x8*)(lds + PG8_SA(b, h) + aoff + m * 2048 + k * 1024); } while (0)
; #define PG8_LDB(dst, b, h) do { _Pragma("unroll") for (int n = 0; n < 2; ++n) _Pragma("unroll") for (int k = 0; k < 2; ++k) dst[n][k] = *(const PG8_LAS bf16x8*)(lds + PG8_SB(b, h) + boff + n * 2048 + k * 1024); } while (0)
; #define PG8_MMA(ai, bj, At, Bt) do { __builtin_amdgcn_s_setprio(1); _Pragma("unroll") for (int m = 0; m < 4; ++m) _Pragma("unroll") for (int n = 0; n < 2; ++n) _Pragma("unroll") for (int k = 0; k < 2; ++k) \
;         acc[ai][bj][m][n] = __builtin_amdgcn_mfma_f32_16x16x32_bf16(Bt[n][k], At[m][k], acc[ai][bj][m][n], 0, 0, 0); __builtin_amdgcn_s_setprio(0); } while (0)
; #define PG8_WAIT_V(n) asm volatile("s_waitcnt vmcnt(" #n ")" ::: "memory")
; #define PG8_WAIT_L(n) asm volatile("s_waitcnt lgkmcnt(" #n ")" ::: "memory")
; #define PG8_BAR __builtin_amdgcn_s_barrier()
; #define PG8_SCHED __builtin_amdgcn_sched_barrier(0)
; template <class Epi, class Sched, bool ALIGN_EPI = false, bool SP2 = false>
; __device__ __forceinline__ void gemm_phase(PG8_LAS unsigned char* lds, const Gemm g, const Sched& S, const Epi& E) {
;     ...
;             PG8_WAIT_V(8); PG8_WAIT_L(0); PG8_BAR; PG8_MMA(1, 0, At, B0); PG8_MMA(1, 1, At, B1); PG8_BAR; PG8_SCHED;
;             PG8_LDB(B0, 1, 0); PG8_LDB(B1, 1, 1); PG8_SCHED; PG8_LDA(At, 1, 0); PG8_STAGE(PG8_SA(0, 1), a2 + hstep, voffA);
;             PG8_WAIT_V(8); PG8_WAIT_L(0); PG8_BAR; PG8_MMA(0, 0, At, B0); PG8_MMA(0, 1, At, B1); PG8_BAR; PG8_SCHED;
	s_setprio 1
	s_waitcnt lgkmcnt(0)
	v_mfma_f32_16x16x32_bf16 v[68:71], v[152:155], v[188:191], v[68:71]
	v_mfma_f32_16x16x32_bf16 v[68:71], v[156:159], v[192:195], v[68:71]
	v_mfma_f32_16x16x32_bf16 v[52:55], v[156:159], v[200:203], v[52:55]
	v_mfma_f32_16x16x32_bf16 v[52:55], v[152:155], v[196:199], v[52:55]
	v_mfma_f32_16x16x32_bf16 v[36:39], v[152:155], v[204:207], v[36:39]
	v_mfma_f32_16x16x32_bf16 v[36:39], v[156:159], v[230:233], v[36:39]
	v_mfma_f32_16x16x32_bf16 v[20:23], v[156:159], v[238:241], v[20:23]
	v_mfma_f32_16x16x32_bf16 v[20:23], v[152:155], v[234:237], v[20:23]
	v_mfma_f32_16x16x32_bf16 v[16:19], v[160:163], v[234:237], v[16:19]
	v_mfma_f32_16x16x32_bf16 v[16:19], v[164:167], v[238:241], v[16:19]
	v_mfma_f32_16x16x32_bf16 v[32:35], v[164:167], v[230:233], v[32:35]
	v_mfma_f32_16x16x32_bf16 v[32:35], v[160:163], v[204:207], v[32:35]
	v_mfma_f32_16x16x32_bf16 v[48:51], v[160:163], v[196:199], v[48:51]
	v_mfma_f32_16x16x32_bf16 v[48:51], v[164:167], v[200:203], v[48:51]
	v_mfma_f32_16x16x32_bf16 v[64:67], v[164:167], v[192:195], v[64:67]
	v_mfma_f32_16x16x32_bf16 v[64:67], v[160:163], v[188:191], v[64:67]
	s_setprio 0
	s_setprio 1
	v_mfma_f32_16x16x32_bf16 v[60:63], v[168:171], v[188:191], v[60:63]
	v_mfma_f32_16x16x32_bf16 v[60:63], v[172:175], v[192:195], v[60:63]
	v_mfma_f32_16x16x32_bf16 v[44:47], v[172:175], v[200:203], v[44:47]
	v_mfma_f32_16x16x32_bf16 v[44:47], v[168:171], v[196:199], v[44:47]
	v_mfma_f32_16x16x32_bf16 v[28:31], v[168:171], v[204:207], v[28:31]
	v_mfma_f32_16x16x32_bf16 v[28:31], v[172:175], v[230:233], v[28:31]
	v_mfma_f32_16x16x32_bf16 v[12:15], v[172:175], v[238:241], v[12:15]
	v_mfma_f32_16x16x32_bf16 v[12:15], v[168:171], v[234:237], v[12:15]
	v_mfma_f32_16x16x32_bf16 v[8:11], v[176:179], v[234:237], v[8:11]
	v_mfma_f32_16x16x32_bf16 v[8:11], v[184:187], v[238:241], v[8:11]
	v_mfma_f32_16x16x32_bf16 v[24:27], v[184:187], v[230:233], v[24:27]
	v_mfma_f32_16x16x32_bf16 v[24:27], v[176:179], v[204:207], v[24:27]
	v_mfma_f32_16x16x32_bf16 v[40:43], v[176:179], v[196:199], v[40:43]
	v_mfma_f32_16x16x32_bf16 v[40:43], v[184:187], v[200:203], v[40:43]
	v_mfma_f32_16x16x32_bf16 v[56:59], v[184:187], v[192:195], v[56:59]
	v_mfma_f32_16x16x32_bf16 v[56:59], v[176:179], v[188:191], v[56:59]
	s_setprio 0
	s_barrier
	s_add_i32 s87, 0, 0x1c000
	v_add_u32_e32 v152, s91, v147
	v_add_u32_e32 v153, s87, v147
	ds_read_b128 v[154:157], v152
	ds_read_b128 v[158:161], v152 offset:1024
	ds_read_b128 v[162:165], v152 offset:2048
	ds_read_b128 v[166:169], v152 offset:3072
	ds_read_b128 v[170:173], v153
	ds_read_b128 v[174:177], v153 offset:1024
	ds_read_b128 v[178:181], v153 offset:2048
	ds_read_b128 v[184:187], v153 offset:3072
	s_add_u32 s22, s22, s48
	s_addc_u32 s23, s23, s49
	s_mov_b32 m0, s53
	v_lshl_add_u64 v[244:245], s[22:23], 0, v[2:3]
	ds_read_b128 v[188:191], v149 offset:32768
	ds_read_b128 v[192:195], v149 offset:33792
	ds_read_b128 v[196:199], v149 offset:34816
	ds_read_b128 v[200:203], v149 offset:35840
	ds_read_b128 v[204:207], v149 offset:36864
	ds_read_b128 v[230:233], v149 offset:37888
	ds_read_b128 v[234:237], v149 offset:38912
	ds_read_b128 v[238:241], v149 offset:39936
	global_load_lds_dwordx4 v[244:245], off
	v_lshl_add_u64 v[244:245], s[22:23], 0, v[136:137]
	s_mov_b32 m0, s72
	s_nop 0
	global_load_lds_dwordx4 v[244:245], off
	s_waitcnt vmcnt(8)
	s_waitcnt lgkmcnt(0)
	s_barrier
	s_setprio 1
	s_waitcnt lgkmcnt(0)
	v_mfma_f32_16x16x32_bf16 v[132:135], v[154:157], v[188:191], v[132:135]
	v_mfma_f32_16x16x32_bf16 v[132:135], v[158:161], v[192:195], v[132:135]
	v_mfma_f32_16x16x32_bf16 v[116:119], v[158:161], v[200:203], v[116:119]
	v_mfma_f32_16x16x32_bf16 v[116:119], v[154:157], v[196:199], v[116:119]
	v_mfma_f32_16x16x32_bf16 v[100:103], v[154:157], v[204:207], v[100:103]
	v_mfma_f32_16x16x32_bf16 v[100:103], v[158:161], v[230:233], v[100:103]
	v_mfma_f32_16x16x32_bf16 v[84:87], v[158:161], v[238:241], v[84:87]
	v_mfma_f32_16x16x32_bf16 v[84:87], v[154:157], v[234:237], v[84:87]
	v_mfma_f32_16x16x32_bf16 v[80:83], v[162:165], v[234:237], v[80:83]
	v_mfma_f32_16x16x32_bf16 v[80:83], v[166:169], v[238:241], v[80:83]
	v_mfma_f32_16x16x32_bf16 v[96:99], v[166:169], v[230:233], v[96:99]
	v_mfma_f32_16x16x32_bf16 v[96:99], v[162:165], v[204:207], v[96:99]
	v_mfma_f32_16x16x32_bf16 v[112:115], v[162:165], v[196:199], v[112:115]
	v_mfma_f32_16x16x32_bf16 v[112:115], v[166:169], v[200:203], v[112:115]
	v_mfma_f32_16x16x32_bf16 v[128:131], v[166:169], v[192:195], v[128:131]
	v_mfma_f32_16x16x32_bf16 v[128:131], v[162:165], v[188:191], v[128:131]
	s_setprio 0
	s_setprio 1
	v_mfma_f32_16x16x32_bf16 v[124:127], v[170:173], v[188:191], v[124:127]
	v_mfma_f32_16x16x32_bf16 v[124:127], v[174:177], v[192:195], v[124:127]
	v_mfma_f32_16x16x32_bf16 v[108:111], v[174:177], v[200:203], v[108:111]
	v_mfma_f32_16x16x32_bf16 v[108:111], v[170:173], v[196:199], v[108:111]
	v_mfma_f32_16x16x32_bf16 v[92:95], v[170:173], v[204:207], v[92:95]
	v_mfma_f32_16x16x32_bf16 v[92:95], v[174:177], v[230:233], v[92:95]
	v_mfma_f32_16x16x32_bf16 v[76:79], v[174:177], v[238:241], v[76:79]
	v_mfma_f32_16x16x32_bf16 v[76:79], v[170:173], v[234:237], v[76:79]
	v_mfma_f32_16x16x32_bf16 v[72:75], v[178:181], v[234:237], v[72:75]
	v_mfma_f32_16x16x32_bf16 v[72:75], v[184:187], v[238:241], v[72:75]
	v_mfma_f32_16x16x32_bf16 v[88:91], v[184:187], v[230:233], v[88:91]
	v_mfma_f32_16x16x32_bf16 v[88:91], v[178:181], v[204:207], v[88:91]
	v_mfma_f32_16x16x32_bf16 v[104:107], v[178:181], v[196:199], v[104:107]
	v_mfma_f32_16x16x32_bf16 v[104:107], v[184:187], v[200:203], v[104:107]
	v_mfma_f32_16x16x32_bf16 v[120:123], v[184:187], v[192:195], v[120:123]
	v_mfma_f32_16x16x32_bf16 v[120:123], v[178:181], v[188:191], v[120:123]
	s_setprio 0
	s_barrier
; #define PG8_STAGE(bufoff, gbase, voff) do { _Pragma("unroll") for (int _i = 0; _i < 2; ++_i) \
;         __builtin_amdgcn_global_load_lds((const unsigned*)((const char*)(gbase) + (voff)[_i]), (PG8_LAS unsigned*)(lds + (bufoff) + ldsw + _i * 8192), 16, 0, 0); } while (0)
; #define PG8_LDA(dst, b, h) do { _Pragma("unroll") for (int m = 0; m < 4; ++m) _Pragma("unroll") for (int k = 0; k < 2; ++k) dst[m][k] = *(const PG8_LAS bf16x8*)(lds + PG8_SA(b, h) + aoff + m * 2048 + k * 1024); } while (0)
; #define PG8_MMA(ai, bj, At, Bt) do { __builtin_amdgcn_s_setprio(1); _Pragma("unroll") for (int m = 0; m < 4; ++m) _Pragma("unroll") for (int n = 0; n < 2; ++n) _Pragma("unroll") for (int k = 0; k < 2; ++k) \
;         acc[ai][bj][m][n] = __builtin_amdgcn_mfma_f32_16x16x32_bf16(Bt[n][k], At[m][k], acc[ai][bj][m][n], 0, 0, 0); __builtin_amdgcn_s_setprio(0); } while (0)
; #define PG8_WAIT_V(n) asm volatile("s_waitcnt vmcnt(" #n ")" ::: "memory")
; #define PG8_WAIT_L(n) asm volatile("s_waitcnt lgkmcnt(" #n ")" ::: "memory")
; #define PG8_BAR __builtin_amdgcn_s_barrier()
; #define PG8_SCHED __builtin_amdgcn_sched_barrier(0)
; template <class Epi, class Sched, bool ALIGN_EPI = false, bool SP2 = false>
; __device__ __forceinline__ void gemm_phase(PG8_LAS unsigned char* lds, const Gemm g, const Sched& S, const Epi& E) {
;     ...
;             if constexpr (Epi::KHOOK) { if ((t & 7) == 0 && t != 0) E.khook(acc, t >> 3, wr, fr, lds); }
;     ...
;             PG8_LDA(At, 1, 1); PG8_STAGE(PG8_SB(1, 0), b3, voffB); PG8_STAGE(PG8_SB(1, 1), b3 + hstep, voffB); PG8_STAGE(PG8_SA(1, 0), a3, voffA);
;             PG8_WAIT_V(8); PG8_WAIT_L(0); PG8_BAR; PG8_MMA(1, 0, At, B0); PG8_MMA(1, 1, At, B1); PG8_BAR; PG8_SCHED;
	s_add_i32 s85, s91, s46
	v_lshl_add_u64 v[208:209], v[208:209], 0, s[24:25]
	s_mov_b32 m0, s85
	s_add_i32 s86, s85, 0x2000
	ds_read_b128 v[188:191], v149 offset:49152
	ds_read_b128 v[192:195], v149 offset:50176
	ds_read_b128 v[196:199], v149 offset:51200
	ds_read_b128 v[200:203], v149 offset:52224
	ds_read_b128 v[204:207], v149 offset:53248
	ds_read_b128 v[230:233], v149 offset:54272
	ds_read_b128 v[234:237], v149 offset:55296
	ds_read_b128 v[238:241], v149 offset:56320
	global_load_lds_dwordx4 v[208:209], off
	v_lshl_add_u64 v[208:209], v[216:217], 0, s[24:25]
	s_mov_b32 m0, s86
	s_add_i32 s87, s87, s46
	global_load_lds_dwordx4 v[208:209], off
	v_lshl_add_u64 v[208:209], v[224:225], 0, s[24:25]
	s_mov_b32 m0, s87
	s_add_i32 s88, s87, 0x2000
	global_load_lds_dwordx4 v[208:209], off
	v_lshl_add_u64 v[208:209], v[226:227], 0, s[24:25]
	s_mov_b32 m0, s88
	s_nop 0
	global_load_lds_dwordx4 v[208:209], off
	v_lshl_add_u64 v[208:209], v[228:229], 0, s[24:25]
	s_mov_b32 m0, s75
	s_nop 0
	global_load_lds_dwordx4 v[208:209], off
	v_lshl_add_u64 v[208:209], v[242:243], 0, s[24:25]
	s_mov_b32 m0, s76
	s_nop 0
	global_load_lds_dwordx4 v[208:209], off
	s_waitcnt vmcnt(8)
	s_waitcnt lgkmcnt(0)
	s_barrier
	s_setprio 1
	s_waitcnt lgkmcnt(0)
	v_mfma_f32_16x16x32_bf16 v[68:71], v[154:157], v[188:191], v[68:71]
	v_mfma_f32_16x16x32_bf16 v[68:71], v[158:161], v[192:195], v[68:71]
	v_mfma_f32_16x16x32_bf16 v[52:55], v[158:161], v[200:203], v[52:55]
	v_mfma_f32_16x16x32_bf16 v[52:55], v[154:157], v[196:199], v[52:55]
	v_mfma_f32_16x16x32_bf16 v[36:39], v[154:157], v[204:207], v[36:39]
	v_mfma_f32_16x16x32_bf16 v[36:39], v[158:161], v[230:233], v[36:39]
	v_mfma_f32_16x16x32_bf16 v[20:23], v[158:161], v[238:241], v[20:23]
	v_mfma_f32_16x16x32_bf16 v[20:23], v[154:157], v[234:237], v[20:23]
	v_mfma_f32_16x16x32_bf16 v[16:19], v[162:165], v[234:237], v[16:19]
	v_mfma_f32_16x16x32_bf16 v[16:19], v[166:169], v[238:241], v[16:19]
	v_mfma_f32_16x16x32_bf16 v[32:35], v[166:169], v[230:233], v[32:35]
	v_mfma_f32_16x16x32_bf16 v[32:35], v[162:165], v[204:207], v[32:35]
	v_mfma_f32_16x16x32_bf16 v[48:51], v[162:165], v[196:199], v[48:51]
	v_mfma_f32_16x16x32_bf16 v[48:51], v[166:169], v[200:203], v[48:51]
	v_mfma_f32_16x16x32_bf16 v[64:67], v[166:169], v[192:195], v[64:67]
	v_mfma_f32_16x16x32_bf16 v[64:67], v[162:165], v[188:191], v[64:67]
	s_setprio 0
	s_setprio 1
	v_mfma_f32_16x16x32_bf16 v[60:63], v[170:173], v[188:191], v[60:63]
	v_mfma_f32_16x16x32_bf16 v[60:63], v[174:177], v[192:195], v[60:63]
	v_mfma_f32_16x16x32_bf16 v[44:47], v[174:177], v[200:203], v[44:47]
	v_mfma_f32_16x16x32_bf16 v[44:47], v[170:173], v[196:199], v[44:47]
	v_mfma_f32_16x16x32_bf16 v[28:31], v[170:173], v[204:207], v[28:31]
	v_mfma_f32_16x16x32_bf16 v[28:31], v[174:177], v[230:233], v[28:31]
	v_mfma_f32_16x16x32_bf16 v[12:15], v[174:177], v[238:241], v[12:15]
	v_mfma_f32_16x16x32_bf16 v[12:15], v[170:173], v[234:237], v[12:15]
	v_mfma_f32_16x16x32_bf16 v[8:11], v[178:181], v[234:237], v[8:11]
	v_mfma_f32_16x16x32_bf16 v[8:11], v[184:187], v[238:241], v[8:11]
	v_mfma_f32_16x16x32_bf16 v[24:27], v[184:187], v[230:233], v[24:27]
	v_mfma_f32_16x16x32_bf16 v[24:27], v[178:181], v[204:207], v[24:27]
	v_mfma_f32_16x16x32_bf16 v[40:43], v[178:181], v[196:199], v[40:43]
	v_mfma_f32_16x16x32_bf16 v[40:43], v[184:187], v[200:203], v[40:43]
	v_mfma_f32_16x16x32_bf16 v[56:59], v[184:187], v[192:195], v[56:59]
	v_mfma_f32_16x16x32_bf16 v[56:59], v[178:181], v[188:191], v[56:59]
	s_setprio 0
	s_barrier
	v_readlane_b32 s22, v252, 42
	v_readlane_b32 s23, v252, 43
	s_andn2_b64 vcc, exec, s[22:23]
	s_cbranch_vccnz .LBB0_251
	s_add_u32 s22, s6, 0x180
	s_addc_u32 s23, s7, 0
	s_add_u32 s89, s10, 0x200
	s_addc_u32 s92, s11, 0
	s_mov_b32 s93, 4
	v_mov_b32_e32 v154, v148
	s_add_i32 s40, s93, -2
	s_and_b32 s40, s40, 6
	s_cmp_lg_u32 s40, 0
	s_cbranch_scc1 .LBB0_250
	s_branch .LBB0_249

; #define PG8_STAGE(bufoff, gbase, voff) do { _Pragma("unroll") for (int _i = 0; _i < 2; ++_i) \
;         __builtin_amdgcn_global_load_lds((const unsigned*)((const char*)(gbase) + (voff)[_i]), (PG8_LAS unsigned*)(lds + (bufoff) + ldsw + _i * 8192), 16, 0, 0); } while (0)
; #define PG8_LDA(dst, b, h) do { _Pragma("unroll") for (int m = 0; m < 4; ++m) _Pragma("unroll") for (int k = 0; k < 2; ++k) dst[m][k] = *(const PG8_LAS bf16x8*)(lds + PG8_SA(b, h) + aoff + m * 2048 + k * 1024); } while (0)
; #define PG8_LDB(dst, b, h) do { _Pragma("unroll") for (int n = 0; n < 2; ++n) _Pragma("unroll") for (int k = 0; k < 2; ++k) dst[n][k] = *(const PG8_LAS bf16x8*)(lds + PG8_SB(b, h) + boff + n * 2048 + k * 1024); } while (0)
; #define PG8_MMA(ai, bj, At, Bt) do { __builtin_amdgcn_s_setprio(1); _Pragma("unroll") for (int m = 0; m < 4; ++m) _Pragma("unroll") for (int n = 0; n < 2; ++n) _Pragma("unroll") for (int k = 0; k < 2; ++k) \
;         acc[ai][bj][m][n] = __builtin_amdgcn_mfma_f32_16x16x32_bf16(Bt[n][k], At[m][k], acc[ai][bj][m][n], 0, 0, 0); __builtin_amdgcn_s_setprio(0); } while (0)
; #define PG8_WAIT_V(n) asm volatile("s_waitcnt vmcnt(" #n ")" ::: "memory")
; #define PG8_WAIT_L(n) asm volatile("s_waitcnt lgkmcnt(" #n ")" ::: "memory")
; #define PG8_BAR __builtin_amdgcn_s_barrier()
; #define PG8_SCHED __builtin_amdgcn_sched_barrier(0)
; template <class Epi, class Sched, bool ALIGN_EPI = false, bool SP2 = false>
; __device__ __forceinline__ void gemm_phase(PG8_LAS unsigned char* lds, const Gemm g, const Sched& S, const Epi& E) {
;     ...
;             PG8_LDB(B0, 0, 0); PG8_LDB(B1, 0, 1); PG8_SCHED; PG8_LDA(At, 0, 0); PG8_STAGE(PG8_SA(1, 1), a1 + hstep, voffA);
;             PG8_WAIT_V(8); PG8_WAIT_L(0); PG8_BAR; PG8_MMA(0, 0, At, B0); PG8_MMA(0, 1, At, B1); PG8_BAR; PG8_SCHED;
;             PG8_LDA(At, 0, 1); PG8_STAGE(PG8_SB(0, 0), b2, voffB); PG8_STAGE(PG8_SB(0, 1), b2 + hstep, voffB); PG8_STAGE(PG8_SA(0, 0), a2, voffA);
;             PG8_WAIT_V(8); PG8_WAIT_L(0); PG8_BAR; PG8_MMA(1, 0, At, B0); PG8_MMA(1, 1, At, B1); PG8_BAR; PG8_SCHED;
.LBB0_250:
	ds_read_b128 v[156:159], v150
	ds_read_b128 v[160:163], v150 offset:1024
	ds_read_b128 v[164:167], v150 offset:2048
	ds_read_b128 v[168:171], v150 offset:3072
	ds_read_b128 v[172:175], v151
	ds_read_b128 v[176:179], v151 offset:1024
	ds_read_b128 v[184:187], v151 offset:2048
	ds_read_b128 v[188:191], v151 offset:3072
	s_add_u32 s40, s22, 0x80
	s_addc_u32 s41, s23, 0
	s_cmp_eq_u32 s9, s93
	s_cselect_b32 s40, s4, s40
	s_cselect_b32 s41, s5, s41
	s_cselect_b32 s95, s17, s92
	s_cselect_b32 s94, s16, s89
	s_mov_b32 m0, s37
	v_lshl_add_u64 v[180:181], s[22:23], 0, v[140:141]
	ds_read_b128 v[192:195], v149
	ds_read_b128 v[196:199], v149 offset:1024
	ds_read_b128 v[200:203], v149 offset:2048
	ds_read_b128 v[204:207], v149 offset:3072
	ds_read_b128 v[230:233], v149 offset:4096
	ds_read_b128 v[234:237], v149 offset:5120
	ds_read_b128 v[238:241], v149 offset:6144
	ds_read_b128 v[242:245], v149 offset:7168
	global_load_lds_dwordx4 v[180:181], off
	v_lshl_add_u64 v[180:181], s[22:23], 0, v[142:143]
	s_mov_b32 m0, s80
	s_nop 0
	global_load_lds_dwordx4 v[180:181], off
	s_waitcnt vmcnt(8)
	s_waitcnt lgkmcnt(0)
	s_barrier
	s_setprio 1
	s_waitcnt lgkmcnt(0)
	v_mfma_f32_16x16x32_bf16 v[132:135], v[156:159], v[192:195], v[132:135]
	v_mfma_f32_16x16x32_bf16 v[132:135], v[160:163], v[196:199], v[132:135]
	v_mfma_f32_16x16x32_bf16 v[116:119], v[160:163], v[204:207], v[116:119]
	v_mfma_f32_16x16x32_bf16 v[116:119], v[156:159], v[200:203], v[116:119]
	v_mfma_f32_16x16x32_bf16 v[100:103], v[156:159], v[230:233], v[100:103]
	v_mfma_f32_16x16x32_bf16 v[100:103], v[160:163], v[234:237], v[100:103]
	v_mfma_f32_16x16x32_bf16 v[84:87], v[160:163], v[242:245], v[84:87]
	v_mfma_f32_16x16x32_bf16 v[84:87], v[156:159], v[238:241], v[84:87]
	v_mfma_f32_16x16x32_bf16 v[80:83], v[164:167], v[238:241], v[80:83]
	v_mfma_f32_16x16x32_bf16 v[80:83], v[168:171], v[242:245], v[80:83]
	v_mfma_f32_16x16x32_bf16 v[96:99], v[168:171], v[234:237], v[96:99]
	v_mfma_f32_16x16x32_bf16 v[96:99], v[164:167], v[230:233], v[96:99]
	v_mfma_f32_16x16x32_bf16 v[112:115], v[164:167], v[200:203], v[112:115]
	v_mfma_f32_16x16x32_bf16 v[112:115], v[168:171], v[204:207], v[112:115]
	v_mfma_f32_16x16x32_bf16 v[128:131], v[168:171], v[196:199], v[128:131]
	v_mfma_f32_16x16x32_bf16 v[128:131], v[164:167], v[192:195], v[128:131]
	s_setprio 0
	s_setprio 1
	v_mfma_f32_16x16x32_bf16 v[124:127], v[172:175], v[192:195], v[124:127]
	v_mfma_f32_16x16x32_bf16 v[124:127], v[176:179], v[196:199], v[124:127]
	v_mfma_f32_16x16x32_bf16 v[108:111], v[176:179], v[204:207], v[108:111]
	v_mfma_f32_16x16x32_bf16 v[108:111], v[172:175], v[200:203], v[108:111]
	v_mfma_f32_16x16x32_bf16 v[92:95], v[172:175], v[230:233], v[92:95]
	v_mfma_f32_16x16x32_bf16 v[92:95], v[176:179], v[234:237], v[92:95]
	v_mfma_f32_16x16x32_bf16 v[76:79], v[176:179], v[242:245], v[76:79]
	v_mfma_f32_16x16x32_bf16 v[76:79], v[172:175], v[238:241], v[76:79]
	v_mfma_f32_16x16x32_bf16 v[72:75], v[184:187], v[238:241], v[72:75]
	v_mfma_f32_16x16x32_bf16 v[72:75], v[188:191], v[242:245], v[72:75]
	v_mfma_f32_16x16x32_bf16 v[88:91], v[188:191], v[234:237], v[88:91]
	v_mfma_f32_16x16x32_bf16 v[88:91], v[184:187], v[230:233], v[88:91]
	v_mfma_f32_16x16x32_bf16 v[104:107], v[184:187], v[200:203], v[104:107]
	v_mfma_f32_16x16x32_bf16 v[104:107], v[188:191], v[204:207], v[104:107]
	v_mfma_f32_16x16x32_bf16 v[120:123], v[188:191], v[196:199], v[120:123]
	v_mfma_f32_16x16x32_bf16 v[120:123], v[184:187], v[192:195], v[120:123]
	s_setprio 0
	s_barrier
	s_mov_b32 m0, s81
	v_lshl_add_u64 v[180:181], s[94:95], 0, v[0:1]
	v_lshl_add_u64 v[208:209], s[94:95], 0, v[138:139]
	s_add_u32 s94, s94, s48
	ds_read_b128 v[192:195], v149 offset:16384
	ds_read_b128 v[196:199], v149 offset:17408
	ds_read_b128 v[200:203], v149 offset:18432
	ds_read_b128 v[204:207], v149 offset:19456
	ds_read_b128 v[230:233], v149 offset:20480
	ds_read_b128 v[234:237], v149 offset:21504
	ds_read_b128 v[238:241], v149 offset:22528
	ds_read_b128 v[242:245], v149 offset:23552
	global_load_lds_dwordx4 v[180:181], off
	s_mov_b32 m0, s82
	s_addc_u32 s95, s95, s49
	global_load_lds_dwordx4 v[208:209], off
	v_lshl_add_u64 v[216:217], s[94:95], 0, v[0:1]
	s_mov_b32 m0, s83
	v_lshl_add_u64 v[224:225], s[94:95], 0, v[138:139]
	global_load_lds_dwordx4 v[216:217], off
	s_mov_b32 m0, s84
	v_lshl_add_u64 v[226:227], s[40:41], 0, v[2:3]
	global_load_lds_dwordx4 v[224:225], off
	s_mov_b32 m0, s47
	v_lshl_add_u64 v[228:229], s[40:41], 0, v[136:137]
	global_load_lds_dwordx4 v[226:227], off
	s_mov_b32 m0, s52
	s_nop 0
	global_load_lds_dwordx4 v[228:229], off
	s_waitcnt vmcnt(8)
	s_waitcnt lgkmcnt(0)
	s_barrier
; #define PG8_STAGE(bufoff, gbase, voff) do { _Pragma("unroll") for (int _i = 0; _i < 2; ++_i) \
;         __builtin_amdgcn_global_load_lds((const unsigned*)((const char*)(gbase) + (voff)[_i]), (PG8_LAS unsigned*)(lds + (bufoff) + ldsw + _i * 8192), 16, 0, 0); } while (0)
; #define PG8_LDA(dst, b, h) do { _Pragma("unroll") for (int m = 0; m < 4; ++m) _Pragma("unroll") for (int k = 0; k < 2; ++k) dst[m][k] = *(const PG8_LAS bf16x8*)(lds + PG8_SA(b, h) + aoff + m * 2048 + k * 1024); } while (0)
; #define PG8_LDB(dst, b, h) do { _Pragma("unroll") for (int n = 0; n < 2; ++n) _Pragma("unroll") for (int k = 0; k < 2; ++k) dst[n][k] = *(const PG8_LAS bf16x8*)(lds + PG8_SB(b, h) + boff + n * 2048 + k * 1024); } while (0)
; #define PG8_MMA(ai, bj, At, Bt) do { __builtin_amdgcn_s_setprio(1); _Pragma("unroll") for (int m = 0; m < 4; ++m) _Pragma("unroll") for (int n = 0; n < 2; ++n) _Pragma("unroll") for (int k = 0; k < 2; ++k) \
;         acc[ai][bj][m][n] = __builtin_amdgcn_mfma_f32_16x16x32_bf16(Bt[n][k], At[m][k], acc[ai][bj][m][n], 0, 0, 0); __builtin_amdgcn_s_setprio(0); } while (0)
; #define PG8_WAIT_V(n) asm volatile("s_waitcnt vmcnt(" #n ")" ::: "memory")
; #define PG8_WAIT_L(n) asm volatile("s_waitcnt lgkmcnt(" #n ")" ::: "memory")
; #define PG8_BAR __builtin_amdgcn_s_barrier()
; #define PG8_SCHED __builtin_amdgcn_sched_barrier(0)
; template <class Epi, class Sched, bool ALIGN_EPI = false, bool SP2 = false>
; __device__ __forceinline__ void gemm_phase(PG8_LAS unsigned char* lds, const Gemm g, const Sched& S, const Epi& E) {
;     ...
;             PG8_WAIT_V(8); PG8_WAIT_L(0); PG8_BAR; PG8_MMA(1, 0, At, B0); PG8_MMA(1, 1, At, B1); PG8_BAR; PG8_SCHED;
;             PG8_LDB(B0, 1, 0); PG8_LDB(B1, 1, 1); PG8_SCHED; PG8_LDA(At, 1, 0); PG8_STAGE(PG8_SA(0, 1), a2 + hstep, voffA);
;             PG8_WAIT_V(8); PG8_WAIT_L(0); PG8_BAR; PG8_MMA(0, 0, At, B0); PG8_MMA(0, 1, At, B1); PG8_BAR; PG8_SCHED;
	s_setprio 1
	s_waitcnt lgkmcnt(0)
	v_mfma_f32_16x16x32_bf16 v[68:71], v[156:159], v[192:195], v[68:71]
	v_mfma_f32_16x16x32_bf16 v[68:71], v[160:163], v[196:199], v[68:71]
	v_mfma_f32_16x16x32_bf16 v[52:55], v[160:163], v[204:207], v[52:55]
	v_mfma_f32_16x16x32_bf16 v[52:55], v[156:159], v[200:203], v[52:55]
	v_mfma_f32_16x16x32_bf16 v[36:39], v[156:159], v[230:233], v[36:39]
	v_mfma_f32_16x16x32_bf16 v[36:39], v[160:163], v[234:237], v[36:39]
	v_mfma_f32_16x16x32_bf16 v[20:23], v[160:163], v[242:245], v[20:23]
	v_mfma_f32_16x16x32_bf16 v[20:23], v[156:159], v[238:241], v[20:23]
	v_mfma_f32_16x16x32_bf16 v[16:19], v[164:167], v[238:241], v[16:19]
	v_mfma_f32_16x16x32_bf16 v[16:19], v[168:171], v[242:245], v[16:19]
	v_mfma_f32_16x16x32_bf16 v[32:35], v[168:171], v[234:237], v[32:35]
	v_mfma_f32_16x16x32_bf16 v[32:35], v[164:167], v[230:233], v[32:35]
	v_mfma_f32_16x16x32_bf16 v[48:51], v[164:167], v[200:203], v[48:51]
	v_mfma_f32_16x16x32_bf16 v[48:51], v[168:171], v[204:207], v[48:51]
	v_mfma_f32_16x16x32_bf16 v[64:67], v[168:171], v[196:199], v[64:67]
	v_mfma_f32_16x16x32_bf16 v[64:67], v[164:167], v[192:195], v[64:67]
	s_setprio 0
	s_setprio 1
	v_mfma_f32_16x16x32_bf16 v[60:63], v[172:175], v[192:195], v[60:63]
	v_mfma_f32_16x16x32_bf16 v[60:63], v[176:179], v[196:199], v[60:63]
	v_mfma_f32_16x16x32_bf16 v[44:47], v[176:179], v[204:207], v[44:47]
	v_mfma_f32_16x16x32_bf16 v[44:47], v[172:175], v[200:203], v[44:47]
	v_mfma_f32_16x16x32_bf16 v[28:31], v[172:175], v[230:233], v[28:31]
	v_mfma_f32_16x16x32_bf16 v[28:31], v[176:179], v[234:237], v[28:31]
	v_mfma_f32_16x16x32_bf16 v[12:15], v[176:179], v[242:245], v[12:15]
	v_mfma_f32_16x16x32_bf16 v[12:15], v[172:175], v[238:241], v[12:15]
	v_mfma_f32_16x16x32_bf16 v[8:11], v[184:187], v[238:241], v[8:11]
	v_mfma_f32_16x16x32_bf16 v[8:11], v[188:191], v[242:245], v[8:11]
	v_mfma_f32_16x16x32_bf16 v[24:27], v[188:191], v[234:237], v[24:27]
	v_mfma_f32_16x16x32_bf16 v[24:27], v[184:187], v[230:233], v[24:27]
	v_mfma_f32_16x16x32_bf16 v[40:43], v[184:187], v[200:203], v[40:43]
	v_mfma_f32_16x16x32_bf16 v[40:43], v[188:191], v[204:207], v[40:43]
	v_mfma_f32_16x16x32_bf16 v[56:59], v[188:191], v[196:199], v[56:59]
	v_mfma_f32_16x16x32_bf16 v[56:59], v[184:187], v[192:195], v[56:59]
	s_setprio 0
	s_barrier
	ds_read_b128 v[156:159], v152
	ds_read_b128 v[160:163], v152 offset:1024
	ds_read_b128 v[164:167], v152 offset:2048
	ds_read_b128 v[168:171], v152 offset:3072
	ds_read_b128 v[172:175], v153
	ds_read_b128 v[176:179], v153 offset:1024
	ds_read_b128 v[184:187], v153 offset:2048
	ds_read_b128 v[188:191], v153 offset:3072
	s_add_u32 s40, s40, s48
	s_addc_u32 s41, s41, s49
	s_mov_b32 m0, s53
	v_lshl_add_u64 v[246:247], s[40:41], 0, v[2:3]
	ds_read_b128 v[192:195], v149 offset:32768
	ds_read_b128 v[196:199], v149 offset:33792
	ds_read_b128 v[200:203], v149 offset:34816
	ds_read_b128 v[204:207], v149 offset:35840
	ds_read_b128 v[230:233], v149 offset:36864
	ds_read_b128 v[234:237], v149 offset:37888
	ds_read_b128 v[238:241], v149 offset:38912
	ds_read_b128 v[242:245], v149 offset:39936
	global_load_lds_dwordx4 v[246:247], off
	v_lshl_add_u64 v[246:247], s[40:41], 0, v[136:137]
	s_mov_b32 m0, s72
	s_nop 0
	global_load_lds_dwordx4 v[246:247], off
	s_waitcnt vmcnt(8)
	s_waitcnt lgkmcnt(0)
	s_barrier
	s_setprio 1
	s_waitcnt lgkmcnt(0)
	v_mfma_f32_16x16x32_bf16 v[132:135], v[156:159], v[192:195], v[132:135]
	v_mfma_f32_16x16x32_bf16 v[132:135], v[160:163], v[196:199], v[132:135]
	v_mfma_f32_16x16x32_bf16 v[116:119], v[160:163], v[204:207], v[116:119]
	v_mfma_f32_16x16x32_bf16 v[116:119], v[156:159], v[200:203], v[116:119]
	v_mfma_f32_16x16x32_bf16 v[100:103], v[156:159], v[230:233], v[100:103]
	v_mfma_f32_16x16x32_bf16 v[100:103], v[160:163], v[234:237], v[100:103]
	v_mfma_f32_16x16x32_bf16 v[84:87], v[160:163], v[242:245], v[84:87]
	v_mfma_f32_16x16x32_bf16 v[84:87], v[156:159], v[238:241], v[84:87]
	v_mfma_f32_16x16x32_bf16 v[80:83], v[164:167], v[238:241], v[80:83]
	v_mfma_f32_16x16x32_bf16 v[80:83], v[168:171], v[242:245], v[80:83]
	v_mfma_f32_16x16x32_bf16 v[96:99], v[168:171], v[234:237], v[96:99]
	v_mfma_f32_16x16x32_bf16 v[96:99], v[164:167], v[230:233], v[96:99]
	v_mfma_f32_16x16x32_bf16 v[112:115], v[164:167], v[200:203], v[112:115]
	v_mfma_f32_16x16x32_bf16 v[112:115], v[168:171], v[204:207], v[112:115]
	v_mfma_f32_16x16x32_bf16 v[128:131], v[168:171], v[196:199], v[128:131]
	v_mfma_f32_16x16x32_bf16 v[128:131], v[164:167], v[192:195], v[128:131]
	s_setprio 0
	s_setprio 1
	v_mfma_f32_16x16x32_bf16 v[124:127], v[172:175], v[192:195], v[124:127]
	v_mfma_f32_16x16x32_bf16 v[124:127], v[176:179], v[196:199], v[124:127]
	v_mfma_f32_16x16x32_bf16 v[108:111], v[176:179], v[204:207], v[108:111]
	v_mfma_f32_16x16x32_bf16 v[108:111], v[172:175], v[200:203], v[108:111]
	v_mfma_f32_16x16x32_bf16 v[92:95], v[172:175], v[230:233], v[92:95]
	v_mfma_f32_16x16x32_bf16 v[92:95], v[176:179], v[234:237], v[92:95]
	v_mfma_f32_16x16x32_bf16 v[76:79], v[176:179], v[242:245], v[76:79]
	v_mfma_f32_16x16x32_bf16 v[76:79], v[172:175], v[238:241], v[76:79]
	v_mfma_f32_16x16x32_bf16 v[72:75], v[184:187], v[238:241], v[72:75]
	v_mfma_f32_16x16x32_bf16 v[72:75], v[188:191], v[242:245], v[72:75]
	v_mfma_f32_16x16x32_bf16 v[88:91], v[188:191], v[234:237], v[88:91]
	v_mfma_f32_16x16x32_bf16 v[88:91], v[184:187], v[230:233], v[88:91]
	v_mfma_f32_16x16x32_bf16 v[104:107], v[184:187], v[200:203], v[104:107]
	v_mfma_f32_16x16x32_bf16 v[104:107], v[188:191], v[204:207], v[104:107]
	v_mfma_f32_16x16x32_bf16 v[120:123], v[188:191], v[196:199], v[120:123]
	v_mfma_f32_16x16x32_bf16 v[120:123], v[184:187], v[192:195], v[120:123]
	s_setprio 0
	s_barrier
; #define PG8_STAGE(bufoff, gbase, voff) do { _Pragma("unroll") for (int _i = 0; _i < 2; ++_i) \
;         __builtin_amdgcn_global_load_lds((const unsigned*)((const char*)(gbase) + (voff)[_i]), (PG8_LAS unsigned*)(lds + (bufoff) + ldsw + _i * 8192), 16, 0, 0); } while (0)
; #define PG8_LDA(dst, b, h) do { _Pragma("unroll") for (int m = 0; m < 4; ++m) _Pragma("unroll") for (int k = 0; k < 2; ++k) dst[m][k] = *(const PG8_LAS bf16x8*)(lds + PG8_SA(b, h) + aoff + m * 2048 + k * 1024); } while (0)
; #define PG8_MMA(ai, bj, At, Bt) do { __builtin_amdgcn_s_setprio(1); _Pragma("unroll") for (int m = 0; m < 4; ++m) _Pragma("unroll") for (int n = 0; n < 2; ++n) _Pragma("unroll") for (int k = 0; k < 2; ++k) \
;         acc[ai][bj][m][n] = __builtin_amdgcn_mfma_f32_16x16x32_bf16(Bt[n][k], At[m][k], acc[ai][bj][m][n], 0, 0, 0); __builtin_amdgcn_s_setprio(0); } while (0)
; #define PG8_WAIT_V(n) asm volatile("s_waitcnt vmcnt(" #n ")" ::: "memory")
; #define PG8_WAIT_L(n) asm volatile("s_waitcnt lgkmcnt(" #n ")" ::: "memory")
; #define PG8_BAR __builtin_amdgcn_s_barrier()
; #define PG8_SCHED __builtin_amdgcn_sched_barrier(0)
; template <class Epi, class Sched, bool ALIGN_EPI = false, bool SP2 = false>
; __device__ __forceinline__ void gemm_phase(PG8_LAS unsigned char* lds, const Gemm g, const Sched& S, const Epi& E) {
;     ...
;         for (int t = 0; t < nt; t += 2) {
;     ...
;             PG8_LDA(At, 1, 1); PG8_STAGE(PG8_SB(1, 0), b3, voffB); PG8_STAGE(PG8_SB(1, 1), b3 + hstep, voffB); PG8_STAGE(PG8_SA(1, 0), a3, voffA);
;             PG8_WAIT_V(8); PG8_WAIT_L(0); PG8_BAR; PG8_MMA(1, 0, At, B0); PG8_MMA(1, 1, At, B1); PG8_BAR; PG8_SCHED;
	s_mov_b32 m0, s85
	v_lshl_add_u64 v[180:181], v[180:181], 0, s[24:25]
	ds_read_b128 v[192:195], v149 offset:49152
	ds_read_b128 v[196:199], v149 offset:50176
	ds_read_b128 v[200:203], v149 offset:51200
	ds_read_b128 v[204:207], v149 offset:52224
	ds_read_b128 v[230:233], v149 offset:53248
	ds_read_b128 v[234:237], v149 offset:54272
	ds_read_b128 v[238:241], v149 offset:55296
	ds_read_b128 v[242:245], v149 offset:56320
	global_load_lds_dwordx4 v[180:181], off
	v_lshl_add_u64 v[180:181], v[208:209], 0, s[24:25]
	s_mov_b32 m0, s86
	s_nop 0
	global_load_lds_dwordx4 v[180:181], off
	v_lshl_add_u64 v[180:181], v[216:217], 0, s[24:25]
	s_mov_b32 m0, s87
	s_nop 0
	global_load_lds_dwordx4 v[180:181], off
	v_lshl_add_u64 v[180:181], v[224:225], 0, s[24:25]
	s_mov_b32 m0, s88
	s_nop 0
	global_load_lds_dwordx4 v[180:181], off
	v_lshl_add_u64 v[180:181], v[226:227], 0, s[24:25]
	s_mov_b32 m0, s75
	s_nop 0
	global_load_lds_dwordx4 v[180:181], off
	v_lshl_add_u64 v[180:181], v[228:229], 0, s[24:25]
	s_mov_b32 m0, s76
	s_nop 0
	global_load_lds_dwordx4 v[180:181], off
	s_waitcnt vmcnt(8)
	s_waitcnt lgkmcnt(0)
	s_barrier
	s_setprio 1
	s_waitcnt lgkmcnt(0)
	v_mfma_f32_16x16x32_bf16 v[68:71], v[156:159], v[192:195], v[68:71]
	v_mfma_f32_16x16x32_bf16 v[68:71], v[160:163], v[196:199], v[68:71]
	v_mfma_f32_16x16x32_bf16 v[52:55], v[160:163], v[204:207], v[52:55]
	v_mfma_f32_16x16x32_bf16 v[52:55], v[156:159], v[200:203], v[52:55]
	v_mfma_f32_16x16x32_bf16 v[36:39], v[156:159], v[230:233], v[36:39]
	v_mfma_f32_16x16x32_bf16 v[36:39], v[160:163], v[234:237], v[36:39]
	v_mfma_f32_16x16x32_bf16 v[20:23], v[160:163], v[242:245], v[20:23]
	v_mfma_f32_16x16x32_bf16 v[20:23], v[156:159], v[238:241], v[20:23]
	v_mfma_f32_16x16x32_bf16 v[16:19], v[164:167], v[238:241], v[16:19]
	v_mfma_f32_16x16x32_bf16 v[16:19], v[168:171], v[242:245], v[16:19]
	v_mfma_f32_16x16x32_bf16 v[32:35], v[168:171], v[234:237], v[32:35]
	v_mfma_f32_16x16x32_bf16 v[32:35], v[164:167], v[230:233], v[32:35]
	v_mfma_f32_16x16x32_bf16 v[48:51], v[164:167], v[200:203], v[48:51]
	v_mfma_f32_16x16x32_bf16 v[48:51], v[168:171], v[204:207], v[48:51]
	v_mfma_f32_16x16x32_bf16 v[64:67], v[168:171], v[196:199], v[64:67]
	v_mfma_f32_16x16x32_bf16 v[64:67], v[164:167], v[192:195], v[64:67]
	s_setprio 0
	s_setprio 1
	v_mfma_f32_16x16x32_bf16 v[60:63], v[172:175], v[192:195], v[60:63]
	v_mfma_f32_16x16x32_bf16 v[60:63], v[176:179], v[196:199], v[60:63]
	v_mfma_f32_16x16x32_bf16 v[44:47], v[176:179], v[204:207], v[44:47]
	v_mfma_f32_16x16x32_bf16 v[44:47], v[172:175], v[200:203], v[44:47]
	v_mfma_f32_16x16x32_bf16 v[28:31], v[172:175], v[230:233], v[28:31]
	v_mfma_f32_16x16x32_bf16 v[28:31], v[176:179], v[234:237], v[28:31]
	v_mfma_f32_16x16x32_bf16 v[12:15], v[176:179], v[242:245], v[12:15]
	v_mfma_f32_16x16x32_bf16 v[12:15], v[172:175], v[238:241], v[12:15]
	v_mfma_f32_16x16x32_bf16 v[8:11], v[184:187], v[238:241], v[8:11]
	v_mfma_f32_16x16x32_bf16 v[8:11], v[188:191], v[242:245], v[8:11]
	v_mfma_f32_16x16x32_bf16 v[24:27], v[188:191], v[234:237], v[24:27]
	v_mfma_f32_16x16x32_bf16 v[24:27], v[184:187], v[230:233], v[24:27]
	v_mfma_f32_16x16x32_bf16 v[40:43], v[184:187], v[200:203], v[40:43]
	v_mfma_f32_16x16x32_bf16 v[40:43], v[188:191], v[204:207], v[40:43]
	v_mfma_f32_16x16x32_bf16 v[56:59], v[188:191], v[196:199], v[56:59]
	v_mfma_f32_16x16x32_bf16 v[56:59], v[184:187], v[192:195], v[56:59]
	s_setprio 0
	s_barrier
	s_add_i32 s40, s93, 2
	s_add_u32 s22, s22, 0x100
	s_addc_u32 s23, s23, 0
	s_add_u32 s89, s89, 0x100
	s_addc_u32 s92, s92, 0
	s_cmp_ge_u32 s93, s9
	v_add_u32_e32 v154, 0x100, v154
	s_cbranch_scc0 .LBB0_248

; #define PG8_STAGE(bufoff, gbase, voff) do { _Pragma("unroll") for (int _i = 0; _i < 2; ++_i) \
;         __builtin_amdgcn_global_load_lds((const unsigned*)((const char*)(gbase) + (voff)[_i]), (PG8_LAS unsigned*)(lds + (bufoff) + ldsw + _i * 8192), 16, 0, 0); } while (0)
; #define PG8_LDA(dst, b, h) do { _Pragma("unroll") for (int m = 0; m < 4; ++m) _Pragma("unroll") for (int k = 0; k < 2; ++k) dst[m][k] = *(const PG8_LAS bf16x8*)(lds + PG8_SA(b, h) + aoff + m * 2048 + k * 1024); } while (0)
; #define PG8_LDB(dst, b, h) do { _Pragma("unroll") for (int n = 0; n < 2; ++n) _Pragma("unroll") for (int k = 0; k < 2; ++k) dst[n][k] = *(const PG8_LAS bf16x8*)(lds + PG8_SB(b, h) + boff + n * 2048 + k * 1024); } while (0)
; #define PG8_MMA(ai, bj, At, Bt) do { __builtin_amdgcn_s_setprio(1); _Pragma("unroll") for (int m = 0; m < 4; ++m) _Pragma("unroll") for (int n = 0; n < 2; ++n) _Pragma("unroll") for (int k = 0; k < 2; ++k) \
;         acc[ai][bj][m][n] = __builtin_amdgcn_mfma_f32_16x16x32_bf16(Bt[n][k], At[m][k], acc[ai][bj][m][n], 0, 0, 0); __builtin_amdgcn_s_setprio(0); } while (0)
; #define PG8_WAIT_V(n) asm volatile("s_waitcnt vmcnt(" #n ")" ::: "memory")
; #define PG8_WAIT_L(n) asm volatile("s_waitcnt lgkmcnt(" #n ")" ::: "memory")
; template <class Epi, class Sched, bool ALIGN_EPI = false, bool SP2 = false>
; __device__ __forceinline__ void gemm_phase(PG8_LAS unsigned char* lds, const Gemm g, const Sched& S, const Epi& E) {
;     ...
;             const bool last = (t == nt - 2);
;             const char* a1 = cA + (size_t)(t + 1) * kstep;
;             const char* a2 = last ? nA : cA + (size_t)(t + 2) * kstep; const char* b2 = last ? nB : cB + (size_t)(t + 2) * kstep;
;             const char* a3 = a2 + kstep; const char* b3 = b2 + kstep;
;             if (last && has_next) S.a_ready(nxt);
;             if constexpr (SP2) {
;             PG8_LDB(B0, 0, 0); PG8_LDB(B1, 0, 1); PG8_SCHED; PG8_LDA(At, 0, 0); PG8_STAGE(PG8_SA(1, 1), a1 + hstep, voffA);
;             PG8_WAIT_V(8); PG8_WAIT_L(0); PG8_BAR; PG8_MMA(0, 0, At, B0); PG8_MMA(0, 1, At, B1); PG8_BAR; PG8_SCHED;
;             PG8_LDA(At, 0, 1); PG8_STAGE(PG8_SB(0, 0), b2, voffB); PG8_STAGE(PG8_SB(0, 1), b2 + hstep, voffB); PG8_STAGE(PG8_SA(0, 0), a2, voffA);
;             PG8_WAIT_V(8); PG8_WAIT_L(0); PG8_BAR; PG8_MMA(1, 0, At, B0); PG8_MMA(1, 1, At, B1); PG8_BAR; PG8_SCHED;
.LBB0_294:
	s_add_i32 s81, s40, 2
	s_add_u32 s82, s38, 0x80
	s_addc_u32 s41, s39, 0
	s_cmp_eq_u32 s33, s40
	s_cselect_b32 s41, s7, s41
	s_cselect_b32 s40, s6, s82
	v_add_u32_e32 v0, s19, v151
	s_cselect_b32 s83, s23, s80
	s_cselect_b32 s82, s22, s79
	s_add_i32 s84, 0, 0x14000
	ds_read_b128 v[154:157], v0
	ds_read_b128 v[158:161], v0 offset:1024
	ds_read_b128 v[162:165], v0 offset:2048
	ds_read_b128 v[166:169], v0 offset:3072
	v_add_u32_e32 v0, s84, v151
	ds_read_b128 v[170:173], v0
	ds_read_b128 v[174:177], v0 offset:1024
	ds_read_b128 v[178:181], v0 offset:2048
	ds_read_b128 v[184:187], v0 offset:3072
	v_lshl_add_u64 v[2:3], s[38:39], 0, v[144:145]
	s_add_i32 m0, s46, 0xc000
	ds_read_b128 v[188:191], v152
	ds_read_b128 v[192:195], v152 offset:1024
	ds_read_b128 v[196:199], v152 offset:2048
	ds_read_b128 v[200:203], v152 offset:3072
	ds_read_b128 v[204:207], v152 offset:4096
	ds_read_b128 v[230:233], v152 offset:5120
	ds_read_b128 v[234:237], v152 offset:6144
	ds_read_b128 v[238:241], v152 offset:7168
	global_load_lds_dwordx4 v[2:3], off
	v_lshl_add_u64 v[2:3], s[38:39], 0, v[146:147]
	s_add_i32 m0, s46, 0xe000
	s_nop 0
	global_load_lds_dwordx4 v[2:3], off
	s_waitcnt vmcnt(8)
	s_waitcnt lgkmcnt(0)
	s_barrier
	s_setprio 1
	s_waitcnt lgkmcnt(0)
	v_mfma_f32_16x16x32_bf16 v[8:11], v[154:157], v[188:191], v[8:11]
	v_mfma_f32_16x16x32_bf16 v[8:11], v[158:161], v[192:195], v[8:11]
	v_mfma_f32_16x16x32_bf16 v[48:51], v[158:161], v[200:203], v[48:51]
	v_mfma_f32_16x16x32_bf16 v[48:51], v[154:157], v[196:199], v[48:51]
	v_mfma_f32_16x16x32_bf16 v[96:99], v[154:157], v[204:207], v[96:99]
	v_mfma_f32_16x16x32_bf16 v[96:99], v[158:161], v[230:233], v[96:99]
	v_mfma_f32_16x16x32_bf16 v[120:123], v[158:161], v[238:241], v[120:123]
	v_mfma_f32_16x16x32_bf16 v[120:123], v[154:157], v[234:237], v[120:123]
	v_mfma_f32_16x16x32_bf16 v[124:127], v[162:165], v[234:237], v[124:127]
	v_mfma_f32_16x16x32_bf16 v[124:127], v[166:169], v[238:241], v[124:127]
	v_mfma_f32_16x16x32_bf16 v[100:103], v[166:169], v[230:233], v[100:103]
	v_mfma_f32_16x16x32_bf16 v[100:103], v[162:165], v[204:207], v[100:103]
	v_mfma_f32_16x16x32_bf16 v[52:55], v[162:165], v[196:199], v[52:55]
	v_mfma_f32_16x16x32_bf16 v[52:55], v[166:169], v[200:203], v[52:55]
	v_mfma_f32_16x16x32_bf16 v[12:15], v[166:169], v[192:195], v[12:15]
	v_mfma_f32_16x16x32_bf16 v[12:15], v[162:165], v[188:191], v[12:15]
	s_setprio 0
	s_setprio 1
	v_mfma_f32_16x16x32_bf16 v[24:27], v[170:173], v[188:191], v[24:27]
	v_mfma_f32_16x16x32_bf16 v[24:27], v[174:177], v[192:195], v[24:27]
	v_mfma_f32_16x16x32_bf16 v[72:75], v[174:177], v[200:203], v[72:75]
	v_mfma_f32_16x16x32_bf16 v[72:75], v[170:173], v[196:199], v[72:75]
	v_mfma_f32_16x16x32_bf16 v[112:115], v[170:173], v[204:207], v[112:115]
	v_mfma_f32_16x16x32_bf16 v[112:115], v[174:177], v[230:233], v[112:115]
	v_mfma_f32_16x16x32_bf16 v[128:131], v[174:177], v[238:241], v[128:131]
	v_mfma_f32_16x16x32_bf16 v[128:131], v[170:173], v[234:237], v[128:131]
	v_mfma_f32_16x16x32_bf16 v[132:135], v[178:181], v[234:237], v[132:135]
	v_mfma_f32_16x16x32_bf16 v[132:135], v[184:187], v[238:241], v[132:135]
	v_mfma_f32_16x16x32_bf16 v[116:119], v[184:187], v[230:233], v[116:119]
	v_mfma_f32_16x16x32_bf16 v[116:119], v[178:181], v[204:207], v[116:119]
	v_mfma_f32_16x16x32_bf16 v[76:79], v[178:181], v[196:199], v[76:79]
	v_mfma_f32_16x16x32_bf16 v[76:79], v[184:187], v[200:203], v[76:79]
	v_mfma_f32_16x16x32_bf16 v[28:31], v[184:187], v[192:195], v[28:31]
	v_mfma_f32_16x16x32_bf16 v[28:31], v[178:181], v[188:191], v[28:31]
	s_setprio 0
	s_barrier
	s_add_i32 s85, s19, s37
	v_lshl_add_u64 v[2:3], s[82:83], 0, v[140:141]
	s_mov_b32 m0, s85
	ds_read_b128 v[188:191], v152 offset:16384
	ds_read_b128 v[192:195], v152 offset:17408
	ds_read_b128 v[196:199], v152 offset:18432
	ds_read_b128 v[200:203], v152 offset:19456
	ds_read_b128 v[204:207], v152 offset:20480
	ds_read_b128 v[230:233], v152 offset:21504
	ds_read_b128 v[234:237], v152 offset:22528
	ds_read_b128 v[238:241], v152 offset:23552
	global_load_lds_dwordx4 v[2:3], off
	s_add_i32 m0, s85, 0x2000
	v_lshl_add_u64 v[208:209], s[82:83], 0, v[136:137]
	s_add_u32 s82, s82, s48
	s_addc_u32 s83, s83, s49
	s_add_i32 s84, s84, s37
	global_load_lds_dwordx4 v[208:209], off
	v_lshl_add_u64 v[216:217], s[82:83], 0, v[140:141]
	s_mov_b32 m0, s84
	v_lshl_add_u64 v[224:225], s[82:83], 0, v[136:137]
	global_load_lds_dwordx4 v[216:217], off
	s_add_i32 m0, s84, 0x2000
	v_lshl_add_u64 v[226:227], s[40:41], 0, v[142:143]
	global_load_lds_dwordx4 v[224:225], off
	s_mov_b32 m0, s46
	v_lshl_add_u64 v[228:229], s[40:41], 0, v[138:139]
	global_load_lds_dwordx4 v[226:227], off
	s_mov_b32 m0, s47
	s_nop 0
	global_load_lds_dwordx4 v[228:229], off
	s_waitcnt vmcnt(8)
	s_waitcnt lgkmcnt(0)
	s_barrier
; #define PG8_STAGE(bufoff, gbase, voff) do { _Pragma("unroll") for (int _i = 0; _i < 2; ++_i) \
;         __builtin_amdgcn_global_load_lds((const unsigned*)((const char*)(gbase) + (voff)[_i]), (PG8_LAS unsigned*)(lds + (bufoff) + ldsw + _i * 8192), 16, 0, 0); } while (0)
; #define PG8_LDA(dst, b, h) do { _Pragma("unroll") for (int m = 0; m < 4; ++m) _Pragma("unroll") for (int k = 0; k < 2; ++k) dst[m][k] = *(const PG8_LAS bf16x8*)(lds + PG8_SA(b, h) + aoff + m * 2048 + k * 1024); } while (0)
; #define PG8_LDB(dst, b, h) do { _Pragma("unroll") for (int n = 0; n < 2; ++n) _Pragma("unroll") for (int k = 0; k < 2; ++k) dst[n][k] = *(const PG8_LAS bf16x8*)(lds + PG8_SB(b, h) + boff + n * 2048 + k * 1024); } while (0)
; #define PG8_MMA(ai, bj, At, Bt) do { __builtin_amdgcn_s_setprio(1); _Pragma("unroll") for (int m = 0; m < 4; ++m) _Pragma("unroll") for (int n = 0; n < 2; ++n) _Pragma("unroll") for (int k = 0; k < 2; ++k) \
;         acc[ai][bj][m][n] = __builtin_amdgcn_mfma_f32_16x16x32_bf16(Bt[n][k], At[m][k], acc[ai][bj][m][n], 0, 0, 0); __builtin_amdgcn_s_setprio(0); } while (0)
; #define PG8_WAIT_V(n) asm volatile("s_waitcnt vmcnt(" #n ")" ::: "memory")
; #define PG8_WAIT_L(n) asm volatile("s_waitcnt lgkmcnt(" #n ")" ::: "memory")
; #define PG8_BAR __builtin_amdgcn_s_barrier()
; #define PG8_SCHED __builtin_amdgcn_sched_barrier(0)
; template <class Epi, class Sched, bool ALIGN_EPI = false, bool SP2 = false>
; __device__ __forceinline__ void gemm_phase(PG8_LAS unsigned char* lds, const Gemm g, const Sched& S, const Epi& E) {
;     ...
;             PG8_WAIT_V(8); PG8_WAIT_L(0); PG8_BAR; PG8_MMA(1, 0, At, B0); PG8_MMA(1, 1, At, B1); PG8_BAR; PG8_SCHED;
;             PG8_LDB(B0, 1, 0); PG8_LDB(B1, 1, 1); PG8_SCHED; PG8_LDA(At, 1, 0); PG8_STAGE(PG8_SA(0, 1), a2 + hstep, voffA);
;             PG8_WAIT_V(8); PG8_WAIT_L(0); PG8_BAR; PG8_MMA(0, 0, At, B0); PG8_MMA(0, 1, At, B1); PG8_BAR; PG8_SCHED;
	s_setprio 1
	s_waitcnt lgkmcnt(0)
	v_mfma_f32_16x16x32_bf16 v[16:19], v[154:157], v[188:191], v[16:19]
	v_mfma_f32_16x16x32_bf16 v[16:19], v[158:161], v[192:195], v[16:19]
	v_mfma_f32_16x16x32_bf16 v[56:59], v[158:161], v[200:203], v[56:59]
	v_mfma_f32_16x16x32_bf16 v[56:59], v[154:157], v[196:199], v[56:59]
	v_mfma_f32_16x16x32_bf16 v[104:107], v[154:157], v[204:207], v[104:107]
	v_mfma_f32_16x16x32_bf16 v[104:107], v[158:161], v[230:233], v[104:107]
	v_mfma_f32_16x16x32_bf16 v[68:71], v[158:161], v[238:241], v[68:71]
	v_mfma_f32_16x16x32_bf16 v[68:71], v[154:157], v[234:237], v[68:71]
	v_mfma_f32_16x16x32_bf16 v[64:67], v[162:165], v[234:237], v[64:67]
	v_mfma_f32_16x16x32_bf16 v[64:67], v[166:169], v[238:241], v[64:67]
	v_mfma_f32_16x16x32_bf16 v[108:111], v[166:169], v[230:233], v[108:111]
	v_mfma_f32_16x16x32_bf16 v[108:111], v[162:165], v[204:207], v[108:111]
	v_mfma_f32_16x16x32_bf16 v[60:63], v[162:165], v[196:199], v[60:63]
	v_mfma_f32_16x16x32_bf16 v[60:63], v[166:169], v[200:203], v[60:63]
	v_mfma_f32_16x16x32_bf16 v[20:23], v[166:169], v[192:195], v[20:23]
	v_mfma_f32_16x16x32_bf16 v[20:23], v[162:165], v[188:191], v[20:23]
	s_setprio 0
	s_setprio 1
	v_mfma_f32_16x16x32_bf16 v[40:43], v[170:173], v[188:191], v[40:43]
	v_mfma_f32_16x16x32_bf16 v[40:43], v[174:177], v[192:195], v[40:43]
	v_mfma_f32_16x16x32_bf16 v[88:91], v[174:177], v[200:203], v[88:91]
	v_mfma_f32_16x16x32_bf16 v[88:91], v[170:173], v[196:199], v[88:91]
	v_mfma_f32_16x16x32_bf16 v[84:87], v[170:173], v[204:207], v[84:87]
	v_mfma_f32_16x16x32_bf16 v[84:87], v[174:177], v[230:233], v[84:87]
	v_mfma_f32_16x16x32_bf16 v[36:39], v[174:177], v[238:241], v[36:39]
	v_mfma_f32_16x16x32_bf16 v[36:39], v[170:173], v[234:237], v[36:39]
	v_mfma_f32_16x16x32_bf16 v[32:35], v[178:181], v[234:237], v[32:35]
	v_mfma_f32_16x16x32_bf16 v[32:35], v[184:187], v[238:241], v[32:35]
	v_mfma_f32_16x16x32_bf16 v[80:83], v[184:187], v[230:233], v[80:83]
	v_mfma_f32_16x16x32_bf16 v[80:83], v[178:181], v[204:207], v[80:83]
	v_mfma_f32_16x16x32_bf16 v[92:95], v[178:181], v[196:199], v[92:95]
	v_mfma_f32_16x16x32_bf16 v[92:95], v[184:187], v[200:203], v[92:95]
	v_mfma_f32_16x16x32_bf16 v[44:47], v[184:187], v[192:195], v[44:47]
	v_mfma_f32_16x16x32_bf16 v[44:47], v[178:181], v[188:191], v[44:47]
	s_setprio 0
	s_barrier
	v_add_u32_e32 v0, s91, v151
	s_add_i32 s82, 0, 0x1c000
	ds_read_b128 v[154:157], v0
	ds_read_b128 v[158:161], v0 offset:1024
	ds_read_b128 v[162:165], v0 offset:2048
	ds_read_b128 v[166:169], v0 offset:3072
	v_add_u32_e32 v0, s82, v151
	ds_read_b128 v[170:173], v0
	ds_read_b128 v[174:177], v0 offset:1024
	ds_read_b128 v[178:181], v0 offset:2048
	ds_read_b128 v[184:187], v0 offset:3072
	s_add_u32 s40, s40, s48
	s_addc_u32 s41, s41, s49
	s_mov_b32 m0, s52
	v_lshl_add_u64 v[242:243], s[40:41], 0, v[142:143]
	ds_read_b128 v[188:191], v152 offset:32768
	ds_read_b128 v[192:195], v152 offset:33792
	ds_read_b128 v[196:199], v152 offset:34816
	ds_read_b128 v[200:203], v152 offset:35840
	ds_read_b128 v[204:207], v152 offset:36864
	ds_read_b128 v[230:233], v152 offset:37888
	ds_read_b128 v[234:237], v152 offset:38912
	ds_read_b128 v[238:241], v152 offset:39936
	global_load_lds_dwordx4 v[242:243], off
	v_lshl_add_u64 v[242:243], s[40:41], 0, v[138:139]
	s_mov_b32 m0, s53
	s_nop 0
	global_load_lds_dwordx4 v[242:243], off
	s_waitcnt vmcnt(8)
	s_waitcnt lgkmcnt(0)
	s_barrier
	s_setprio 1
	s_waitcnt lgkmcnt(0)
	v_mfma_f32_16x16x32_bf16 v[8:11], v[154:157], v[188:191], v[8:11]
	v_mfma_f32_16x16x32_bf16 v[8:11], v[158:161], v[192:195], v[8:11]
	v_mfma_f32_16x16x32_bf16 v[48:51], v[158:161], v[200:203], v[48:51]
	v_mfma_f32_16x16x32_bf16 v[48:51], v[154:157], v[196:199], v[48:51]
	v_mfma_f32_16x16x32_bf16 v[96:99], v[154:157], v[204:207], v[96:99]
	v_mfma_f32_16x16x32_bf16 v[96:99], v[158:161], v[230:233], v[96:99]
	v_mfma_f32_16x16x32_bf16 v[120:123], v[158:161], v[238:241], v[120:123]
	v_mfma_f32_16x16x32_bf16 v[120:123], v[154:157], v[234:237], v[120:123]
	v_mfma_f32_16x16x32_bf16 v[124:127], v[162:165], v[234:237], v[124:127]
	v_mfma_f32_16x16x32_bf16 v[124:127], v[166:169], v[238:241], v[124:127]
	v_mfma_f32_16x16x32_bf16 v[100:103], v[166:169], v[230:233], v[100:103]
	v_mfma_f32_16x16x32_bf16 v[100:103], v[162:165], v[204:207], v[100:103]
	v_mfma_f32_16x16x32_bf16 v[52:55], v[162:165], v[196:199], v[52:55]
	v_mfma_f32_16x16x32_bf16 v[52:55], v[166:169], v[200:203], v[52:55]
	v_mfma_f32_16x16x32_bf16 v[12:15], v[166:169], v[192:195], v[12:15]
	v_mfma_f32_16x16x32_bf16 v[12:15], v[162:165], v[188:191], v[12:15]
	s_setprio 0
	s_setprio 1
	v_mfma_f32_16x16x32_bf16 v[24:27], v[170:173], v[188:191], v[24:27]
	v_mfma_f32_16x16x32_bf16 v[24:27], v[174:177], v[192:195], v[24:27]
	v_mfma_f32_16x16x32_bf16 v[72:75], v[174:177], v[200:203], v[72:75]
	v_mfma_f32_16x16x32_bf16 v[72:75], v[170:173], v[196:199], v[72:75]
	v_mfma_f32_16x16x32_bf16 v[112:115], v[170:173], v[204:207], v[112:115]
	v_mfma_f32_16x16x32_bf16 v[112:115], v[174:177], v[230:233], v[112:115]
	v_mfma_f32_16x16x32_bf16 v[128:131], v[174:177], v[238:241], v[128:131]
	v_mfma_f32_16x16x32_bf16 v[128:131], v[170:173], v[234:237], v[128:131]
	v_mfma_f32_16x16x32_bf16 v[132:135], v[178:181], v[234:237], v[132:135]
	v_mfma_f32_16x16x32_bf16 v[132:135], v[184:187], v[238:241], v[132:135]
	v_mfma_f32_16x16x32_bf16 v[116:119], v[184:187], v[230:233], v[116:119]
	v_mfma_f32_16x16x32_bf16 v[116:119], v[178:181], v[204:207], v[116:119]
	v_mfma_f32_16x16x32_bf16 v[76:79], v[178:181], v[196:199], v[76:79]
	v_mfma_f32_16x16x32_bf16 v[76:79], v[184:187], v[200:203], v[76:79]
	v_mfma_f32_16x16x32_bf16 v[28:31], v[184:187], v[192:195], v[28:31]
	v_mfma_f32_16x16x32_bf16 v[28:31], v[178:181], v[188:191], v[28:31]
	s_setprio 0
	s_barrier
; #define PG8_STAGE(bufoff, gbase, voff) do { _Pragma("unroll") for (int _i = 0; _i < 2; ++_i) \
;         __builtin_amdgcn_global_load_lds((const unsigned*)((const char*)(gbase) + (voff)[_i]), (PG8_LAS unsigned*)(lds + (bufoff) + ldsw + _i * 8192), 16, 0, 0); } while (0)
; #define PG8_LDA(dst, b, h) do { _Pragma("unroll") for (int m = 0; m < 4; ++m) _Pragma("unroll") for (int k = 0; k < 2; ++k) dst[m][k] = *(const PG8_LAS bf16x8*)(lds + PG8_SA(b, h) + aoff + m * 2048 + k * 1024); } while (0)
; #define PG8_MMA(ai, bj, At, Bt) do { __builtin_amdgcn_s_setprio(1); _Pragma("unroll") for (int m = 0; m < 4; ++m) _Pragma("unroll") for (int n = 0; n < 2; ++n) _Pragma("unroll") for (int k = 0; k < 2; ++k) \
;         acc[ai][bj][m][n] = __builtin_amdgcn_mfma_f32_16x16x32_bf16(Bt[n][k], At[m][k], acc[ai][bj][m][n], 0, 0, 0); __builtin_amdgcn_s_setprio(0); } while (0)
; #define PG8_WAIT_V(n) asm volatile("s_waitcnt vmcnt(" #n ")" ::: "memory")
; #define PG8_WAIT_L(n) asm volatile("s_waitcnt lgkmcnt(" #n ")" ::: "memory")
; #define PG8_BAR __builtin_amdgcn_s_barrier()
; #define PG8_SCHED __builtin_amdgcn_sched_barrier(0)
; template <class Epi, class Sched, bool ALIGN_EPI = false, bool SP2 = false>
; __device__ __forceinline__ void gemm_phase(PG8_LAS unsigned char* lds, const Gemm g, const Sched& S, const Epi& E) {
;     ...
;             PG8_LDA(At, 1, 1); PG8_STAGE(PG8_SB(1, 0), b3, voffB); PG8_STAGE(PG8_SB(1, 1), b3 + hstep, voffB); PG8_STAGE(PG8_SA(1, 0), a3, voffA);
;             PG8_WAIT_V(8); PG8_WAIT_L(0); PG8_BAR; PG8_MMA(1, 0, At, B0); PG8_MMA(1, 1, At, B1); PG8_BAR; PG8_SCHED;
	s_add_i32 s40, s91, s37
	v_lshl_add_u64 v[2:3], v[2:3], 0, s[24:25]
	s_mov_b32 m0, s40
	ds_read_b128 v[188:191], v152 offset:49152
	ds_read_b128 v[192:195], v152 offset:50176
	ds_read_b128 v[196:199], v152 offset:51200
	ds_read_b128 v[200:203], v152 offset:52224
	ds_read_b128 v[204:207], v152 offset:53248
	ds_read_b128 v[230:233], v152 offset:54272
	ds_read_b128 v[234:237], v152 offset:55296
	ds_read_b128 v[238:241], v152 offset:56320
	global_load_lds_dwordx4 v[2:3], off
	v_lshl_add_u64 v[2:3], v[208:209], 0, s[24:25]
	s_add_i32 m0, s40, 0x2000
	s_add_i32 s40, s82, s37
	global_load_lds_dwordx4 v[2:3], off
	v_lshl_add_u64 v[2:3], v[216:217], 0, s[24:25]
	s_mov_b32 m0, s40
	s_nop 0
	global_load_lds_dwordx4 v[2:3], off
	v_lshl_add_u64 v[2:3], v[224:225], 0, s[24:25]
	s_add_i32 m0, s40, 0x2000
	s_nop 0
	global_load_lds_dwordx4 v[2:3], off
	v_lshl_add_u64 v[2:3], v[226:227], 0, s[24:25]
	s_mov_b32 m0, s73
	s_nop 0
	global_load_lds_dwordx4 v[2:3], off
	v_lshl_add_u64 v[2:3], v[228:229], 0, s[24:25]
	s_mov_b32 m0, s74
	s_nop 0
	global_load_lds_dwordx4 v[2:3], off
	s_waitcnt vmcnt(8)
	s_waitcnt lgkmcnt(0)
	s_barrier
	s_setprio 1
	s_waitcnt lgkmcnt(0)
	v_mfma_f32_16x16x32_bf16 v[16:19], v[154:157], v[188:191], v[16:19]
	v_mfma_f32_16x16x32_bf16 v[16:19], v[158:161], v[192:195], v[16:19]
	v_mfma_f32_16x16x32_bf16 v[56:59], v[158:161], v[200:203], v[56:59]
	v_mfma_f32_16x16x32_bf16 v[56:59], v[154:157], v[196:199], v[56:59]
	v_mfma_f32_16x16x32_bf16 v[104:107], v[154:157], v[204:207], v[104:107]
	v_mfma_f32_16x16x32_bf16 v[104:107], v[158:161], v[230:233], v[104:107]
	v_mfma_f32_16x16x32_bf16 v[68:71], v[158:161], v[238:241], v[68:71]
	v_mfma_f32_16x16x32_bf16 v[68:71], v[154:157], v[234:237], v[68:71]
	v_mfma_f32_16x16x32_bf16 v[64:67], v[162:165], v[234:237], v[64:67]
	v_mfma_f32_16x16x32_bf16 v[64:67], v[166:169], v[238:241], v[64:67]
	v_mfma_f32_16x16x32_bf16 v[108:111], v[166:169], v[230:233], v[108:111]
	v_mfma_f32_16x16x32_bf16 v[108:111], v[162:165], v[204:207], v[108:111]
	v_mfma_f32_16x16x32_bf16 v[60:63], v[162:165], v[196:199], v[60:63]
	v_mfma_f32_16x16x32_bf16 v[60:63], v[166:169], v[200:203], v[60:63]
	v_mfma_f32_16x16x32_bf16 v[20:23], v[166:169], v[192:195], v[20:23]
	v_mfma_f32_16x16x32_bf16 v[20:23], v[162:165], v[188:191], v[20:23]
	s_setprio 0
	s_setprio 1
	v_mfma_f32_16x16x32_bf16 v[40:43], v[170:173], v[188:191], v[40:43]
	v_mfma_f32_16x16x32_bf16 v[40:43], v[174:177], v[192:195], v[40:43]
	v_mfma_f32_16x16x32_bf16 v[88:91], v[174:177], v[200:203], v[88:91]
	v_mfma_f32_16x16x32_bf16 v[88:91], v[170:173], v[196:199], v[88:91]
	v_mfma_f32_16x16x32_bf16 v[84:87], v[170:173], v[204:207], v[84:87]
	v_mfma_f32_16x16x32_bf16 v[84:87], v[174:177], v[230:233], v[84:87]
	v_mfma_f32_16x16x32_bf16 v[36:39], v[174:177], v[238:241], v[36:39]
	v_mfma_f32_16x16x32_bf16 v[36:39], v[170:173], v[234:237], v[36:39]
	v_mfma_f32_16x16x32_bf16 v[32:35], v[178:181], v[234:237], v[32:35]
	v_mfma_f32_16x16x32_bf16 v[32:35], v[184:187], v[238:241], v[32:35]
	v_mfma_f32_16x16x32_bf16 v[80:83], v[184:187], v[230:233], v[80:83]
	v_mfma_f32_16x16x32_bf16 v[80:83], v[178:181], v[204:207], v[80:83]
	v_mfma_f32_16x16x32_bf16 v[92:95], v[178:181], v[196:199], v[92:95]
	v_mfma_f32_16x16x32_bf16 v[92:95], v[184:187], v[200:203], v[92:95]
	v_mfma_f32_16x16x32_bf16 v[44:47], v[184:187], v[192:195], v[44:47]
	v_mfma_f32_16x16x32_bf16 v[44:47], v[178:181], v[188:191], v[44:47]
	s_setprio 0
	s_barrier
	s_add_u32 s38, s38, 0x100
	s_addc_u32 s39, s39, 0
	s_add_u32 s79, s79, 0x100
	s_addc_u32 s80, s80, 0
	s_cmp_ge_u32 s81, s9
	s_mov_b32 s40, s81
	s_cbranch_scc0 .LBB0_294

; #define PG8_STAGE(bufoff, gbase, voff) do { _Pragma("unroll") for (int _i = 0; _i < 2; ++_i) \
;         __builtin_amdgcn_global_load_lds((const unsigned*)((const char*)(gbase) + (voff)[_i]), (PG8_LAS unsigned*)(lds + (bufoff) + ldsw + _i * 8192), 16, 0, 0); } while (0)
; #define PG8_LDA(dst, b, h) do { _Pragma("unroll") for (int m = 0; m < 4; ++m) _Pragma("unroll") for (int k = 0; k < 2; ++k) dst[m][k] = *(const PG8_LAS bf16x8*)(lds + PG8_SA(b, h) + aoff + m * 2048 + k * 1024); } while (0)
; #define PG8_LDB(dst, b, h) do { _Pragma("unroll") for (int n = 0; n < 2; ++n) _Pragma("unroll") for (int k = 0; k < 2; ++k) dst[n][k] = *(const PG8_LAS bf16x8*)(lds + PG8_SB(b, h) + boff + n * 2048 + k * 1024); } while (0)
; #define PG8_MMA(ai, bj, At, Bt) do { __builtin_amdgcn_s_setprio(1); _Pragma("unroll") for (int m = 0; m < 4; ++m) _Pragma("unroll") for (int n = 0; n < 2; ++n) _Pragma("unroll") for (int k = 0; k < 2; ++k) \
;         acc[ai][bj][m][n] = __builtin_amdgcn_mfma_f32_16x16x32_bf16(Bt[n][k], At[m][k], acc[ai][bj][m][n], 0, 0, 0); __builtin_amdgcn_s_setprio(0); } while (0)
; #define PG8_WAIT_V(n) asm volatile("s_waitcnt vmcnt(" #n ")" ::: "memory")
; #define PG8_WAIT_L(n) asm volatile("s_waitcnt lgkmcnt(" #n ")" ::: "memory")
; template <class Epi, class Sched, bool ALIGN_EPI = false, bool SP2 = false>
; __device__ __forceinline__ void gemm_phase(PG8_LAS unsigned char* lds, const Gemm g, const Sched& S, const Epi& E) {
;     ...
;             const bool last = (t == nt - 2);
;             const char* a1 = cA + (size_t)(t + 1) * kstep;
;             const char* a2 = last ? nA : cA + (size_t)(t + 2) * kstep; const char* b2 = last ? nB : cB + (size_t)(t + 2) * kstep;
;             const char* a3 = a2 + kstep; const char* b3 = b2 + kstep;
;             if (last && has_next) S.a_ready(nxt);
;             if constexpr (SP2) {
;             PG8_LDB(B0, 0, 0); PG8_LDB(B1, 0, 1); PG8_SCHED; PG8_LDA(At, 0, 0); PG8_STAGE(PG8_SA(1, 1), a1 + hstep, voffA);
;             PG8_WAIT_V(8); PG8_WAIT_L(0); PG8_BAR; PG8_MMA(0, 0, At, B0); PG8_MMA(0, 1, At, B1); PG8_BAR; PG8_SCHED;
;             PG8_LDA(At, 0, 1); PG8_STAGE(PG8_SB(0, 0), b2, voffB); PG8_STAGE(PG8_SB(0, 1), b2 + hstep, voffB); PG8_STAGE(PG8_SA(0, 0), a2, voffA);
;             PG8_WAIT_V(8); PG8_WAIT_L(0); PG8_BAR; PG8_MMA(1, 0, At, B0); PG8_MMA(1, 1, At, B1); PG8_BAR; PG8_SCHED;
.LBB0_365:
	s_add_i32 s88, s86, 2
	s_add_u32 s89, s0, 0x80
	s_addc_u32 s87, s1, 0
	s_cmp_eq_u32 s33, s86
	s_cselect_b32 s87, s3, s87
	s_cselect_b32 s86, s2, s89
	v_add_u32_e32 v0, s19, v230
	s_cselect_b32 vcc_hi, s85, s73
	s_cselect_b32 vcc_lo, s84, s72
	s_add_i32 s89, 0, 0x14000
	ds_read_b128 v[120:123], v0
	ds_read_b128 v[124:127], v0 offset:1024
	ds_read_b128 v[128:131], v0 offset:2048
	ds_read_b128 v[132:135], v0 offset:3072
	v_add_u32_e32 v0, s89, v230
	ds_read_b128 v[136:139], v0
	ds_read_b128 v[140:143], v0 offset:1024
	ds_read_b128 v[162:165], v0 offset:2048
	ds_read_b128 v[166:169], v0 offset:3072
	v_lshl_add_u64 v[144:145], s[0:1], 0, v[184:185]
	s_add_i32 m0, s93, 0xc000
	ds_read_b128 v[170:173], v238
	ds_read_b128 v[188:191], v238 offset:1024
	ds_read_b128 v[192:195], v238 offset:2048
	ds_read_b128 v[196:199], v238 offset:3072
	ds_read_b128 v[200:203], v238 offset:4096
	ds_read_b128 v[204:207], v238 offset:5120
	ds_read_b128 v[242:245], v238 offset:6144
	ds_read_b128 v[246:249], v238 offset:7168
	global_load_lds_dwordx4 v[144:145], off
	v_lshl_add_u64 v[144:145], s[0:1], 0, v[186:187]
	s_add_i32 m0, s93, 0xe000
	s_nop 0
	global_load_lds_dwordx4 v[144:145], off
	s_waitcnt vmcnt(8)
	s_waitcnt lgkmcnt(0)
	s_barrier
	s_setprio 1
	s_waitcnt lgkmcnt(0)
	v_mfma_f32_16x16x32_bf16 v[158:161], v[120:123], v[170:173], v[158:161]
	v_mfma_f32_16x16x32_bf16 v[158:161], v[124:127], v[188:191], v[158:161]
	v_mfma_f32_16x16x32_bf16 v[150:153], v[120:123], v[192:195], v[150:153]
	v_mfma_f32_16x16x32_bf16 v[150:153], v[124:127], v[196:199], v[150:153]
	v_mfma_f32_16x16x32_bf16 v[100:103], v[120:123], v[200:203], v[100:103]
	v_mfma_f32_16x16x32_bf16 v[100:103], v[124:127], v[204:207], v[100:103]
	v_mfma_f32_16x16x32_bf16 v[116:119], v[120:123], v[242:245], v[116:119]
	v_mfma_f32_16x16x32_bf16 v[116:119], v[124:127], v[246:249], v[116:119]
	v_mfma_f32_16x16x32_bf16 v[68:71], v[128:131], v[242:245], v[68:71]
	v_mfma_f32_16x16x32_bf16 v[68:71], v[132:135], v[246:249], v[68:71]
	v_mfma_f32_16x16x32_bf16 v[36:39], v[128:131], v[200:203], v[36:39]
	v_mfma_f32_16x16x32_bf16 v[36:39], v[132:135], v[204:207], v[36:39]
	v_mfma_f32_16x16x32_bf16 v[52:55], v[128:131], v[192:195], v[52:55]
	v_mfma_f32_16x16x32_bf16 v[52:55], v[132:135], v[196:199], v[52:55]
	v_mfma_f32_16x16x32_bf16 v[60:63], v[128:131], v[170:173], v[60:63]
	v_mfma_f32_16x16x32_bf16 v[60:63], v[132:135], v[188:191], v[60:63]
	s_setprio 0
	s_setprio 1
	v_mfma_f32_16x16x32_bf16 v[154:157], v[136:139], v[170:173], v[154:157]
	v_mfma_f32_16x16x32_bf16 v[154:157], v[140:143], v[188:191], v[154:157]
	v_mfma_f32_16x16x32_bf16 v[144:147], v[136:139], v[192:195], v[146:149]
	v_mfma_f32_16x16x32_bf16 v[144:147], v[140:143], v[196:199], v[144:147]
	v_mfma_f32_16x16x32_bf16 v[96:99], v[136:139], v[200:203], v[96:99]
	v_mfma_f32_16x16x32_bf16 v[96:99], v[140:143], v[204:207], v[96:99]
	v_mfma_f32_16x16x32_bf16 v[112:115], v[136:139], v[242:245], v[112:115]
	v_mfma_f32_16x16x32_bf16 v[112:115], v[140:143], v[246:249], v[112:115]
	v_mfma_f32_16x16x32_bf16 v[64:67], v[162:165], v[242:245], v[64:67]
	v_mfma_f32_16x16x32_bf16 v[64:67], v[166:169], v[246:249], v[64:67]
	v_mfma_f32_16x16x32_bf16 v[32:35], v[162:165], v[200:203], v[32:35]
	v_mfma_f32_16x16x32_bf16 v[32:35], v[166:169], v[204:207], v[32:35]
	v_mfma_f32_16x16x32_bf16 v[48:51], v[162:165], v[192:195], v[48:51]
	v_mfma_f32_16x16x32_bf16 v[48:51], v[166:169], v[196:199], v[48:51]
	v_mfma_f32_16x16x32_bf16 v[56:59], v[162:165], v[170:173], v[56:59]
	v_mfma_f32_16x16x32_bf16 v[56:59], v[166:169], v[188:191], v[56:59]
	s_setprio 0
	s_barrier
	s_add_i32 s38, s19, s92
	v_lshl_add_u64 v[174:175], vcc, 0, v[176:177]
	s_mov_b32 m0, s38
	ds_read_b128 v[170:173], v238 offset:16384
	ds_read_b128 v[188:191], v238 offset:17408
	ds_read_b128 v[192:195], v238 offset:18432
	ds_read_b128 v[196:199], v238 offset:19456
	ds_read_b128 v[200:203], v238 offset:20480
	ds_read_b128 v[204:207], v238 offset:21504
	ds_read_b128 v[242:245], v238 offset:22528
	ds_read_b128 v[246:249], v238 offset:23552
	global_load_lds_dwordx4 v[174:175], off
	s_add_i32 m0, s38, 0x2000
	v_lshl_add_u64 v[208:209], vcc, 0, v[180:181]
	s_add_u32 vcc_lo, vcc_lo, s48
	s_addc_u32 vcc_hi, vcc_hi, s49
	s_add_i32 s38, s89, s92
	global_load_lds_dwordx4 v[208:209], off
	v_lshl_add_u64 v[216:217], vcc, 0, v[176:177]
	s_mov_b32 m0, s38
	v_lshl_add_u64 v[224:225], vcc, 0, v[180:181]
	global_load_lds_dwordx4 v[216:217], off
	s_add_i32 m0, s38, 0x2000
	v_lshl_add_u64 v[226:227], s[86:87], 0, v[2:3]
	global_load_lds_dwordx4 v[224:225], off
	s_mov_b32 m0, s93
	v_lshl_add_u64 v[228:229], s[86:87], 0, v[178:179]
	global_load_lds_dwordx4 v[226:227], off
	s_mov_b32 m0, s94
	s_nop 0
	global_load_lds_dwordx4 v[228:229], off
	s_waitcnt vmcnt(8)
	s_waitcnt lgkmcnt(0)
	s_barrier
; #define PG8_STAGE(bufoff, gbase, voff) do { _Pragma("unroll") for (int _i = 0; _i < 2; ++_i) \
;         __builtin_amdgcn_global_load_lds((const unsigned*)((const char*)(gbase) + (voff)[_i]), (PG8_LAS unsigned*)(lds + (bufoff) + ldsw + _i * 8192), 16, 0, 0); } while (0)
; #define PG8_LDA(dst, b, h) do { _Pragma("unroll") for (int m = 0; m < 4; ++m) _Pragma("unroll") for (int k = 0; k < 2; ++k) dst[m][k] = *(const PG8_LAS bf16x8*)(lds + PG8_SA(b, h) + aoff + m * 2048 + k * 1024); } while (0)
; #define PG8_LDB(dst, b, h) do { _Pragma("unroll") for (int n = 0; n < 2; ++n) _Pragma("unroll") for (int k = 0; k < 2; ++k) dst[n][k] = *(const PG8_LAS bf16x8*)(lds + PG8_SB(b, h) + boff + n * 2048 + k * 1024); } while (0)
; #define PG8_MMA(ai, bj, At, Bt) do { __builtin_amdgcn_s_setprio(1); _Pragma("unroll") for (int m = 0; m < 4; ++m) _Pragma("unroll") for (int n = 0; n < 2; ++n) _Pragma("unroll") for (int k = 0; k < 2; ++k) \
;         acc[ai][bj][m][n] = __builtin_amdgcn_mfma_f32_16x16x32_bf16(Bt[n][k], At[m][k], acc[ai][bj][m][n], 0, 0, 0); __builtin_amdgcn_s_setprio(0); } while (0)
; #define PG8_WAIT_V(n) asm volatile("s_waitcnt vmcnt(" #n ")" ::: "memory")
; #define PG8_WAIT_L(n) asm volatile("s_waitcnt lgkmcnt(" #n ")" ::: "memory")
; #define PG8_BAR __builtin_amdgcn_s_barrier()
; #define PG8_SCHED __builtin_amdgcn_sched_barrier(0)
; template <class Epi, class Sched, bool ALIGN_EPI = false, bool SP2 = false>
; __device__ __forceinline__ void gemm_phase(PG8_LAS unsigned char* lds, const Gemm g, const Sched& S, const Epi& E) {
;     ...
;             PG8_WAIT_V(8); PG8_WAIT_L(0); PG8_BAR; PG8_MMA(1, 0, At, B0); PG8_MMA(1, 1, At, B1); PG8_BAR; PG8_SCHED;
;             PG8_LDB(B0, 1, 0); PG8_LDB(B1, 1, 1); PG8_SCHED; PG8_LDA(At, 1, 0); PG8_STAGE(PG8_SA(0, 1), a2 + hstep, voffA);
;             PG8_WAIT_V(8); PG8_WAIT_L(0); PG8_BAR; PG8_MMA(0, 0, At, B0); PG8_MMA(0, 1, At, B1); PG8_BAR; PG8_SCHED;
	s_setprio 1
	s_waitcnt lgkmcnt(0)
	v_mfma_f32_16x16x32_bf16 v[92:95], v[120:123], v[170:173], v[92:95]
	v_mfma_f32_16x16x32_bf16 v[92:95], v[124:127], v[188:191], v[92:95]
	v_mfma_f32_16x16x32_bf16 v[84:87], v[124:127], v[196:199], v[84:87]
	v_mfma_f32_16x16x32_bf16 v[84:87], v[120:123], v[192:195], v[84:87]
	v_mfma_f32_16x16x32_bf16 v[76:79], v[120:123], v[200:203], v[76:79]
	v_mfma_f32_16x16x32_bf16 v[76:79], v[124:127], v[204:207], v[76:79]
	v_mfma_f32_16x16x32_bf16 v[108:111], v[124:127], v[246:249], v[108:111]
	v_mfma_f32_16x16x32_bf16 v[108:111], v[120:123], v[242:245], v[108:111]
	v_mfma_f32_16x16x32_bf16 v[44:47], v[128:131], v[242:245], v[44:47]
	v_mfma_f32_16x16x32_bf16 v[44:47], v[132:135], v[246:249], v[44:47]
	v_mfma_f32_16x16x32_bf16 v[12:15], v[132:135], v[204:207], v[12:15]
	v_mfma_f32_16x16x32_bf16 v[12:15], v[128:131], v[200:203], v[12:15]
	v_mfma_f32_16x16x32_bf16 v[20:23], v[128:131], v[192:195], v[20:23]
	v_mfma_f32_16x16x32_bf16 v[20:23], v[132:135], v[196:199], v[20:23]
	v_mfma_f32_16x16x32_bf16 v[28:31], v[132:135], v[188:191], v[28:31]
	v_mfma_f32_16x16x32_bf16 v[28:31], v[128:131], v[170:173], v[28:31]
	s_setprio 0
	s_setprio 1
	v_mfma_f32_16x16x32_bf16 v[88:91], v[136:139], v[170:173], v[88:91]
	v_mfma_f32_16x16x32_bf16 v[88:91], v[140:143], v[188:191], v[88:91]
	v_mfma_f32_16x16x32_bf16 v[80:83], v[140:143], v[196:199], v[80:83]
	v_mfma_f32_16x16x32_bf16 v[80:83], v[136:139], v[192:195], v[80:83]
	v_mfma_f32_16x16x32_bf16 v[72:75], v[136:139], v[200:203], v[72:75]
	v_mfma_f32_16x16x32_bf16 v[72:75], v[140:143], v[204:207], v[72:75]
	v_mfma_f32_16x16x32_bf16 v[104:107], v[140:143], v[246:249], v[104:107]
	v_mfma_f32_16x16x32_bf16 v[104:107], v[136:139], v[242:245], v[104:107]
	v_mfma_f32_16x16x32_bf16 v[40:43], v[162:165], v[242:245], v[40:43]
	v_mfma_f32_16x16x32_bf16 v[40:43], v[166:169], v[246:249], v[40:43]
	v_mfma_f32_16x16x32_bf16 v[8:11], v[166:169], v[204:207], v[8:11]
	v_mfma_f32_16x16x32_bf16 v[8:11], v[162:165], v[200:203], v[8:11]
	v_mfma_f32_16x16x32_bf16 v[16:19], v[162:165], v[192:195], v[16:19]
	v_mfma_f32_16x16x32_bf16 v[16:19], v[166:169], v[196:199], v[16:19]
	v_mfma_f32_16x16x32_bf16 v[24:27], v[166:169], v[188:191], v[24:27]
	v_mfma_f32_16x16x32_bf16 v[24:27], v[162:165], v[170:173], v[24:27]
	s_setprio 0
	s_barrier
	v_add_u32_e32 v0, s91, v230
	s_add_i32 s38, 0, 0x1c000
	ds_read_b128 v[120:123], v0
	ds_read_b128 v[124:127], v0 offset:1024
	ds_read_b128 v[128:131], v0 offset:2048
	ds_read_b128 v[132:135], v0 offset:3072
	v_add_u32_e32 v0, s38, v230
	ds_read_b128 v[136:139], v0
	ds_read_b128 v[140:143], v0 offset:1024
	ds_read_b128 v[162:165], v0 offset:2048
	ds_read_b128 v[166:169], v0 offset:3072
	s_add_u32 s86, s86, s48
	s_addc_u32 s87, s87, s49
	s_mov_b32 m0, s95
	v_lshl_add_u64 v[148:149], s[86:87], 0, v[2:3]
	ds_read_b128 v[170:173], v238 offset:32768
	ds_read_b128 v[188:191], v238 offset:33792
	ds_read_b128 v[192:195], v238 offset:34816
	ds_read_b128 v[196:199], v238 offset:35840
	ds_read_b128 v[200:203], v238 offset:36864
	ds_read_b128 v[204:207], v238 offset:37888
	ds_read_b128 v[242:245], v238 offset:38912
	ds_read_b128 v[246:249], v238 offset:39936
	global_load_lds_dwordx4 v[148:149], off
	v_lshl_add_u64 v[148:149], s[86:87], 0, v[178:179]
	s_mov_b32 m0, s96
	s_nop 0
	global_load_lds_dwordx4 v[148:149], off
	s_waitcnt vmcnt(8)
	s_waitcnt lgkmcnt(0)
	s_barrier
	s_setprio 1
	s_waitcnt lgkmcnt(0)
	v_mfma_f32_16x16x32_bf16 v[158:161], v[120:123], v[170:173], v[158:161]
	v_mfma_f32_16x16x32_bf16 v[158:161], v[124:127], v[188:191], v[158:161]
	v_mfma_f32_16x16x32_bf16 v[148:151], v[120:123], v[192:195], v[150:153]
	v_mfma_f32_16x16x32_bf16 v[150:153], v[124:127], v[196:199], v[148:151]
	v_mfma_f32_16x16x32_bf16 v[100:103], v[120:123], v[200:203], v[100:103]
	v_mfma_f32_16x16x32_bf16 v[100:103], v[124:127], v[204:207], v[100:103]
	v_mfma_f32_16x16x32_bf16 v[116:119], v[120:123], v[242:245], v[116:119]
	v_mfma_f32_16x16x32_bf16 v[116:119], v[124:127], v[246:249], v[116:119]
	v_mfma_f32_16x16x32_bf16 v[68:71], v[128:131], v[242:245], v[68:71]
	v_mfma_f32_16x16x32_bf16 v[68:71], v[132:135], v[246:249], v[68:71]
	v_mfma_f32_16x16x32_bf16 v[36:39], v[128:131], v[200:203], v[36:39]
	v_mfma_f32_16x16x32_bf16 v[36:39], v[132:135], v[204:207], v[36:39]
	v_mfma_f32_16x16x32_bf16 v[52:55], v[128:131], v[192:195], v[52:55]
	v_mfma_f32_16x16x32_bf16 v[52:55], v[132:135], v[196:199], v[52:55]
	v_mfma_f32_16x16x32_bf16 v[60:63], v[128:131], v[170:173], v[60:63]
	v_mfma_f32_16x16x32_bf16 v[60:63], v[132:135], v[188:191], v[60:63]
	s_setprio 0
	s_setprio 1
	v_mfma_f32_16x16x32_bf16 v[154:157], v[136:139], v[170:173], v[154:157]
	v_mfma_f32_16x16x32_bf16 v[154:157], v[140:143], v[188:191], v[154:157]
	v_mfma_f32_16x16x32_bf16 v[144:147], v[136:139], v[192:195], v[144:147]
	v_mfma_f32_16x16x32_bf16 v[146:149], v[140:143], v[196:199], v[144:147]
	v_mfma_f32_16x16x32_bf16 v[96:99], v[136:139], v[200:203], v[96:99]
	v_mfma_f32_16x16x32_bf16 v[96:99], v[140:143], v[204:207], v[96:99]
	v_mfma_f32_16x16x32_bf16 v[112:115], v[136:139], v[242:245], v[112:115]
	v_mfma_f32_16x16x32_bf16 v[112:115], v[140:143], v[246:249], v[112:115]
	v_mfma_f32_16x16x32_bf16 v[64:67], v[162:165], v[242:245], v[64:67]
	v_mfma_f32_16x16x32_bf16 v[64:67], v[166:169], v[246:249], v[64:67]
	v_mfma_f32_16x16x32_bf16 v[32:35], v[162:165], v[200:203], v[32:35]
	v_mfma_f32_16x16x32_bf16 v[32:35], v[166:169], v[204:207], v[32:35]
	v_mfma_f32_16x16x32_bf16 v[48:51], v[162:165], v[192:195], v[48:51]
	v_mfma_f32_16x16x32_bf16 v[48:51], v[166:169], v[196:199], v[48:51]
	v_mfma_f32_16x16x32_bf16 v[56:59], v[162:165], v[170:173], v[56:59]
	v_mfma_f32_16x16x32_bf16 v[56:59], v[166:169], v[188:191], v[56:59]
	s_setprio 0
	s_barrier
; #define PG8_STAGE(bufoff, gbase, voff) do { _Pragma("unroll") for (int _i = 0; _i < 2; ++_i) \
;         __builtin_amdgcn_global_load_lds((const unsigned*)((const char*)(gbase) + (voff)[_i]), (PG8_LAS unsigned*)(lds + (bufoff) + ldsw + _i * 8192), 16, 0, 0); } while (0)
; #define PG8_LDA(dst, b, h) do { _Pragma("unroll") for (int m = 0; m < 4; ++m) _Pragma("unroll") for (int k = 0; k < 2; ++k) dst[m][k] = *(const PG8_LAS bf16x8*)(lds + PG8_SA(b, h) + aoff + m * 2048 + k * 1024); } while (0)
; #define PG8_MMA(ai, bj, At, Bt) do { __builtin_amdgcn_s_setprio(1); _Pragma("unroll") for (int m = 0; m < 4; ++m) _Pragma("unroll") for (int n = 0; n < 2; ++n) _Pragma("unroll") for (int k = 0; k < 2; ++k) \
;         acc[ai][bj][m][n] = __builtin_amdgcn_mfma_f32_16x16x32_bf16(Bt[n][k], At[m][k], acc[ai][bj][m][n], 0, 0, 0); __builtin_amdgcn_s_setprio(0); } while (0)
; #define PG8_WAIT_V(n) asm volatile("s_waitcnt vmcnt(" #n ")" ::: "memory")
; #define PG8_WAIT_L(n) asm volatile("s_waitcnt lgkmcnt(" #n ")" ::: "memory")
; #define PG8_BAR __builtin_amdgcn_s_barrier()
; #define PG8_SCHED __builtin_amdgcn_sched_barrier(0)
; template <class Epi, class Sched, bool ALIGN_EPI = false, bool SP2 = false>
; __device__ __forceinline__ void gemm_phase(PG8_LAS unsigned char* lds, const Gemm g, const Sched& S, const Epi& E) {
;     ...
;             PG8_LDA(At, 1, 1); PG8_STAGE(PG8_SB(1, 0), b3, voffB); PG8_STAGE(PG8_SB(1, 1), b3 + hstep, voffB); PG8_STAGE(PG8_SA(1, 0), a3, voffA);
;             PG8_WAIT_V(8); PG8_WAIT_L(0); PG8_BAR; PG8_MMA(1, 0, At, B0); PG8_MMA(1, 1, At, B1); PG8_BAR; PG8_SCHED;
	s_add_i32 s39, s91, s92
	v_lshl_add_u64 v[144:145], v[174:175], 0, s[24:25]
	s_mov_b32 m0, s39
	ds_read_b128 v[170:173], v238 offset:49152
	ds_read_b128 v[188:191], v238 offset:50176
	ds_read_b128 v[192:195], v238 offset:51200
	ds_read_b128 v[196:199], v238 offset:52224
	ds_read_b128 v[200:203], v238 offset:53248
	ds_read_b128 v[204:207], v238 offset:54272
	ds_read_b128 v[242:245], v238 offset:55296
	ds_read_b128 v[246:249], v238 offset:56320
	global_load_lds_dwordx4 v[144:145], off
	v_lshl_add_u64 v[144:145], v[208:209], 0, s[24:25]
	s_add_i32 m0, s39, 0x2000
	s_add_i32 s38, s38, s92
	global_load_lds_dwordx4 v[144:145], off
	v_lshl_add_u64 v[144:145], v[216:217], 0, s[24:25]
	s_mov_b32 m0, s38
	s_nop 0
	global_load_lds_dwordx4 v[144:145], off
	v_lshl_add_u64 v[144:145], v[224:225], 0, s[24:25]
	s_add_i32 m0, s38, 0x2000
	s_nop 0
	global_load_lds_dwordx4 v[144:145], off
	v_lshl_add_u64 v[144:145], v[226:227], 0, s[24:25]
	s_mov_b32 m0, s10
	s_nop 0
	global_load_lds_dwordx4 v[144:145], off
	v_lshl_add_u64 v[144:145], v[228:229], 0, s[24:25]
	s_mov_b32 m0, s11
	s_nop 0
	global_load_lds_dwordx4 v[144:145], off
	s_waitcnt vmcnt(8)
	s_waitcnt lgkmcnt(0)
	s_barrier
	s_setprio 1
	s_waitcnt lgkmcnt(0)
	v_mfma_f32_16x16x32_bf16 v[92:95], v[120:123], v[170:173], v[92:95]
	v_mfma_f32_16x16x32_bf16 v[92:95], v[124:127], v[188:191], v[92:95]
	v_mfma_f32_16x16x32_bf16 v[84:87], v[124:127], v[196:199], v[84:87]
	v_mfma_f32_16x16x32_bf16 v[84:87], v[120:123], v[192:195], v[84:87]
	v_mfma_f32_16x16x32_bf16 v[76:79], v[120:123], v[200:203], v[76:79]
	v_mfma_f32_16x16x32_bf16 v[76:79], v[124:127], v[204:207], v[76:79]
	v_mfma_f32_16x16x32_bf16 v[108:111], v[124:127], v[246:249], v[108:111]
	v_mfma_f32_16x16x32_bf16 v[108:111], v[120:123], v[242:245], v[108:111]
	v_mfma_f32_16x16x32_bf16 v[44:47], v[128:131], v[242:245], v[44:47]
	v_mfma_f32_16x16x32_bf16 v[44:47], v[132:135], v[246:249], v[44:47]
	v_mfma_f32_16x16x32_bf16 v[12:15], v[132:135], v[204:207], v[12:15]
	v_mfma_f32_16x16x32_bf16 v[12:15], v[128:131], v[200:203], v[12:15]
	v_mfma_f32_16x16x32_bf16 v[20:23], v[128:131], v[192:195], v[20:23]
	v_mfma_f32_16x16x32_bf16 v[20:23], v[132:135], v[196:199], v[20:23]
	v_mfma_f32_16x16x32_bf16 v[28:31], v[132:135], v[188:191], v[28:31]
	v_mfma_f32_16x16x32_bf16 v[28:31], v[128:131], v[170:173], v[28:31]
	s_setprio 0
	s_setprio 1
	v_mfma_f32_16x16x32_bf16 v[88:91], v[136:139], v[170:173], v[88:91]
	v_mfma_f32_16x16x32_bf16 v[88:91], v[140:143], v[188:191], v[88:91]
	v_mfma_f32_16x16x32_bf16 v[80:83], v[140:143], v[196:199], v[80:83]
	v_mfma_f32_16x16x32_bf16 v[80:83], v[136:139], v[192:195], v[80:83]
	v_mfma_f32_16x16x32_bf16 v[72:75], v[136:139], v[200:203], v[72:75]
	v_mfma_f32_16x16x32_bf16 v[72:75], v[140:143], v[204:207], v[72:75]
	v_mfma_f32_16x16x32_bf16 v[104:107], v[140:143], v[246:249], v[104:107]
	v_mfma_f32_16x16x32_bf16 v[104:107], v[136:139], v[242:245], v[104:107]
	v_mfma_f32_16x16x32_bf16 v[40:43], v[162:165], v[242:245], v[40:43]
	v_mfma_f32_16x16x32_bf16 v[40:43], v[166:169], v[246:249], v[40:43]
	v_mfma_f32_16x16x32_bf16 v[8:11], v[166:169], v[204:207], v[8:11]
	v_mfma_f32_16x16x32_bf16 v[8:11], v[162:165], v[200:203], v[8:11]
	v_mfma_f32_16x16x32_bf16 v[16:19], v[162:165], v[192:195], v[16:19]
	v_mfma_f32_16x16x32_bf16 v[16:19], v[166:169], v[196:199], v[16:19]
	v_mfma_f32_16x16x32_bf16 v[24:27], v[166:169], v[188:191], v[24:27]
	v_mfma_f32_16x16x32_bf16 v[24:27], v[162:165], v[170:173], v[24:27]
	s_setprio 0
	s_barrier
	s_add_u32 s0, s0, 0x100
	s_addc_u32 s1, s1, 0
	s_add_u32 s72, s72, 0x100
	s_addc_u32 s73, s73, 0
	s_cmp_ge_u32 s88, s9
	s_mov_b32 s86, s88
	s_cbranch_scc0 .LBB0_365

; #define PG8_STAGE(bufoff, gbase, voff) do { _Pragma("unroll") for (int _i = 0; _i < 2; ++_i) \
;         __builtin_amdgcn_global_load_lds((const unsigned*)((const char*)(gbase) + (voff)[_i]), (PG8_LAS unsigned*)(lds + (bufoff) + ldsw + _i * 8192), 16, 0, 0); } while (0)
; #define PG8_LDA(dst, b, h) do { _Pragma("unroll") for (int m = 0; m < 4; ++m) _Pragma("unroll") for (int k = 0; k < 2; ++k) dst[m][k] = *(const PG8_LAS bf16x8*)(lds + PG8_SA(b, h) + aoff + m * 2048 + k * 1024); } while (0)
; #define PG8_LDB(dst, b, h) do { _Pragma("unroll") for (int n = 0; n < 2; ++n) _Pragma("unroll") for (int k = 0; k < 2; ++k) dst[n][k] = *(const PG8_LAS bf16x8*)(lds + PG8_SB(b, h) + boff + n * 2048 + k * 1024); } while (0)
; #define PG8_MMA(ai, bj, At, Bt) do { __builtin_amdgcn_s_setprio(1); _Pragma("unroll") for (int m = 0; m < 4; ++m) _Pragma("unroll") for (int n = 0; n < 2; ++n) _Pragma("unroll") for (int k = 0; k < 2; ++k) \
;         acc[ai][bj][m][n] = __builtin_amdgcn_mfma_f32_16x16x32_bf16(Bt[n][k], At[m][k], acc[ai][bj][m][n], 0, 0, 0); __builtin_amdgcn_s_setprio(0); } while (0)
; #define PG8_WAIT_V(n) asm volatile("s_waitcnt vmcnt(" #n ")" ::: "memory")
; #define PG8_WAIT_L(n) asm volatile("s_waitcnt lgkmcnt(" #n ")" ::: "memory")
; template <class Epi, class Sched, bool ALIGN_EPI = false, bool SP2 = false>
; __device__ __forceinline__ void gemm_phase(PG8_LAS unsigned char* lds, const Gemm g, const Sched& S, const Epi& E) {
;     ...
;             const bool last = (t == nt - 2);
;             const char* a1 = cA + (size_t)(t + 1) * kstep;
;             const char* a2 = last ? nA : cA + (size_t)(t + 2) * kstep; const char* b2 = last ? nB : cB + (size_t)(t + 2) * kstep;
;             const char* a3 = a2 + kstep; const char* b3 = b2 + kstep;
;             if (last && has_next) S.a_ready(nxt);
;             if constexpr (SP2) {
;             PG8_LDB(B0, 0, 0); PG8_LDB(B1, 0, 1); PG8_SCHED; PG8_LDA(At, 0, 0); PG8_STAGE(PG8_SA(1, 1), a1 + hstep, voffA);
;             PG8_WAIT_V(8); PG8_WAIT_L(0); PG8_BAR; PG8_MMA(0, 0, At, B0); PG8_MMA(0, 1, At, B1); PG8_BAR; PG8_SCHED;
;             PG8_LDA(At, 0, 1); PG8_STAGE(PG8_SB(0, 0), b2, voffB); PG8_STAGE(PG8_SB(0, 1), b2 + hstep, voffB); PG8_STAGE(PG8_SA(0, 0), a2, voffA);
;             PG8_WAIT_V(8); PG8_WAIT_L(0); PG8_BAR; PG8_MMA(1, 0, At, B0); PG8_MMA(1, 1, At, B1); PG8_BAR; PG8_SCHED;
.LBB0_468:
	s_add_i32 s78, s38, 2
	s_add_u32 s79, s0, 0x80
	s_addc_u32 s39, s1, 0
	s_cmp_eq_u32 s33, s38
	s_cselect_b32 s39, s7, s39
	s_cselect_b32 s38, s6, s79
	s_cselect_b32 s81, s23, s41
	s_cselect_b32 s80, s22, s40
	s_add_i32 s79, 0, 0x14000
	v_add_u32_e32 v148, s19, v162
	v_add_u32_e32 v171, s79, v162
	ds_read_b128 v[136:139], v148
	ds_read_b128 v[140:143], v148 offset:1024
	ds_read_b128 v[144:147], v148 offset:2048
	ds_read_b128 v[148:151], v148 offset:3072
	ds_read_b128 v[172:175], v171
	ds_read_b128 v[176:179], v171 offset:1024
	ds_read_b128 v[184:187], v171 offset:2048
	ds_read_b128 v[188:191], v171 offset:3072
	v_lshl_add_u64 v[180:181], s[0:1], 0, v[158:159]
	s_add_i32 m0, s46, 0xc000
	ds_read_b128 v[192:195], v167
	ds_read_b128 v[196:199], v167 offset:1024
	ds_read_b128 v[200:203], v167 offset:2048
	ds_read_b128 v[204:207], v167 offset:3072
	ds_read_b128 v[230:233], v167 offset:4096
	ds_read_b128 v[234:237], v167 offset:5120
	ds_read_b128 v[238:241], v167 offset:6144
	ds_read_b128 v[242:245], v167 offset:7168
	global_load_lds_dwordx4 v[180:181], off
	v_lshl_add_u64 v[180:181], s[0:1], 0, v[160:161]
	s_add_i32 m0, s46, 0xe000
	s_nop 0
	global_load_lds_dwordx4 v[180:181], off
	s_waitcnt vmcnt(8)
	s_waitcnt lgkmcnt(0)
	s_barrier
	s_setprio 1
	s_waitcnt lgkmcnt(0)
	v_mfma_f32_16x16x32_bf16 v[132:135], v[136:139], v[192:195], v[132:135]
	v_mfma_f32_16x16x32_bf16 v[132:135], v[140:143], v[196:199], v[132:135]
	v_mfma_f32_16x16x32_bf16 v[116:119], v[140:143], v[204:207], v[116:119]
	v_mfma_f32_16x16x32_bf16 v[116:119], v[136:139], v[200:203], v[116:119]
	v_mfma_f32_16x16x32_bf16 v[100:103], v[136:139], v[230:233], v[100:103]
	v_mfma_f32_16x16x32_bf16 v[100:103], v[140:143], v[234:237], v[100:103]
	v_mfma_f32_16x16x32_bf16 v[84:87], v[140:143], v[242:245], v[84:87]
	v_mfma_f32_16x16x32_bf16 v[84:87], v[136:139], v[238:241], v[84:87]
	v_mfma_f32_16x16x32_bf16 v[80:83], v[144:147], v[238:241], v[80:83]
	v_mfma_f32_16x16x32_bf16 v[80:83], v[148:151], v[242:245], v[80:83]
	v_mfma_f32_16x16x32_bf16 v[96:99], v[148:151], v[234:237], v[96:99]
	v_mfma_f32_16x16x32_bf16 v[96:99], v[144:147], v[230:233], v[96:99]
	v_mfma_f32_16x16x32_bf16 v[112:115], v[144:147], v[200:203], v[112:115]
	v_mfma_f32_16x16x32_bf16 v[112:115], v[148:151], v[204:207], v[112:115]
	v_mfma_f32_16x16x32_bf16 v[128:131], v[148:151], v[196:199], v[128:131]
	v_mfma_f32_16x16x32_bf16 v[128:131], v[144:147], v[192:195], v[128:131]
	s_setprio 0
	s_setprio 1
	v_mfma_f32_16x16x32_bf16 v[124:127], v[172:175], v[192:195], v[124:127]
	v_mfma_f32_16x16x32_bf16 v[124:127], v[176:179], v[196:199], v[124:127]
	v_mfma_f32_16x16x32_bf16 v[108:111], v[176:179], v[204:207], v[108:111]
	v_mfma_f32_16x16x32_bf16 v[108:111], v[172:175], v[200:203], v[108:111]
	v_mfma_f32_16x16x32_bf16 v[92:95], v[172:175], v[230:233], v[92:95]
	v_mfma_f32_16x16x32_bf16 v[92:95], v[176:179], v[234:237], v[92:95]
	v_mfma_f32_16x16x32_bf16 v[76:79], v[176:179], v[242:245], v[76:79]
	v_mfma_f32_16x16x32_bf16 v[76:79], v[172:175], v[238:241], v[76:79]
	v_mfma_f32_16x16x32_bf16 v[72:75], v[184:187], v[238:241], v[72:75]
	v_mfma_f32_16x16x32_bf16 v[72:75], v[188:191], v[242:245], v[72:75]
	v_mfma_f32_16x16x32_bf16 v[88:91], v[188:191], v[234:237], v[88:91]
	v_mfma_f32_16x16x32_bf16 v[88:91], v[184:187], v[230:233], v[88:91]
	v_mfma_f32_16x16x32_bf16 v[104:107], v[184:187], v[200:203], v[104:107]
	v_mfma_f32_16x16x32_bf16 v[104:107], v[188:191], v[204:207], v[104:107]
	v_mfma_f32_16x16x32_bf16 v[120:123], v[188:191], v[196:199], v[120:123]
	v_mfma_f32_16x16x32_bf16 v[120:123], v[184:187], v[192:195], v[120:123]
	s_setprio 0
	s_barrier
	s_add_i32 s82, s19, s42
	v_lshl_add_u64 v[180:181], s[80:81], 0, v[154:155]
	s_mov_b32 m0, s82
	ds_read_b128 v[192:195], v167 offset:16384
	ds_read_b128 v[196:199], v167 offset:17408
	ds_read_b128 v[200:203], v167 offset:18432
	ds_read_b128 v[204:207], v167 offset:19456
	ds_read_b128 v[230:233], v167 offset:20480
	ds_read_b128 v[234:237], v167 offset:21504
	ds_read_b128 v[238:241], v167 offset:22528
	ds_read_b128 v[242:245], v167 offset:23552
	global_load_lds_dwordx4 v[180:181], off
	s_add_i32 m0, s82, 0x2000
	v_lshl_add_u64 v[208:209], s[80:81], 0, v[2:3]
	s_add_u32 s80, s80, s48
	s_addc_u32 s81, s81, s49
	s_add_i32 s79, s79, s42
	global_load_lds_dwordx4 v[208:209], off
	v_lshl_add_u64 v[216:217], s[80:81], 0, v[154:155]
	s_mov_b32 m0, s79
	v_lshl_add_u64 v[224:225], s[80:81], 0, v[2:3]
	global_load_lds_dwordx4 v[216:217], off
	s_add_i32 m0, s79, 0x2000
	v_lshl_add_u64 v[226:227], s[38:39], 0, v[156:157]
	global_load_lds_dwordx4 v[224:225], off
	s_mov_b32 m0, s46
	v_lshl_add_u64 v[246:247], s[38:39], 0, v[152:153]
	global_load_lds_dwordx4 v[226:227], off
	s_mov_b32 m0, s47
	s_nop 0
	global_load_lds_dwordx4 v[246:247], off
	s_waitcnt vmcnt(8)
	s_waitcnt lgkmcnt(0)
	s_barrier
; #define PG8_STAGE(bufoff, gbase, voff) do { _Pragma("unroll") for (int _i = 0; _i < 2; ++_i) \
;         __builtin_amdgcn_global_load_lds((const unsigned*)((const char*)(gbase) + (voff)[_i]), (PG8_LAS unsigned*)(lds + (bufoff) + ldsw + _i * 8192), 16, 0, 0); } while (0)
; #define PG8_LDA(dst, b, h) do { _Pragma("unroll") for (int m = 0; m < 4; ++m) _Pragma("unroll") for (int k = 0; k < 2; ++k) dst[m][k] = *(const PG8_LAS bf16x8*)(lds + PG8_SA(b, h) + aoff + m * 2048 + k * 1024); } while (0)
; #define PG8_LDB(dst, b, h) do { _Pragma("unroll") for (int n = 0; n < 2; ++n) _Pragma("unroll") for (int k = 0; k < 2; ++k) dst[n][k] = *(const PG8_LAS bf16x8*)(lds + PG8_SB(b, h) + boff + n * 2048 + k * 1024); } while (0)
; #define PG8_MMA(ai, bj, At, Bt) do { __builtin_amdgcn_s_setprio(1); _Pragma("unroll") for (int m = 0; m < 4; ++m) _Pragma("unroll") for (int n = 0; n < 2; ++n) _Pragma("unroll") for (int k = 0; k < 2; ++k) \
;         acc[ai][bj][m][n] = __builtin_amdgcn_mfma_f32_16x16x32_bf16(Bt[n][k], At[m][k], acc[ai][bj][m][n], 0, 0, 0); __builtin_amdgcn_s_setprio(0); } while (0)
; #define PG8_WAIT_V(n) asm volatile("s_waitcnt vmcnt(" #n ")" ::: "memory")
; #define PG8_WAIT_L(n) asm volatile("s_waitcnt lgkmcnt(" #n ")" ::: "memory")
; #define PG8_BAR __builtin_amdgcn_s_barrier()
; #define PG8_SCHED __builtin_amdgcn_sched_barrier(0)
; template <class Epi, class Sched, bool ALIGN_EPI = false, bool SP2 = false>
; __device__ __forceinline__ void gemm_phase(PG8_LAS unsigned char* lds, const Gemm g, const Sched& S, const Epi& E) {
;     ...
;             PG8_WAIT_V(8); PG8_WAIT_L(0); PG8_BAR; PG8_MMA(1, 0, At, B0); PG8_MMA(1, 1, At, B1); PG8_BAR; PG8_SCHED;
;             PG8_LDB(B0, 1, 0); PG8_LDB(B1, 1, 1); PG8_SCHED; PG8_LDA(At, 1, 0); PG8_STAGE(PG8_SA(0, 1), a2 + hstep, voffA);
;             PG8_WAIT_V(8); PG8_WAIT_L(0); PG8_BAR; PG8_MMA(0, 0, At, B0); PG8_MMA(0, 1, At, B1); PG8_BAR; PG8_SCHED;
	s_setprio 1
	s_waitcnt lgkmcnt(0)
	v_mfma_f32_16x16x32_bf16 v[68:71], v[136:139], v[192:195], v[68:71]
	v_mfma_f32_16x16x32_bf16 v[68:71], v[140:143], v[196:199], v[68:71]
	v_mfma_f32_16x16x32_bf16 v[52:55], v[140:143], v[204:207], v[52:55]
	v_mfma_f32_16x16x32_bf16 v[52:55], v[136:139], v[200:203], v[52:55]
	v_mfma_f32_16x16x32_bf16 v[36:39], v[136:139], v[230:233], v[36:39]
	v_mfma_f32_16x16x32_bf16 v[36:39], v[140:143], v[234:237], v[36:39]
	v_mfma_f32_16x16x32_bf16 v[20:23], v[140:143], v[242:245], v[20:23]
	v_mfma_f32_16x16x32_bf16 v[20:23], v[136:139], v[238:241], v[20:23]
	v_mfma_f32_16x16x32_bf16 v[16:19], v[144:147], v[238:241], v[16:19]
	v_mfma_f32_16x16x32_bf16 v[16:19], v[148:151], v[242:245], v[16:19]
	v_mfma_f32_16x16x32_bf16 v[32:35], v[148:151], v[234:237], v[32:35]
	v_mfma_f32_16x16x32_bf16 v[32:35], v[144:147], v[230:233], v[32:35]
	v_mfma_f32_16x16x32_bf16 v[48:51], v[144:147], v[200:203], v[48:51]
	v_mfma_f32_16x16x32_bf16 v[48:51], v[148:151], v[204:207], v[48:51]
	v_mfma_f32_16x16x32_bf16 v[64:67], v[148:151], v[196:199], v[64:67]
	v_mfma_f32_16x16x32_bf16 v[64:67], v[144:147], v[192:195], v[64:67]
	s_setprio 0
	s_setprio 1
	v_mfma_f32_16x16x32_bf16 v[60:63], v[172:175], v[192:195], v[60:63]
	v_mfma_f32_16x16x32_bf16 v[60:63], v[176:179], v[196:199], v[60:63]
	v_mfma_f32_16x16x32_bf16 v[44:47], v[176:179], v[204:207], v[44:47]
	v_mfma_f32_16x16x32_bf16 v[44:47], v[172:175], v[200:203], v[44:47]
	v_mfma_f32_16x16x32_bf16 v[28:31], v[172:175], v[230:233], v[28:31]
	v_mfma_f32_16x16x32_bf16 v[28:31], v[176:179], v[234:237], v[28:31]
	v_mfma_f32_16x16x32_bf16 v[12:15], v[176:179], v[242:245], v[12:15]
	v_mfma_f32_16x16x32_bf16 v[12:15], v[172:175], v[238:241], v[12:15]
	v_mfma_f32_16x16x32_bf16 v[8:11], v[184:187], v[238:241], v[8:11]
	v_mfma_f32_16x16x32_bf16 v[8:11], v[188:191], v[242:245], v[8:11]
	v_mfma_f32_16x16x32_bf16 v[24:27], v[188:191], v[234:237], v[24:27]
	v_mfma_f32_16x16x32_bf16 v[24:27], v[184:187], v[230:233], v[24:27]
	v_mfma_f32_16x16x32_bf16 v[40:43], v[184:187], v[200:203], v[40:43]
	v_mfma_f32_16x16x32_bf16 v[40:43], v[188:191], v[204:207], v[40:43]
	v_mfma_f32_16x16x32_bf16 v[56:59], v[188:191], v[196:199], v[56:59]
	v_mfma_f32_16x16x32_bf16 v[56:59], v[184:187], v[192:195], v[56:59]
	s_setprio 0
	s_barrier
	s_add_i32 s79, 0, 0x1c000
	v_add_u32_e32 v148, s91, v162
	v_add_u32_e32 v171, s79, v162
	ds_read_b128 v[136:139], v148
	ds_read_b128 v[140:143], v148 offset:1024
	ds_read_b128 v[144:147], v148 offset:2048
	ds_read_b128 v[148:151], v148 offset:3072
	ds_read_b128 v[172:175], v171
	ds_read_b128 v[176:179], v171 offset:1024
	ds_read_b128 v[184:187], v171 offset:2048
	ds_read_b128 v[188:191], v171 offset:3072
	s_add_u32 s38, s38, s48
	s_addc_u32 s39, s39, s49
	s_mov_b32 m0, s52
	v_lshl_add_u64 v[248:249], s[38:39], 0, v[156:157]
	ds_read_b128 v[192:195], v167 offset:32768
	ds_read_b128 v[196:199], v167 offset:33792
	ds_read_b128 v[200:203], v167 offset:34816
	ds_read_b128 v[204:207], v167 offset:35840
	ds_read_b128 v[230:233], v167 offset:36864
	ds_read_b128 v[234:237], v167 offset:37888
	ds_read_b128 v[238:241], v167 offset:38912
	ds_read_b128 v[242:245], v167 offset:39936
	global_load_lds_dwordx4 v[248:249], off
	v_lshl_add_u64 v[248:249], s[38:39], 0, v[152:153]
	s_mov_b32 m0, s53
	s_nop 0
	global_load_lds_dwordx4 v[248:249], off
	s_waitcnt vmcnt(8)
	s_waitcnt lgkmcnt(0)
	s_barrier
	s_setprio 1
	s_waitcnt lgkmcnt(0)
	v_mfma_f32_16x16x32_bf16 v[132:135], v[136:139], v[192:195], v[132:135]
	v_mfma_f32_16x16x32_bf16 v[132:135], v[140:143], v[196:199], v[132:135]
	v_mfma_f32_16x16x32_bf16 v[116:119], v[140:143], v[204:207], v[116:119]
	v_mfma_f32_16x16x32_bf16 v[116:119], v[136:139], v[200:203], v[116:119]
	v_mfma_f32_16x16x32_bf16 v[100:103], v[136:139], v[230:233], v[100:103]
	v_mfma_f32_16x16x32_bf16 v[100:103], v[140:143], v[234:237], v[100:103]
	v_mfma_f32_16x16x32_bf16 v[84:87], v[140:143], v[242:245], v[84:87]
	v_mfma_f32_16x16x32_bf16 v[84:87], v[136:139], v[238:241], v[84:87]
	v_mfma_f32_16x16x32_bf16 v[80:83], v[144:147], v[238:241], v[80:83]
	v_mfma_f32_16x16x32_bf16 v[80:83], v[148:151], v[242:245], v[80:83]
	v_mfma_f32_16x16x32_bf16 v[96:99], v[148:151], v[234:237], v[96:99]
	v_mfma_f32_16x16x32_bf16 v[96:99], v[144:147], v[230:233], v[96:99]
	v_mfma_f32_16x16x32_bf16 v[112:115], v[144:147], v[200:203], v[112:115]
	v_mfma_f32_16x16x32_bf16 v[112:115], v[148:151], v[204:207], v[112:115]
	v_mfma_f32_16x16x32_bf16 v[128:131], v[148:151], v[196:199], v[128:131]
	v_mfma_f32_16x16x32_bf16 v[128:131], v[144:147], v[192:195], v[128:131]
	s_setprio 0
	s_setprio 1
	v_mfma_f32_16x16x32_bf16 v[124:127], v[172:175], v[192:195], v[124:127]
	v_mfma_f32_16x16x32_bf16 v[124:127], v[176:179], v[196:199], v[124:127]
	v_mfma_f32_16x16x32_bf16 v[108:111], v[176:179], v[204:207], v[108:111]
	v_mfma_f32_16x16x32_bf16 v[108:111], v[172:175], v[200:203], v[108:111]
	v_mfma_f32_16x16x32_bf16 v[92:95], v[172:175], v[230:233], v[92:95]
	v_mfma_f32_16x16x32_bf16 v[92:95], v[176:179], v[234:237], v[92:95]
	v_mfma_f32_16x16x32_bf16 v[76:79], v[176:179], v[242:245], v[76:79]
	v_mfma_f32_16x16x32_bf16 v[76:79], v[172:175], v[238:241], v[76:79]
	v_mfma_f32_16x16x32_bf16 v[72:75], v[184:187], v[238:241], v[72:75]
	v_mfma_f32_16x16x32_bf16 v[72:75], v[188:191], v[242:245], v[72:75]
	v_mfma_f32_16x16x32_bf16 v[88:91], v[188:191], v[234:237], v[88:91]
	v_mfma_f32_16x16x32_bf16 v[88:91], v[184:187], v[230:233], v[88:91]
	v_mfma_f32_16x16x32_bf16 v[104:107], v[184:187], v[200:203], v[104:107]
	v_mfma_f32_16x16x32_bf16 v[104:107], v[188:191], v[204:207], v[104:107]
	v_mfma_f32_16x16x32_bf16 v[120:123], v[188:191], v[196:199], v[120:123]
	v_mfma_f32_16x16x32_bf16 v[120:123], v[184:187], v[192:195], v[120:123]
	s_setprio 0
	s_barrier
; #define PG8_STAGE(bufoff, gbase, voff) do { _Pragma("unroll") for (int _i = 0; _i < 2; ++_i) \
;         __builtin_amdgcn_global_load_lds((const unsigned*)((const char*)(gbase) + (voff)[_i]), (PG8_LAS unsigned*)(lds + (bufoff) + ldsw + _i * 8192), 16, 0, 0); } while (0)
; #define PG8_LDA(dst, b, h) do { _Pragma("unroll") for (int m = 0; m < 4; ++m) _Pragma("unroll") for (int k = 0; k < 2; ++k) dst[m][k] = *(const PG8_LAS bf16x8*)(lds + PG8_SA(b, h) + aoff + m * 2048 + k * 1024); } while (0)
; #define PG8_MMA(ai, bj, At, Bt) do { __builtin_amdgcn_s_setprio(1); _Pragma("unroll") for (int m = 0; m < 4; ++m) _Pragma("unroll") for (int n = 0; n < 2; ++n) _Pragma("unroll") for (int k = 0; k < 2; ++k) \
;         acc[ai][bj][m][n] = __builtin_amdgcn_mfma_f32_16x16x32_bf16(Bt[n][k], At[m][k], acc[ai][bj][m][n], 0, 0, 0); __builtin_amdgcn_s_setprio(0); } while (0)
; #define PG8_WAIT_V(n) asm volatile("s_waitcnt vmcnt(" #n ")" ::: "memory")
; #define PG8_WAIT_L(n) asm volatile("s_waitcnt lgkmcnt(" #n ")" ::: "memory")
; #define PG8_BAR __builtin_amdgcn_s_barrier()
; #define PG8_SCHED __builtin_amdgcn_sched_barrier(0)
; template <class Epi, class Sched, bool ALIGN_EPI = false, bool SP2 = false>
; __device__ __forceinline__ void gemm_phase(PG8_LAS unsigned char* lds, const Gemm g, const Sched& S, const Epi& E) {
;     ...
;             PG8_LDA(At, 1, 1); PG8_STAGE(PG8_SB(1, 0), b3, voffB); PG8_STAGE(PG8_SB(1, 1), b3 + hstep, voffB); PG8_STAGE(PG8_SA(1, 0), a3, voffA);
;             PG8_WAIT_V(8); PG8_WAIT_L(0); PG8_BAR; PG8_MMA(1, 0, At, B0); PG8_MMA(1, 1, At, B1); PG8_BAR; PG8_SCHED;
	s_add_i32 s38, s91, s42
	v_lshl_add_u64 v[180:181], v[180:181], 0, s[24:25]
	s_mov_b32 m0, s38
	ds_read_b128 v[192:195], v167 offset:49152
	ds_read_b128 v[196:199], v167 offset:50176
	ds_read_b128 v[200:203], v167 offset:51200
	ds_read_b128 v[204:207], v167 offset:52224
	ds_read_b128 v[230:233], v167 offset:53248
	ds_read_b128 v[234:237], v167 offset:54272
	ds_read_b128 v[238:241], v167 offset:55296
	ds_read_b128 v[242:245], v167 offset:56320
	global_load_lds_dwordx4 v[180:181], off
	v_lshl_add_u64 v[180:181], v[208:209], 0, s[24:25]
	s_add_i32 m0, s38, 0x2000
	s_add_i32 s38, s79, s42
	global_load_lds_dwordx4 v[180:181], off
	v_lshl_add_u64 v[180:181], v[216:217], 0, s[24:25]
	s_mov_b32 m0, s38
	s_nop 0
	global_load_lds_dwordx4 v[180:181], off
	v_lshl_add_u64 v[180:181], v[224:225], 0, s[24:25]
	s_add_i32 m0, s38, 0x2000
	s_nop 0
	global_load_lds_dwordx4 v[180:181], off
	v_lshl_add_u64 v[180:181], v[226:227], 0, s[24:25]
	s_mov_b32 m0, s72
	s_nop 0
	global_load_lds_dwordx4 v[180:181], off
	v_lshl_add_u64 v[180:181], v[246:247], 0, s[24:25]
	s_mov_b32 m0, s73
	s_nop 0
	global_load_lds_dwordx4 v[180:181], off
	s_waitcnt vmcnt(8)
	s_waitcnt lgkmcnt(0)
	s_barrier
	s_setprio 1
	s_waitcnt lgkmcnt(0)
	v_mfma_f32_16x16x32_bf16 v[68:71], v[136:139], v[192:195], v[68:71]
	v_mfma_f32_16x16x32_bf16 v[68:71], v[140:143], v[196:199], v[68:71]
	v_mfma_f32_16x16x32_bf16 v[52:55], v[140:143], v[204:207], v[52:55]
	v_mfma_f32_16x16x32_bf16 v[52:55], v[136:139], v[200:203], v[52:55]
	v_mfma_f32_16x16x32_bf16 v[36:39], v[136:139], v[230:233], v[36:39]
	v_mfma_f32_16x16x32_bf16 v[36:39], v[140:143], v[234:237], v[36:39]
	v_mfma_f32_16x16x32_bf16 v[20:23], v[140:143], v[242:245], v[20:23]
	v_mfma_f32_16x16x32_bf16 v[20:23], v[136:139], v[238:241], v[20:23]
	v_mfma_f32_16x16x32_bf16 v[16:19], v[144:147], v[238:241], v[16:19]
	v_mfma_f32_16x16x32_bf16 v[16:19], v[148:151], v[242:245], v[16:19]
	v_mfma_f32_16x16x32_bf16 v[32:35], v[148:151], v[234:237], v[32:35]
	v_mfma_f32_16x16x32_bf16 v[32:35], v[144:147], v[230:233], v[32:35]
	v_mfma_f32_16x16x32_bf16 v[48:51], v[144:147], v[200:203], v[48:51]
	v_mfma_f32_16x16x32_bf16 v[48:51], v[148:151], v[204:207], v[48:51]
	v_mfma_f32_16x16x32_bf16 v[64:67], v[148:151], v[196:199], v[64:67]
	v_mfma_f32_16x16x32_bf16 v[64:67], v[144:147], v[192:195], v[64:67]
	s_setprio 0
	s_setprio 1
	v_mfma_f32_16x16x32_bf16 v[60:63], v[172:175], v[192:195], v[60:63]
	v_mfma_f32_16x16x32_bf16 v[60:63], v[176:179], v[196:199], v[60:63]
	v_mfma_f32_16x16x32_bf16 v[44:47], v[176:179], v[204:207], v[44:47]
	v_mfma_f32_16x16x32_bf16 v[44:47], v[172:175], v[200:203], v[44:47]
	v_mfma_f32_16x16x32_bf16 v[28:31], v[172:175], v[230:233], v[28:31]
	v_mfma_f32_16x16x32_bf16 v[28:31], v[176:179], v[234:237], v[28:31]
	v_mfma_f32_16x16x32_bf16 v[12:15], v[176:179], v[242:245], v[12:15]
	v_mfma_f32_16x16x32_bf16 v[12:15], v[172:175], v[238:241], v[12:15]
	v_mfma_f32_16x16x32_bf16 v[8:11], v[184:187], v[238:241], v[8:11]
	v_mfma_f32_16x16x32_bf16 v[8:11], v[188:191], v[242:245], v[8:11]
	v_mfma_f32_16x16x32_bf16 v[24:27], v[188:191], v[234:237], v[24:27]
	v_mfma_f32_16x16x32_bf16 v[24:27], v[184:187], v[230:233], v[24:27]
	v_mfma_f32_16x16x32_bf16 v[40:43], v[184:187], v[200:203], v[40:43]
	v_mfma_f32_16x16x32_bf16 v[40:43], v[188:191], v[204:207], v[40:43]
	v_mfma_f32_16x16x32_bf16 v[56:59], v[188:191], v[196:199], v[56:59]
	v_mfma_f32_16x16x32_bf16 v[56:59], v[184:187], v[192:195], v[56:59]
	s_setprio 0
	s_barrier
	s_add_u32 s0, s0, 0x100
	s_addc_u32 s1, s1, 0
	s_add_u32 s40, s40, 0x100
	s_addc_u32 s41, s41, 0
	s_cmp_ge_u32 s78, s9
	s_mov_b32 s38, s78
	s_cbranch_scc0 .LBB0_468

; #define PG8_STAGE(bufoff, gbase, voff) do { _Pragma("unroll") for (int _i = 0; _i < 2; ++_i) \
;         __builtin_amdgcn_global_load_lds((const unsigned*)((const char*)(gbase) + (voff)[_i]), (PG8_LAS unsigned*)(lds + (bufoff) + ldsw + _i * 8192), 16, 0, 0); } while (0)
; #define PG8_LDA(dst, b, h) do { _Pragma("unroll") for (int m = 0; m < 4; ++m) _Pragma("unroll") for (int k = 0; k < 2; ++k) dst[m][k] = *(const PG8_LAS bf16x8*)(lds + PG8_SA(b, h) + aoff + m * 2048 + k * 1024); } while (0)
; #define PG8_LDB(dst, b, h) do { _Pragma("unroll") for (int n = 0; n < 2; ++n) _Pragma("unroll") for (int k = 0; k < 2; ++k) dst[n][k] = *(const PG8_LAS bf16x8*)(lds + PG8_SB(b, h) + boff + n * 2048 + k * 1024); } while (0)
; #define PG8_MMA(ai, bj, At, Bt) do { __builtin_amdgcn_s_setprio(1); _Pragma("unroll") for (int m = 0; m < 4; ++m) _Pragma("unroll") for (int n = 0; n < 2; ++n) _Pragma("unroll") for (int k = 0; k < 2; ++k) \
;         acc[ai][bj][m][n] = __builtin_amdgcn_mfma_f32_16x16x32_bf16(Bt[n][k], At[m][k], acc[ai][bj][m][n], 0, 0, 0); __builtin_amdgcn_s_setprio(0); } while (0)
; #define PG8_WAIT_V(n) asm volatile("s_waitcnt vmcnt(" #n ")" ::: "memory")
; #define PG8_WAIT_L(n) asm volatile("s_waitcnt lgkmcnt(" #n ")" ::: "memory")
; template <class Epi, class Sched, bool ALIGN_EPI = false, bool SP2 = false>
; __device__ __forceinline__ void gemm_phase(PG8_LAS unsigned char* lds, const Gemm g, const Sched& S, const Epi& E) {
;     ...
;             const bool last = (t == nt - 2);
;             const char* a1 = cA + (size_t)(t + 1) * kstep;
;             const char* a2 = last ? nA : cA + (size_t)(t + 2) * kstep; const char* b2 = last ? nB : cB + (size_t)(t + 2) * kstep;
;             const char* a3 = a2 + kstep; const char* b3 = b2 + kstep;
;             if (last && has_next) S.a_ready(nxt);
;             if constexpr (SP2) {
;             PG8_LDB(B0, 0, 0); PG8_LDB(B1, 0, 1); PG8_SCHED; PG8_LDA(At, 0, 0); PG8_STAGE(PG8_SA(1, 1), a1 + hstep, voffA);
;             PG8_WAIT_V(8); PG8_WAIT_L(0); PG8_BAR; PG8_MMA(0, 0, At, B0); PG8_MMA(0, 1, At, B1); PG8_BAR; PG8_SCHED;
;             PG8_LDA(At, 0, 1); PG8_STAGE(PG8_SB(0, 0), b2, voffB); PG8_STAGE(PG8_SB(0, 1), b2 + hstep, voffB); PG8_STAGE(PG8_SA(0, 0), a2, voffA);
;             PG8_WAIT_V(8); PG8_WAIT_L(0); PG8_BAR; PG8_MMA(1, 0, At, B0); PG8_MMA(1, 1, At, B1); PG8_BAR; PG8_SCHED;
.LBB0_501:
	s_add_i32 s80, s4, 2
	s_add_u32 s81, s0, 0x80
	s_addc_u32 s5, s1, 0
	s_cmp_eq_u32 s33, s4
	s_cselect_b32 s5, s23, s5
	s_cselect_b32 s4, s22, s81
	s_cselect_b32 s83, s41, s43
	s_cselect_b32 s82, s40, s42
	s_add_i32 s81, 0, 0x14000
	v_add_u32_e32 v148, s19, v164
	v_add_u32_e32 v162, s81, v164
	ds_read_b128 v[136:139], v148
	ds_read_b128 v[140:143], v148 offset:1024
	ds_read_b128 v[144:147], v148 offset:2048
	ds_read_b128 v[148:151], v148 offset:3072
	ds_read_b128 v[174:177], v162
	ds_read_b128 v[178:181], v162 offset:1024
	ds_read_b128 v[184:187], v162 offset:2048
	ds_read_b128 v[188:191], v162 offset:3072
	v_lshl_add_u64 v[162:163], s[0:1], 0, v[158:159]
	s_add_i32 m0, s45, 0xc000
	ds_read_b128 v[192:195], v170
	ds_read_b128 v[196:199], v170 offset:1024
	ds_read_b128 v[200:203], v170 offset:2048
	ds_read_b128 v[204:207], v170 offset:3072
	ds_read_b128 v[230:233], v170 offset:4096
	ds_read_b128 v[234:237], v170 offset:5120
	ds_read_b128 v[238:241], v170 offset:6144
	ds_read_b128 v[242:245], v170 offset:7168
	global_load_lds_dwordx4 v[162:163], off
	v_lshl_add_u64 v[162:163], s[0:1], 0, v[160:161]
	s_add_i32 m0, s45, 0xe000
	s_nop 0
	global_load_lds_dwordx4 v[162:163], off
	s_waitcnt vmcnt(8)
	s_waitcnt lgkmcnt(0)
	s_barrier
	s_setprio 1
	s_waitcnt lgkmcnt(0)
	v_mfma_f32_16x16x32_bf16 v[132:135], v[136:139], v[192:195], v[132:135]
	v_mfma_f32_16x16x32_bf16 v[132:135], v[140:143], v[196:199], v[132:135]
	v_mfma_f32_16x16x32_bf16 v[116:119], v[140:143], v[204:207], v[116:119]
	v_mfma_f32_16x16x32_bf16 v[116:119], v[136:139], v[200:203], v[116:119]
	v_mfma_f32_16x16x32_bf16 v[100:103], v[136:139], v[230:233], v[100:103]
	v_mfma_f32_16x16x32_bf16 v[100:103], v[140:143], v[234:237], v[100:103]
	v_mfma_f32_16x16x32_bf16 v[84:87], v[140:143], v[242:245], v[84:87]
	v_mfma_f32_16x16x32_bf16 v[84:87], v[136:139], v[238:241], v[84:87]
	v_mfma_f32_16x16x32_bf16 v[80:83], v[144:147], v[238:241], v[80:83]
	v_mfma_f32_16x16x32_bf16 v[80:83], v[148:151], v[242:245], v[80:83]
	v_mfma_f32_16x16x32_bf16 v[96:99], v[148:151], v[234:237], v[96:99]
	v_mfma_f32_16x16x32_bf16 v[96:99], v[144:147], v[230:233], v[96:99]
	v_mfma_f32_16x16x32_bf16 v[112:115], v[144:147], v[200:203], v[112:115]
	v_mfma_f32_16x16x32_bf16 v[112:115], v[148:151], v[204:207], v[112:115]
	v_mfma_f32_16x16x32_bf16 v[128:131], v[148:151], v[196:199], v[128:131]
	v_mfma_f32_16x16x32_bf16 v[128:131], v[144:147], v[192:195], v[128:131]
	s_setprio 0
	s_setprio 1
	v_mfma_f32_16x16x32_bf16 v[124:127], v[174:177], v[192:195], v[124:127]
	v_mfma_f32_16x16x32_bf16 v[124:127], v[178:181], v[196:199], v[124:127]
	v_mfma_f32_16x16x32_bf16 v[108:111], v[178:181], v[204:207], v[108:111]
	v_mfma_f32_16x16x32_bf16 v[108:111], v[174:177], v[200:203], v[108:111]
	v_mfma_f32_16x16x32_bf16 v[92:95], v[174:177], v[230:233], v[92:95]
	v_mfma_f32_16x16x32_bf16 v[92:95], v[178:181], v[234:237], v[92:95]
	v_mfma_f32_16x16x32_bf16 v[76:79], v[178:181], v[242:245], v[76:79]
	v_mfma_f32_16x16x32_bf16 v[76:79], v[174:177], v[238:241], v[76:79]
	v_mfma_f32_16x16x32_bf16 v[72:75], v[184:187], v[238:241], v[72:75]
	v_mfma_f32_16x16x32_bf16 v[72:75], v[188:191], v[242:245], v[72:75]
	v_mfma_f32_16x16x32_bf16 v[88:91], v[188:191], v[234:237], v[88:91]
	v_mfma_f32_16x16x32_bf16 v[88:91], v[184:187], v[230:233], v[88:91]
	v_mfma_f32_16x16x32_bf16 v[104:107], v[184:187], v[200:203], v[104:107]
	v_mfma_f32_16x16x32_bf16 v[104:107], v[188:191], v[204:207], v[104:107]
	v_mfma_f32_16x16x32_bf16 v[120:123], v[188:191], v[196:199], v[120:123]
	v_mfma_f32_16x16x32_bf16 v[120:123], v[184:187], v[192:195], v[120:123]
	s_setprio 0
	s_barrier
	s_add_i32 s84, s19, s44
	v_lshl_add_u64 v[162:163], s[82:83], 0, v[152:153]
	s_mov_b32 m0, s84
	ds_read_b128 v[192:195], v170 offset:16384
	ds_read_b128 v[196:199], v170 offset:17408
	ds_read_b128 v[200:203], v170 offset:18432
	ds_read_b128 v[204:207], v170 offset:19456
	ds_read_b128 v[230:233], v170 offset:20480
	ds_read_b128 v[234:237], v170 offset:21504
	ds_read_b128 v[238:241], v170 offset:22528
	ds_read_b128 v[242:245], v170 offset:23552
	global_load_lds_dwordx4 v[162:163], off
	s_add_i32 m0, s84, 0x2000
	v_lshl_add_u64 v[208:209], s[82:83], 0, v[156:157]
	s_add_u32 s82, s82, s48
	s_addc_u32 s83, s83, s49
	s_add_i32 s81, s81, s44
	global_load_lds_dwordx4 v[208:209], off
	v_lshl_add_u64 v[246:247], s[82:83], 0, v[152:153]
	s_mov_b32 m0, s81
	v_lshl_add_u64 v[248:249], s[82:83], 0, v[156:157]
	global_load_lds_dwordx4 v[246:247], off
	s_add_i32 m0, s81, 0x2000
	v_lshl_add_u64 v[216:217], s[4:5], 0, v[2:3]
	global_load_lds_dwordx4 v[248:249], off
	s_mov_b32 m0, s45
	v_lshl_add_u64 v[224:225], s[4:5], 0, v[154:155]
	global_load_lds_dwordx4 v[216:217], off
	s_mov_b32 m0, s46
	s_nop 0
	global_load_lds_dwordx4 v[224:225], off
	s_waitcnt vmcnt(8)
	s_waitcnt lgkmcnt(0)
	s_barrier
; #define PG8_STAGE(bufoff, gbase, voff) do { _Pragma("unroll") for (int _i = 0; _i < 2; ++_i) \
;         __builtin_amdgcn_global_load_lds((const unsigned*)((const char*)(gbase) + (voff)[_i]), (PG8_LAS unsigned*)(lds + (bufoff) + ldsw + _i * 8192), 16, 0, 0); } while (0)
; #define PG8_LDA(dst, b, h) do { _Pragma("unroll") for (int m = 0; m < 4; ++m) _Pragma("unroll") for (int k = 0; k < 2; ++k) dst[m][k] = *(const PG8_LAS bf16x8*)(lds + PG8_SA(b, h) + aoff + m * 2048 + k * 1024); } while (0)
; #define PG8_LDB(dst, b, h) do { _Pragma("unroll") for (int n = 0; n < 2; ++n) _Pragma("unroll") for (int k = 0; k < 2; ++k) dst[n][k] = *(const PG8_LAS bf16x8*)(lds + PG8_SB(b, h) + boff + n * 2048 + k * 1024); } while (0)
; #define PG8_MMA(ai, bj, At, Bt) do { __builtin_amdgcn_s_setprio(1); _Pragma("unroll") for (int m = 0; m < 4; ++m) _Pragma("unroll") for (int n = 0; n < 2; ++n) _Pragma("unroll") for (int k = 0; k < 2; ++k) \
;         acc[ai][bj][m][n] = __builtin_amdgcn_mfma_f32_16x16x32_bf16(Bt[n][k], At[m][k], acc[ai][bj][m][n], 0, 0, 0); __builtin_amdgcn_s_setprio(0); } while (0)
; #define PG8_WAIT_V(n) asm volatile("s_waitcnt vmcnt(" #n ")" ::: "memory")
; #define PG8_WAIT_L(n) asm volatile("s_waitcnt lgkmcnt(" #n ")" ::: "memory")
; #define PG8_BAR __builtin_amdgcn_s_barrier()
; #define PG8_SCHED __builtin_amdgcn_sched_barrier(0)
; template <class Epi, class Sched, bool ALIGN_EPI = false, bool SP2 = false>
; __device__ __forceinline__ void gemm_phase(PG8_LAS unsigned char* lds, const Gemm g, const Sched& S, const Epi& E) {
;     ...
;             PG8_WAIT_V(8); PG8_WAIT_L(0); PG8_BAR; PG8_MMA(1, 0, At, B0); PG8_MMA(1, 1, At, B1); PG8_BAR; PG8_SCHED;
;             PG8_LDB(B0, 1, 0); PG8_LDB(B1, 1, 1); PG8_SCHED; PG8_LDA(At, 1, 0); PG8_STAGE(PG8_SA(0, 1), a2 + hstep, voffA);
;             PG8_WAIT_V(8); PG8_WAIT_L(0); PG8_BAR; PG8_MMA(0, 0, At, B0); PG8_MMA(0, 1, At, B1); PG8_BAR; PG8_SCHED;
	s_setprio 1
	s_waitcnt lgkmcnt(0)
	v_mfma_f32_16x16x32_bf16 v[68:71], v[136:139], v[192:195], v[68:71]
	v_mfma_f32_16x16x32_bf16 v[68:71], v[140:143], v[196:199], v[68:71]
	v_mfma_f32_16x16x32_bf16 v[52:55], v[140:143], v[204:207], v[52:55]
	v_mfma_f32_16x16x32_bf16 v[52:55], v[136:139], v[200:203], v[52:55]
	v_mfma_f32_16x16x32_bf16 v[36:39], v[136:139], v[230:233], v[36:39]
	v_mfma_f32_16x16x32_bf16 v[36:39], v[140:143], v[234:237], v[36:39]
	v_mfma_f32_16x16x32_bf16 v[20:23], v[140:143], v[242:245], v[20:23]
	v_mfma_f32_16x16x32_bf16 v[20:23], v[136:139], v[238:241], v[20:23]
	v_mfma_f32_16x16x32_bf16 v[16:19], v[144:147], v[238:241], v[16:19]
	v_mfma_f32_16x16x32_bf16 v[16:19], v[148:151], v[242:245], v[16:19]
	v_mfma_f32_16x16x32_bf16 v[32:35], v[148:151], v[234:237], v[32:35]
	v_mfma_f32_16x16x32_bf16 v[32:35], v[144:147], v[230:233], v[32:35]
	v_mfma_f32_16x16x32_bf16 v[48:51], v[144:147], v[200:203], v[48:51]
	v_mfma_f32_16x16x32_bf16 v[48:51], v[148:151], v[204:207], v[48:51]
	v_mfma_f32_16x16x32_bf16 v[64:67], v[148:151], v[196:199], v[64:67]
	v_mfma_f32_16x16x32_bf16 v[64:67], v[144:147], v[192:195], v[64:67]
	s_setprio 0
	s_setprio 1
	v_mfma_f32_16x16x32_bf16 v[60:63], v[174:177], v[192:195], v[60:63]
	v_mfma_f32_16x16x32_bf16 v[60:63], v[178:181], v[196:199], v[60:63]
	v_mfma_f32_16x16x32_bf16 v[44:47], v[178:181], v[204:207], v[44:47]
	v_mfma_f32_16x16x32_bf16 v[44:47], v[174:177], v[200:203], v[44:47]
	v_mfma_f32_16x16x32_bf16 v[28:31], v[174:177], v[230:233], v[28:31]
	v_mfma_f32_16x16x32_bf16 v[28:31], v[178:181], v[234:237], v[28:31]
	v_mfma_f32_16x16x32_bf16 v[12:15], v[178:181], v[242:245], v[12:15]
	v_mfma_f32_16x16x32_bf16 v[12:15], v[174:177], v[238:241], v[12:15]
	v_mfma_f32_16x16x32_bf16 v[8:11], v[184:187], v[238:241], v[8:11]
	v_mfma_f32_16x16x32_bf16 v[8:11], v[188:191], v[242:245], v[8:11]
	v_mfma_f32_16x16x32_bf16 v[24:27], v[188:191], v[234:237], v[24:27]
	v_mfma_f32_16x16x32_bf16 v[24:27], v[184:187], v[230:233], v[24:27]
	v_mfma_f32_16x16x32_bf16 v[40:43], v[184:187], v[200:203], v[40:43]
	v_mfma_f32_16x16x32_bf16 v[40:43], v[188:191], v[204:207], v[40:43]
	v_mfma_f32_16x16x32_bf16 v[56:59], v[188:191], v[196:199], v[56:59]
	v_mfma_f32_16x16x32_bf16 v[56:59], v[184:187], v[192:195], v[56:59]
	s_setprio 0
	s_barrier
	s_add_i32 s81, 0, 0x1c000
	v_add_u32_e32 v148, s91, v164
	v_add_u32_e32 v173, s81, v164
	ds_read_b128 v[136:139], v148
	ds_read_b128 v[140:143], v148 offset:1024
	ds_read_b128 v[144:147], v148 offset:2048
	ds_read_b128 v[148:151], v148 offset:3072
	ds_read_b128 v[174:177], v173
	ds_read_b128 v[178:181], v173 offset:1024
	ds_read_b128 v[184:187], v173 offset:2048
	ds_read_b128 v[188:191], v173 offset:3072
	s_add_u32 s4, s4, s48
	s_addc_u32 s5, s5, s49
	s_mov_b32 m0, s47
	v_lshl_add_u64 v[226:227], s[4:5], 0, v[2:3]
	ds_read_b128 v[192:195], v170 offset:32768
	ds_read_b128 v[196:199], v170 offset:33792
	ds_read_b128 v[200:203], v170 offset:34816
	ds_read_b128 v[204:207], v170 offset:35840
	ds_read_b128 v[230:233], v170 offset:36864
	ds_read_b128 v[234:237], v170 offset:37888
	ds_read_b128 v[238:241], v170 offset:38912
	ds_read_b128 v[242:245], v170 offset:39936
	global_load_lds_dwordx4 v[226:227], off
	v_lshl_add_u64 v[226:227], s[4:5], 0, v[154:155]
	s_mov_b32 m0, s52
	s_nop 0
	global_load_lds_dwordx4 v[226:227], off
	s_waitcnt vmcnt(8)
	s_waitcnt lgkmcnt(0)
	s_barrier
	s_setprio 1
	s_waitcnt lgkmcnt(0)
	v_mfma_f32_16x16x32_bf16 v[132:135], v[136:139], v[192:195], v[132:135]
	v_mfma_f32_16x16x32_bf16 v[132:135], v[140:143], v[196:199], v[132:135]
	v_mfma_f32_16x16x32_bf16 v[116:119], v[140:143], v[204:207], v[116:119]
	v_mfma_f32_16x16x32_bf16 v[116:119], v[136:139], v[200:203], v[116:119]
	v_mfma_f32_16x16x32_bf16 v[100:103], v[136:139], v[230:233], v[100:103]
	v_mfma_f32_16x16x32_bf16 v[100:103], v[140:143], v[234:237], v[100:103]
	v_mfma_f32_16x16x32_bf16 v[84:87], v[140:143], v[242:245], v[84:87]
	v_mfma_f32_16x16x32_bf16 v[84:87], v[136:139], v[238:241], v[84:87]
	v_mfma_f32_16x16x32_bf16 v[80:83], v[144:147], v[238:241], v[80:83]
	v_mfma_f32_16x16x32_bf16 v[80:83], v[148:151], v[242:245], v[80:83]
	v_mfma_f32_16x16x32_bf16 v[96:99], v[148:151], v[234:237], v[96:99]
	v_mfma_f32_16x16x32_bf16 v[96:99], v[144:147], v[230:233], v[96:99]
	v_mfma_f32_16x16x32_bf16 v[112:115], v[144:147], v[200:203], v[112:115]
	v_mfma_f32_16x16x32_bf16 v[112:115], v[148:151], v[204:207], v[112:115]
	v_mfma_f32_16x16x32_bf16 v[128:131], v[148:151], v[196:199], v[128:131]
	v_mfma_f32_16x16x32_bf16 v[128:131], v[144:147], v[192:195], v[128:131]
	s_setprio 0
	s_setprio 1
	v_mfma_f32_16x16x32_bf16 v[124:127], v[174:177], v[192:195], v[124:127]
	v_mfma_f32_16x16x32_bf16 v[124:127], v[178:181], v[196:199], v[124:127]
	v_mfma_f32_16x16x32_bf16 v[108:111], v[178:181], v[204:207], v[108:111]
	v_mfma_f32_16x16x32_bf16 v[108:111], v[174:177], v[200:203], v[108:111]
	v_mfma_f32_16x16x32_bf16 v[92:95], v[174:177], v[230:233], v[92:95]
	v_mfma_f32_16x16x32_bf16 v[92:95], v[178:181], v[234:237], v[92:95]
	v_mfma_f32_16x16x32_bf16 v[76:79], v[178:181], v[242:245], v[76:79]
	v_mfma_f32_16x16x32_bf16 v[76:79], v[174:177], v[238:241], v[76:79]
	v_mfma_f32_16x16x32_bf16 v[72:75], v[184:187], v[238:241], v[72:75]
	v_mfma_f32_16x16x32_bf16 v[72:75], v[188:191], v[242:245], v[72:75]
	v_mfma_f32_16x16x32_bf16 v[88:91], v[188:191], v[234:237], v[88:91]
	v_mfma_f32_16x16x32_bf16 v[88:91], v[184:187], v[230:233], v[88:91]
	v_mfma_f32_16x16x32_bf16 v[104:107], v[184:187], v[200:203], v[104:107]
	v_mfma_f32_16x16x32_bf16 v[104:107], v[188:191], v[204:207], v[104:107]
	v_mfma_f32_16x16x32_bf16 v[120:123], v[188:191], v[196:199], v[120:123]
	v_mfma_f32_16x16x32_bf16 v[120:123], v[184:187], v[192:195], v[120:123]
	s_setprio 0
	s_barrier
; #define PG8_STAGE(bufoff, gbase, voff) do { _Pragma("unroll") for (int _i = 0; _i < 2; ++_i) \
;         __builtin_amdgcn_global_load_lds((const unsigned*)((const char*)(gbase) + (voff)[_i]), (PG8_LAS unsigned*)(lds + (bufoff) + ldsw + _i * 8192), 16, 0, 0); } while (0)
; #define PG8_LDA(dst, b, h) do { _Pragma("unroll") for (int m = 0; m < 4; ++m) _Pragma("unroll") for (int k = 0; k < 2; ++k) dst[m][k] = *(const PG8_LAS bf16x8*)(lds + PG8_SA(b, h) + aoff + m * 2048 + k * 1024); } while (0)
; #define PG8_MMA(ai, bj, At, Bt) do { __builtin_amdgcn_s_setprio(1); _Pragma("unroll") for (int m = 0; m < 4; ++m) _Pragma("unroll") for (int n = 0; n < 2; ++n) _Pragma("unroll") for (int k = 0; k < 2; ++k) \
;         acc[ai][bj][m][n] = __builtin_amdgcn_mfma_f32_16x16x32_bf16(Bt[n][k], At[m][k], acc[ai][bj][m][n], 0, 0, 0); __builtin_amdgcn_s_setprio(0); } while (0)
; #define PG8_WAIT_V(n) asm volatile("s_waitcnt vmcnt(" #n ")" ::: "memory")
; #define PG8_WAIT_L(n) asm volatile("s_waitcnt lgkmcnt(" #n ")" ::: "memory")
; #define PG8_BAR __builtin_amdgcn_s_barrier()
; #define PG8_SCHED __builtin_amdgcn_sched_barrier(0)
; template <class Epi, class Sched, bool ALIGN_EPI = false, bool SP2 = false>
; __device__ __forceinline__ void gemm_phase(PG8_LAS unsigned char* lds, const Gemm g, const Sched& S, const Epi& E) {
;     ...
;             PG8_LDA(At, 1, 1); PG8_STAGE(PG8_SB(1, 0), b3, voffB); PG8_STAGE(PG8_SB(1, 1), b3 + hstep, voffB); PG8_STAGE(PG8_SA(1, 0), a3, voffA);
;             PG8_WAIT_V(8); PG8_WAIT_L(0); PG8_BAR; PG8_MMA(1, 0, At, B0); PG8_MMA(1, 1, At, B1); PG8_BAR; PG8_SCHED;
	s_add_i32 s4, s91, s44
	v_lshl_add_u64 v[162:163], v[162:163], 0, s[24:25]
	s_mov_b32 m0, s4
	ds_read_b128 v[192:195], v170 offset:49152
	ds_read_b128 v[196:199], v170 offset:50176
	ds_read_b128 v[200:203], v170 offset:51200
	ds_read_b128 v[204:207], v170 offset:52224
	ds_read_b128 v[230:233], v170 offset:53248
	ds_read_b128 v[234:237], v170 offset:54272
	ds_read_b128 v[238:241], v170 offset:55296
	ds_read_b128 v[242:245], v170 offset:56320
	global_load_lds_dwordx4 v[162:163], off
	v_lshl_add_u64 v[162:163], v[208:209], 0, s[24:25]
	s_add_i32 m0, s4, 0x2000
	s_add_i32 s4, s81, s44
	global_load_lds_dwordx4 v[162:163], off
	v_lshl_add_u64 v[162:163], v[246:247], 0, s[24:25]
	s_mov_b32 m0, s4
	s_nop 0
	global_load_lds_dwordx4 v[162:163], off
	v_lshl_add_u64 v[162:163], v[248:249], 0, s[24:25]
	s_add_i32 m0, s4, 0x2000
	s_nop 0
	global_load_lds_dwordx4 v[162:163], off
	v_lshl_add_u64 v[162:163], v[216:217], 0, s[24:25]
	s_mov_b32 m0, s53
	s_nop 0
	global_load_lds_dwordx4 v[162:163], off
	v_lshl_add_u64 v[162:163], v[224:225], 0, s[24:25]
	s_mov_b32 m0, s72
	s_nop 0
	global_load_lds_dwordx4 v[162:163], off
	s_waitcnt vmcnt(8)
	s_waitcnt lgkmcnt(0)
	s_barrier
	s_setprio 1
	s_waitcnt lgkmcnt(0)
	v_mfma_f32_16x16x32_bf16 v[68:71], v[136:139], v[192:195], v[68:71]
	v_mfma_f32_16x16x32_bf16 v[68:71], v[140:143], v[196:199], v[68:71]
	v_mfma_f32_16x16x32_bf16 v[52:55], v[140:143], v[204:207], v[52:55]
	v_mfma_f32_16x16x32_bf16 v[52:55], v[136:139], v[200:203], v[52:55]
	v_mfma_f32_16x16x32_bf16 v[36:39], v[136:139], v[230:233], v[36:39]
	v_mfma_f32_16x16x32_bf16 v[36:39], v[140:143], v[234:237], v[36:39]
	v_mfma_f32_16x16x32_bf16 v[20:23], v[140:143], v[242:245], v[20:23]
	v_mfma_f32_16x16x32_bf16 v[20:23], v[136:139], v[238:241], v[20:23]
	v_mfma_f32_16x16x32_bf16 v[16:19], v[144:147], v[238:241], v[16:19]
	v_mfma_f32_16x16x32_bf16 v[16:19], v[148:151], v[242:245], v[16:19]
	v_mfma_f32_16x16x32_bf16 v[32:35], v[148:151], v[234:237], v[32:35]
	v_mfma_f32_16x16x32_bf16 v[32:35], v[144:147], v[230:233], v[32:35]
	v_mfma_f32_16x16x32_bf16 v[48:51], v[144:147], v[200:203], v[48:51]
	v_mfma_f32_16x16x32_bf16 v[48:51], v[148:151], v[204:207], v[48:51]
	v_mfma_f32_16x16x32_bf16 v[64:67], v[148:151], v[196:199], v[64:67]
	v_mfma_f32_16x16x32_bf16 v[64:67], v[144:147], v[192:195], v[64:67]
	s_setprio 0
	s_setprio 1
	v_mfma_f32_16x16x32_bf16 v[60:63], v[174:177], v[192:195], v[60:63]
	v_mfma_f32_16x16x32_bf16 v[60:63], v[178:181], v[196:199], v[60:63]
	v_mfma_f32_16x16x32_bf16 v[44:47], v[178:181], v[204:207], v[44:47]
	v_mfma_f32_16x16x32_bf16 v[44:47], v[174:177], v[200:203], v[44:47]
	v_mfma_f32_16x16x32_bf16 v[28:31], v[174:177], v[230:233], v[28:31]
	v_mfma_f32_16x16x32_bf16 v[28:31], v[178:181], v[234:237], v[28:31]
	v_mfma_f32_16x16x32_bf16 v[12:15], v[178:181], v[242:245], v[12:15]
	v_mfma_f32_16x16x32_bf16 v[12:15], v[174:177], v[238:241], v[12:15]
	v_mfma_f32_16x16x32_bf16 v[8:11], v[184:187], v[238:241], v[8:11]
	v_mfma_f32_16x16x32_bf16 v[8:11], v[188:191], v[242:245], v[8:11]
	v_mfma_f32_16x16x32_bf16 v[24:27], v[188:191], v[234:237], v[24:27]
	v_mfma_f32_16x16x32_bf16 v[24:27], v[184:187], v[230:233], v[24:27]
	v_mfma_f32_16x16x32_bf16 v[40:43], v[184:187], v[200:203], v[40:43]
	v_mfma_f32_16x16x32_bf16 v[40:43], v[188:191], v[204:207], v[40:43]
	v_mfma_f32_16x16x32_bf16 v[56:59], v[188:191], v[196:199], v[56:59]
	v_mfma_f32_16x16x32_bf16 v[56:59], v[184:187], v[192:195], v[56:59]
	s_setprio 0
	s_barrier
	s_add_u32 s0, s0, 0x100
	s_addc_u32 s1, s1, 0
	s_add_u32 s42, s42, 0x100
	s_addc_u32 s43, s43, 0
	s_cmp_ge_u32 s80, s9
	s_mov_b32 s4, s80
	s_cbranch_scc0 .LBB0_501
